# nt cache hint on the f32 residual loads and stores of the two residual-GEMM epilogues
# speedup vs baseline: 1.0201x; 1.0201x over previous
; __device__ __forceinline__ int lane_id_v() { int l; asm volatile("v_mbcnt_lo_u32_b32 %0, -1, 0\n\tv_mbcnt_hi_u32_b32 %0, -1, %0" : "=v"(l)); return l; }
;     __device__ __forceinline__ void operator()(const f32x4 (&acc)[2][2][4][2], const pg8::Unit& u, int wr, int wc, int fr_, int fq_) const {
;         const int lane_ = pg8::lane_id_v(); const int fr = lane_ & 15, fq = lane_ >> 4;
;         const bool hi = (fr & 8) != 0; const int r8 = fr & 7;
;         const int grow0 = rowbase + u.pm * 256 + wr * 64 + fr;
;         const int mrow0 = rowbase + u.pm * 256 + wr * 64 + r8;
;         const int b = batch_of(rowbase + u.pm * 256);
;         const int col0 = u.pn * 256 + wc * 32 + 4 * fq;
;         const int mcol = col0 + (hi ? 16 : 0);
;         const float* rp0 = (first ? (mrow0 < MP ? xp + (size_t)mrow0 * D : xs + (size_t)(mrow0 - MP) * D) : out + (size_t)mrow0 * D) + mcol;
;         f32x4 xi[RES_DEPTH][4];
; #pragma unroll
;         for (int r = 0; r < RES_DEPTH; ++r)
; #pragma unroll
;             for (int q = 0; q < 4; ++q) xi[r][q] = *(const f32x4*)(rp0 + (size_t)((r >> 2) * 128 + (r & 3) * 16 + (q & 1) * 8) * D + (q >> 1) * 128);
;         const float* gp = gate + (size_t)b * NMOD + col0;
;         f32x4 gv[2][2], mv[2][2];
; #pragma unroll
;         for (int bj = 0; bj < 2; ++bj)
; #pragma unroll
;             for (int n = 0; n < 2; ++n) { gv[bj][n] = *(const f32x4*)(gp + bj * 128 + n * 16) * coef;
;                 mv[bj][n] = gm ? *(const f32x4*)(gm + b * D + col0 + bj * 128 + n * 16) : (f32x4){0.f, 0.f, 0.f, 0.f}; }
; #pragma unroll
;         for (int r = 0; r < 8; ++r) {
;             const int ai = r >> 2, m = r & 3;
;             const int grow = grow0 + ai * 128 + m * 16;
;             const size_t mo0 = (size_t)(mrow0 + ai * 128 + m * 16) * D + mcol, mo1 = mo0 + (size_t)8 * D;
;             f32x4 xo[2][2];
; #pragma unroll
;             for (int bj = 0; bj < 2; ++bj) {
;                 const f32x4 L1 = xi[r % RES_DEPTH][bj * 2], L2 = xi[r % RES_DEPTH][bj * 2 + 1];
;                 const f32x4 T = dpp_ror8(hi ? L1 : L2);
;                 const f32x4 x0 = hi ? T : L1, x1 = hi ? L2 : T;
;                 xo[bj][0] = x0 + gv[bj][0] * acc[ai][bj][m][0]; xo[bj][1] = x1 + gv[bj][1] * acc[ai][bj][m][1];
.LBB0_153:
	s_lshl_b32 s23, s10, 8
	s_add_i32 s40, s23, s91
	s_addk_i32 s23, 0x8000
	s_lshr_b32 s23, s23, 14
	s_ashr_i32 s26, s10, 4
	s_add_i32 s23, s23, 8
	s_cmpk_lt_i32 s10, 0x80
	v_mbcnt_lo_u32_b32 v52, -1, 0
	v_mbcnt_hi_u32_b32 v52, -1, v52
	s_cselect_b32 s10, s26, s23
	s_lshl_b32 s23, s2, 8
	v_ashrrev_i32_e32 v48, 2, v52
	v_and_or_b32 v174, v52, 7, s40
	s_or_b32 s23, s23, s15
	v_and_b32_e32 v48, -4, v48
	v_and_b32_e32 v173, 8, v52
	v_add_u32_e32 v48, s23, v48
	v_ashrrev_i32_e32 v175, 31, v174
	s_mul_i32 s26, s10, 0x9000
	v_readlane_b32 s27, v254, 32
	v_lshl_add_u32 v176, v173, 1, v48
	v_lshlrev_b64 v[50:51], 12, v[174:175]
	s_mul_hi_i32 s23, s10, 0x9000
	s_add_u32 s26, s27, s26
	v_readlane_b32 s27, v254, 33
	v_ashrrev_i32_e32 v49, 31, v48
	v_lshl_add_u64 v[50:51], s[82:83], 0, v[50:51]
	v_ashrrev_i32_e32 v177, 31, v176
	s_addc_u32 s27, s27, s23
	v_lshlrev_b64 v[48:49], 2, v[48:49]
	v_lshl_add_u64 v[210:211], v[176:177], 2, v[50:51]
	v_lshl_add_u64 v[50:51], s[26:27], 0, v[48:49]
	s_mov_b32 s23, 0x8000
	global_load_dwordx4 v[180:183], v[50:51], off nt
	global_load_dwordx4 v[184:187], v[50:51], off offset:64 nt
	global_load_dwordx4 v[188:191], v[50:51], off offset:512 nt
	global_load_dwordx4 v[218:221], v[50:51], off offset:576 nt
	v_add_co_u32_e32 v214, vcc, s23, v210
	v_lshlrev_b64 v[50:51], 10, v[174:175]
	s_nop 0
	v_addc_co_u32_e32 v215, vcc, 0, v211, vcc
	global_load_dwordx4 v[222:225], v[214:215], off nt
	global_load_dwordx4 v[226:229], v[210:211], off nt
	global_load_dwordx4 v[230:233], v[210:211], off offset:512 nt
	global_load_dwordx4 v[242:245], v[214:215], off offset:512 nt
	s_lshl_b32 s74, s2, 2
	s_mov_b32 s2, 0x10000
	v_and_or_b32 v172, v52, 15, s40
	v_readlane_b32 s40, v254, 34
	v_lshl_add_u64 v[198:199], v[50:51], 0, v[176:177]
	v_add_co_u32_e32 v50, vcc, s2, v210
	s_lshl_b32 s26, s10, 10
	v_readlane_b32 s41, v254, 35
	v_addc_co_u32_e32 v51, vcc, 0, v211, vcc
	s_mov_b32 s2, 0x18000
	v_cmp_gt_u32_e64 s[38:39], 16, v52
	s_ashr_i32 s27, s26, 31
	v_lshl_add_u64 v[48:49], s[40:41], 0, v[48:49]
	v_add_co_u32_e32 v52, vcc, s2, v210
	v_lshl_add_u64 v[48:49], s[26:27], 2, v[48:49]
	s_nop 0
	v_addc_co_u32_e32 v53, vcc, 0, v211, vcc
	global_load_dwordx4 v[156:159], v[50:51], off nt
	global_load_dwordx4 v[148:151], v[50:51], off offset:512 nt
	global_load_dwordx4 v[152:155], v[52:53], off nt
	global_load_dwordx4 v[144:147], v[52:53], off offset:512 nt
	global_load_dwordx4 v[60:63], v[48:49], off nt
	global_load_dwordx4 v[56:59], v[48:49], off offset:64 nt
	s_nop 0
	global_load_dwordx4 v[52:55], v[48:49], off offset:512 nt
	s_nop 0
	global_load_dwordx4 v[48:51], v[48:49], off offset:576 nt
	v_mov_b32_e32 v197, v196
	v_cmp_eq_u32_e64 s[40:41], 0, v173
	v_mov_b32_e32 v241, v193
	v_mov_b32_e32 v246, v193
	v_mov_b32_e32 v247, v193
	v_mov_b32_e32 v248, v193
	s_mov_b32 s2, 0x20000
	v_lshl_add_u64 v[198:199], v[198:199], 1, s[8:9]
	v_lshl_add_u64 v[212:213], v[210:211], 0, s[60:61]
	s_ashr_i32 s75, s74, 31
	s_mov_b64 s[26:27], 0x4000
	s_waitcnt vmcnt(0)
	v_pk_mul_f32 v[178:179], v[196:197], v[182:183]
	v_pk_mul_f32 v[182:183], v[196:197], v[186:187]
	v_pk_mul_f32 v[208:209], v[196:197], v[190:191]
	v_pk_mul_f32 v[190:191], v[166:167], v[188:189]
	v_pk_mul_f32 v[188:189], v[196:197], v[220:221]
	v_pk_mul_f32 v[180:181], v[166:167], v[180:181]
	v_pk_mul_f32 v[184:185], v[166:167], v[184:185]
	v_cndmask_b32_e64 v173, v229, v225, s[40:41]
	v_cndmask_b32_e64 v175, v228, v224, s[40:41]
	v_cndmask_b32_e64 v197, v227, v223, s[40:41]
	v_cndmask_b32_e64 v200, v226, v222, s[40:41]
	v_mov_b32_dpp v247, v175 row_ror:8 row_mask:0xf bank_mask:0xf
	v_mov_b32_dpp v246, v197 row_ror:8 row_mask:0xf bank_mask:0xf
	v_mov_b32_dpp v241, v200 row_ror:8 row_mask:0xf bank_mask:0xf
	v_mov_b32_dpp v248, v173 row_ror:8 row_mask:0xf bank_mask:0xf
	v_cndmask_b32_e64 v201, v246, v227, s[40:41]
	v_cndmask_b32_e64 v200, v241, v226, s[40:41]
	v_cndmask_b32_e64 v221, v223, v246, s[40:41]
	v_cndmask_b32_e64 v220, v222, v241, s[40:41]
	v_cndmask_b32_e64 v223, v225, v248, s[40:41]
	v_cndmask_b32_e64 v222, v224, v247, s[40:41]
	v_pk_mul_f32 v[186:187], v[166:167], v[218:219]
	v_cndmask_b32_e64 v219, v248, v229, s[40:41]
	v_cndmask_b32_e64 v218, v247, v228, s[40:41]
	v_pk_fma_f32 v[200:201], v[140:141], v[180:181], v[200:201]
	v_pk_fma_f32 v[228:229], v[138:139], v[182:183], v[222:223]
	v_cndmask_b32_e64 v138, v231, v243, s[40:41]
	v_cndmask_b32_e64 v139, v230, v242, s[40:41]
	v_mov_b32_e32 v140, v193
	v_mov_b32_e32 v141, v193
	v_pk_fma_f32 v[226:227], v[142:143], v[178:179], v[218:219]
	v_pk_fma_f32 v[246:247], v[136:137], v[184:185], v[220:221]
	v_cndmask_b32_e64 v136, v233, v245, s[40:41]
	v_cndmask_b32_e64 v137, v232, v244, s[40:41]
	v_mov_b32_dpp v140, v139 row_ror:8 row_mask:0xf bank_mask:0xf
	v_mov_b32_dpp v141, v138 row_ror:8 row_mask:0xf bank_mask:0xf
	v_mov_b32_e32 v142, v193
	v_mov_b32_e32 v143, v193
	v_mul_f32_e32 v173, v201, v201
	v_mov_b32_dpp v142, v137 row_ror:8 row_mask:0xf bank_mask:0xf
	v_mov_b32_dpp v143, v136 row_ror:8 row_mask:0xf bank_mask:0xf
	v_cndmask_b32_e64 v137, v141, v231, s[40:41]
	v_cndmask_b32_e64 v136, v140, v230, s[40:41]
	v_cndmask_b32_e64 v141, v243, v141, s[40:41]
	v_cndmask_b32_e64 v140, v242, v140, s[40:41]
	v_cndmask_b32_e64 v139, v143, v233, s[40:41]
	v_cndmask_b32_e64 v138, v142, v232, s[40:41]
	v_cndmask_b32_e64 v143, v245, v143, s[40:41]
	v_cndmask_b32_e64 v142, v244, v142, s[40:41]
	v_pk_fma_f32 v[244:245], v[128:129], v[186:187], v[140:141]
	v_add_co_u32_e32 v128, vcc, s2, v210
	s_mov_b32 s2, 0x28000
	s_nop 0
	v_addc_co_u32_e32 v129, vcc, 0, v211, vcc
	v_pk_fma_f32 v[242:243], v[130:131], v[188:189], v[142:143]
;     __device__ __forceinline__ void operator()(const f32x4 (&acc)[2][2][4][2], const pg8::Unit& u, int wr, int wc, int fr_, int fq_) const {
;     ...
;         for (int r = 0; r < 8; ++r) {
;             const int ai = r >> 2, m = r & 3;
;             const int grow = grow0 + ai * 128 + m * 16;
;             const size_t mo0 = (size_t)(mrow0 + ai * 128 + m * 16) * D + mcol, mo1 = mo0 + (size_t)8 * D;
;             f32x4 xo[2][2];
; #pragma unroll
;             for (int bj = 0; bj < 2; ++bj) {
;                 const f32x4 L1 = xi[r % RES_DEPTH][bj * 2], L2 = xi[r % RES_DEPTH][bj * 2 + 1];
;                 const f32x4 T = dpp_ror8(hi ? L1 : L2);
;                 const f32x4 x0 = hi ? T : L1, x1 = hi ? L2 : T;
;                 xo[bj][0] = x0 + gv[bj][0] * acc[ai][bj][m][0]; xo[bj][1] = x1 + gv[bj][1] * acc[ai][bj][m][1];
;             }
;             if (r + RES_DEPTH < 8) {
;                 const int r2 = r + RES_DEPTH;
; #pragma unroll
;                 for (int q = 0; q < 4; ++q) xi[r % RES_DEPTH][q] = *(const f32x4*)(rp0 + (size_t)((r2 >> 2) * 128 + (r2 & 3) * 16 + (q & 1) * 8) * D + (q >> 1) * 128);
;             }
;             float ss = 0.f;
; #pragma unroll
;             for (int bj = 0; bj < 2; ++bj) {
;                 const f32x4 a0 = xo[bj][0], a1 = xo[bj][1];
;                 ss += ((a0[0] * a0[0] + a0[1] * a0[1]) + (a0[2] * a0[2] + a0[3] * a0[3])) + ((a1[0] * a1[0] + a1[1] * a1[1]) + (a1[2] * a1[2] + a1[3] * a1[3]));
;                 const f32x4 T2 = dpp_ror8(hi ? a0 : a1);
;                 const f32x4 d1 = hi ? T2 : a0, d2 = hi ? a1 : T2;
;                 *(f32x4*)(out + mo0 + bj * 128) = d1; *(f32x4*)(out + mo1 + bj * 128) = d2;
;                 if (gm) { const f32x4 o0 = a0 * mv[bj][0], o1 = a1 * mv[bj][1];
;                     u32x2 w0, w1; w0.x = cvt_pk_bf16(o0[0], o0[1]); w0.y = cvt_pk_bf16(o0[2], o0[3]); w1.x = cvt_pk_bf16(o1[0], o1[1]); w1.y = cvt_pk_bf16(o1[2], o1[3]);
;                     const u32x2 T3 = dpp_ror8(hi ? w0 : w1);
;                     const u32x2 e1 = hi ? T3 : w0, e2 = hi ? w1 : T3;
;                     *(u32x2*)(xg + mo0 + bj * 128) = e1; *(u32x2*)(xg + mo1 + bj * 128) = e2; }
;             }
;             ss += __shfl_xor(ss, 16); ss += __shfl_xor(ss, 32);
;             if (fq == 0) rss[(size_t)grow * 16 + u.pn * 4 + wc] = ss;
	v_add_co_u32_e32 v130, vcc, s2, v210
	v_pk_fma_f32 v[230:231], v[134:135], v[208:209], v[138:139]
	s_nop 0
	v_addc_co_u32_e32 v131, vcc, 0, v211, vcc
	v_pk_fma_f32 v[232:233], v[132:133], v[190:191], v[136:137]
	global_load_dwordx4 v[136:139], v[128:129], off nt
	global_load_dwordx4 v[132:135], v[128:129], off offset:512 nt
	global_load_dwordx4 v[140:143], v[130:131], off nt
	s_nop 0
	global_load_dwordx4 v[128:131], v[130:131], off offset:512 nt
	v_mul_f32_e32 v175, v227, v227
	v_fmac_f32_e32 v173, v200, v200
	v_fmac_f32_e32 v175, v226, v226
	v_add_f32_e32 v173, v173, v175
	v_mul_f32_e32 v175, v247, v247
	v_mul_f32_e32 v197, v229, v229
	v_fmac_f32_e32 v175, v246, v246
	v_fmac_f32_e32 v197, v228, v228
	v_add_f32_e32 v175, v175, v197
	v_cndmask_b32_e64 v197, v226, v228, s[40:41]
	v_mov_b32_e32 v224, v193
	v_add_f32_e32 v173, v173, v175
	v_cndmask_b32_e64 v175, v227, v229, s[40:41]
	v_cndmask_b32_e64 v218, v201, v247, s[40:41]
	v_cndmask_b32_e64 v219, v200, v246, s[40:41]
	v_mov_b32_e32 v222, v193
	v_mov_b32_e32 v223, v193
	v_mov_b32_dpp v224, v197 row_ror:8 row_mask:0xf bank_mask:0xf
	v_mov_b32_e32 v197, v193
	v_mov_b32_dpp v222, v219 row_ror:8 row_mask:0xf bank_mask:0xf
	v_mov_b32_dpp v223, v218 row_ror:8 row_mask:0xf bank_mask:0xf
	v_mov_b32_dpp v197, v175 row_ror:8 row_mask:0xf bank_mask:0xf
	v_cndmask_b32_e64 v221, v197, v227, s[40:41]
	v_cndmask_b32_e64 v220, v224, v226, s[40:41]
	v_cndmask_b32_e64 v219, v223, v201, s[40:41]
	v_cndmask_b32_e64 v218, v222, v200, s[40:41]
	v_cndmask_b32_e64 v225, v229, v197, s[40:41]
	v_cndmask_b32_e64 v224, v228, v224, s[40:41]
	v_cndmask_b32_e64 v223, v247, v223, s[40:41]
	v_cndmask_b32_e64 v222, v246, v222, s[40:41]
	global_store_dwordx4 v[210:211], v[218:221], off nt
	global_store_dwordx4 v[214:215], v[222:225], off nt
	v_pk_mul_f32 v[214:215], v[62:63], v[226:227]
	v_pk_mul_f32 v[200:201], v[60:61], v[200:201]
	v_pk_mul_f32 v[218:219], v[58:59], v[228:229]
	v_pk_mul_f32 v[220:221], v[56:57], v[246:247]
	v_cvt_pk_bf16_f32 v175, v200, v201
	v_cvt_pk_bf16_f32 v197, v214, v215
	s_movk_i32 s2, 0x4000
	v_cvt_pk_bf16_f32 v214, v220, v221
	v_cvt_pk_bf16_f32 v215, v218, v219
	v_mov_b32_e32 v218, v193
	v_cndmask_b32_e64 v200, v197, v215, s[40:41]
	v_cndmask_b32_e64 v201, v175, v214, s[40:41]
	v_mov_b32_e32 v219, v193
	v_mov_b32_e32 v222, v193
	v_mov_b32_dpp v218, v201 row_ror:8 row_mask:0xf bank_mask:0xf
	v_mov_b32_dpp v219, v200 row_ror:8 row_mask:0xf bank_mask:0xf
	v_cndmask_b32_e64 v201, v219, v197, s[40:41]
	v_cndmask_b32_e64 v200, v218, v175, s[40:41]
	v_cndmask_b32_e64 v214, v214, v218, s[40:41]
	v_add_co_u32_e32 v218, vcc, s2, v198
	v_mul_f32_e32 v175, v233, v233
	v_mul_f32_e32 v197, v231, v231
	v_cndmask_b32_e64 v215, v215, v219, s[40:41]
	v_addc_co_u32_e32 v219, vcc, 0, v199, vcc
	v_fmac_f32_e32 v175, v232, v232
	v_fmac_f32_e32 v197, v230, v230
	global_store_dwordx2 v[218:219], v[214:215], off
	v_add_f32_e32 v175, v175, v197
	v_mul_f32_e32 v197, v245, v245
	v_mul_f32_e32 v214, v243, v243
	v_fmac_f32_e32 v197, v244, v244
	v_fmac_f32_e32 v214, v242, v242
	v_cndmask_b32_e64 v215, v232, v244, s[40:41]
	v_add_f32_e32 v197, v197, v214
	v_cndmask_b32_e64 v214, v233, v245, s[40:41]
	v_mov_b32_dpp v222, v215 row_ror:8 row_mask:0xf bank_mask:0xf
	v_mov_b32_e32 v215, v193
	v_add_f32_e32 v175, v175, v197
	v_cndmask_b32_e64 v197, v230, v242, s[40:41]
	v_mov_b32_dpp v215, v214 row_ror:8 row_mask:0xf bank_mask:0xf
	v_mov_b32_e32 v214, v193
	v_add_f32_e32 v173, v173, v175
	v_cndmask_b32_e64 v175, v231, v243, s[40:41]
	v_mov_b32_dpp v214, v197 row_ror:8 row_mask:0xf bank_mask:0xf
	v_mov_b32_e32 v197, v193
	v_cndmask_b32_e64 v220, v214, v230, s[40:41]
	v_cndmask_b32_e64 v219, v215, v233, s[40:41]
	v_mov_b32_dpp v197, v175 row_ror:8 row_mask:0xf bank_mask:0xf
	v_cndmask_b32_e64 v221, v197, v231, s[40:41]
	v_cndmask_b32_e64 v218, v222, v232, s[40:41]
	global_store_dwordx2 v[198:199], v[200:201], off
	v_cndmask_b32_e64 v225, v243, v197, s[40:41]
	v_cndmask_b32_e64 v224, v242, v214, s[40:41]
	v_cndmask_b32_e64 v223, v245, v215, s[40:41]
	v_cndmask_b32_e64 v222, v244, v222, s[40:41]
	global_store_dwordx4 v[210:211], v[218:221], off offset:512 nt
	global_store_dwordx4 v[212:213], v[222:225], off offset:512 nt
	v_pk_mul_f32 v[212:213], v[54:55], v[230:231]
	v_pk_mul_f32 v[218:219], v[50:51], v[242:243]
	v_pk_mul_f32 v[214:215], v[52:53], v[232:233]
	v_pk_mul_f32 v[220:221], v[48:49], v[244:245]
	v_cvt_pk_bf16_f32 v197, v214, v215
	v_cvt_pk_bf16_f32 v212, v212, v213
	v_lshl_add_u64 v[200:201], v[198:199], 0, s[26:27]
	v_cvt_pk_bf16_f32 v213, v220, v221
	v_cvt_pk_bf16_f32 v219, v218, v219
	v_mov_b32_e32 v218, v193
	v_cndmask_b32_e64 v175, v197, v213, s[40:41]
	v_cndmask_b32_e64 v214, v212, v219, s[40:41]
	v_mov_b32_e32 v220, v193
	v_mov_b32_dpp v218, v175 row_ror:8 row_mask:0xf bank_mask:0xf
	v_xor_b32_e32 v175, 16, v234
	v_cmp_lt_i32_e32 vcc, v175, v236
	v_mov_b32_dpp v220, v214 row_ror:8 row_mask:0xf bank_mask:0xf
	v_cndmask_b32_e64 v215, v220, v212, s[40:41]
	v_cndmask_b32_e32 v175, v234, v175, vcc
	v_lshlrev_b32_e32 v175, 2, v175
	ds_bpermute_b32 v221, v175, v173
	v_cndmask_b32_e64 v214, v218, v197, s[40:41]
	v_cndmask_b32_e64 v218, v213, v218, s[40:41]
	v_cndmask_b32_e64 v219, v219, v220, s[40:41]
	global_store_dwordx2 v[198:199], v[214:215], off offset:256
	global_store_dwordx2 v[200:201], v[218:219], off offset:256
	s_waitcnt lgkmcnt(0)
	v_add_f32_e32 v212, v173, v221
	v_xor_b32_e32 v173, 32, v234
	v_cmp_lt_i32_e32 vcc, v173, v236
	s_nop 1
	v_cndmask_b32_e32 v173, v234, v173, vcc
	v_lshlrev_b32_e32 v197, 2, v173
	ds_bpermute_b32 v213, v197, v212
	v_ashrrev_i32_e32 v173, 31, v172
	s_and_saveexec_b64 s[26:27], s[38:39]
	s_cbranch_execz .LBB0_155
	v_lshlrev_b64 v[198:199], 6, v[172:173]
	v_lshl_add_u64 v[198:199], s[96:97], 0, v[198:199]
	v_lshl_add_u64 v[198:199], s[74:75], 2, v[198:199]
	s_lshl_b32 s10, s17, 2
	v_lshl_add_u64 v[198:199], v[198:199], 0, s[10:11]
	s_waitcnt lgkmcnt(0)
	v_add_f32_e32 v200, v212, v213
	global_store_dword v[198:199], v200, off
; __device__ __forceinline__ unsigned cvt_pk_bf16(float lo, float hi) { unsigned r; asm volatile("v_cvt_pk_bf16_f32 %0, %1, %2" : "=v"(r) : "v"(lo), "v"(hi)); return r; }
;     __device__ __forceinline__ void operator()(const f32x4 (&acc)[2][2][4][2], const pg8::Unit& u, int wr, int wc, int fr_, int fq_) const {
;     ...
;         for (int r = 0; r < 8; ++r) {
;             const int ai = r >> 2, m = r & 3;
;             const int grow = grow0 + ai * 128 + m * 16;
;             const size_t mo0 = (size_t)(mrow0 + ai * 128 + m * 16) * D + mcol, mo1 = mo0 + (size_t)8 * D;
;             f32x4 xo[2][2];
; #pragma unroll
;             for (int bj = 0; bj < 2; ++bj) {
;                 const f32x4 L1 = xi[r % RES_DEPTH][bj * 2], L2 = xi[r % RES_DEPTH][bj * 2 + 1];
;                 const f32x4 T = dpp_ror8(hi ? L1 : L2);
;                 const f32x4 x0 = hi ? T : L1, x1 = hi ? L2 : T;
;                 xo[bj][0] = x0 + gv[bj][0] * acc[ai][bj][m][0]; xo[bj][1] = x1 + gv[bj][1] * acc[ai][bj][m][1];
;             }
;             if (r + RES_DEPTH < 8) {
;                 const int r2 = r + RES_DEPTH;
; #pragma unroll
;                 for (int q = 0; q < 4; ++q) xi[r % RES_DEPTH][q] = *(const f32x4*)(rp0 + (size_t)((r2 >> 2) * 128 + (r2 & 3) * 16 + (q & 1) * 8) * D + (q >> 1) * 128);
;             }
;             float ss = 0.f;
; #pragma unroll
;             for (int bj = 0; bj < 2; ++bj) {
;                 const f32x4 a0 = xo[bj][0], a1 = xo[bj][1];
;                 ss += ((a0[0] * a0[0] + a0[1] * a0[1]) + (a0[2] * a0[2] + a0[3] * a0[3])) + ((a1[0] * a1[0] + a1[1] * a1[1]) + (a1[2] * a1[2] + a1[3] * a1[3]));
;                 const f32x4 T2 = dpp_ror8(hi ? a0 : a1);
;                 const f32x4 d1 = hi ? T2 : a0, d2 = hi ? a1 : T2;
;                 *(f32x4*)(out + mo0 + bj * 128) = d1; *(f32x4*)(out + mo1 + bj * 128) = d2;
;                 if (gm) { const f32x4 o0 = a0 * mv[bj][0], o1 = a1 * mv[bj][1];
;                     u32x2 w0, w1; w0.x = cvt_pk_bf16(o0[0], o0[1]); w0.y = cvt_pk_bf16(o0[2], o0[3]); w1.x = cvt_pk_bf16(o1[0], o1[1]); w1.y = cvt_pk_bf16(o1[2], o1[3]);
;                     const u32x2 T3 = dpp_ror8(hi ? w0 : w1);
;                     const u32x2 e1 = hi ? T3 : w0, e2 = hi ? w1 : T3;
;                     *(u32x2*)(xg + mo0 + bj * 128) = e1; *(u32x2*)(xg + mo1 + bj * 128) = e2; }
;             }
.LBB0_155:
	s_or_b64 exec, exec, s[26:27]
	s_waitcnt lgkmcnt(0)
	v_cndmask_b32_e64 v213, v156, v152, s[40:41]
	v_mov_b32_e32 v214, v193
	v_cndmask_b32_e64 v212, v157, v153, s[40:41]
	v_cndmask_b32_e64 v201, v158, v154, s[40:41]
	v_mov_b32_dpp v214, v213 row_ror:8 row_mask:0xf bank_mask:0xf
	v_mov_b32_e32 v213, v193
	v_cndmask_b32_e64 v200, v159, v155, s[40:41]
	v_cndmask_b32_e64 v156, v214, v156, s[40:41]
	v_mov_b32_dpp v213, v212 row_ror:8 row_mask:0xf bank_mask:0xf
	v_mov_b32_e32 v212, v193
	v_cndmask_b32_e64 v157, v213, v157, s[40:41]
	v_cndmask_b32_e64 v153, v153, v213, s[40:41]
	v_mov_b32_dpp v212, v201 row_ror:8 row_mask:0xf bank_mask:0xf
	v_mov_b32_e32 v201, v193
	v_cndmask_b32_e64 v154, v154, v212, s[40:41]
	v_cndmask_b32_e64 v158, v212, v158, s[40:41]
	v_mov_b32_dpp v201, v200 row_ror:8 row_mask:0xf bank_mask:0xf
	v_cndmask_b32_e64 v155, v155, v201, s[40:41]
	v_cndmask_b32_e64 v159, v201, v159, s[40:41]
	v_cndmask_b32_e64 v152, v152, v214, s[40:41]
	v_pk_fma_f32 v[156:157], v[124:125], v[180:181], v[156:157]
	v_pk_fma_f32 v[154:155], v[122:123], v[182:183], v[154:155]
	v_cndmask_b32_e64 v122, v149, v145, s[40:41]
	v_cndmask_b32_e64 v123, v148, v144, s[40:41]
	v_mov_b32_e32 v124, v193
	v_mov_b32_e32 v125, v193
	v_pk_fma_f32 v[158:159], v[126:127], v[178:179], v[158:159]
	v_pk_fma_f32 v[152:153], v[120:121], v[184:185], v[152:153]
	v_cndmask_b32_e64 v120, v151, v147, s[40:41]
	v_cndmask_b32_e64 v121, v150, v146, s[40:41]
	v_mov_b32_dpp v124, v123 row_ror:8 row_mask:0xf bank_mask:0xf
	v_mov_b32_dpp v125, v122 row_ror:8 row_mask:0xf bank_mask:0xf
	v_mov_b32_e32 v126, v193
	v_mov_b32_e32 v127, v193
	s_mov_b32 s10, 0x30000
	v_mov_b32_dpp v126, v121 row_ror:8 row_mask:0xf bank_mask:0xf
	v_mov_b32_dpp v127, v120 row_ror:8 row_mask:0xf bank_mask:0xf
	v_cndmask_b32_e64 v121, v125, v149, s[40:41]
	v_cndmask_b32_e64 v120, v124, v148, s[40:41]
	v_cndmask_b32_e64 v125, v145, v125, s[40:41]
	v_cndmask_b32_e64 v124, v144, v124, s[40:41]
	v_pk_fma_f32 v[218:219], v[112:113], v[186:187], v[124:125]
	v_add_co_u32_e32 v112, vcc, s10, v210
	v_cndmask_b32_e64 v123, v127, v151, s[40:41]
	v_cndmask_b32_e64 v122, v126, v150, s[40:41]
	v_cndmask_b32_e64 v127, v147, v127, s[40:41]
	v_cndmask_b32_e64 v126, v146, v126, s[40:41]
	v_addc_co_u32_e32 v113, vcc, 0, v211, vcc
	s_mov_b32 s10, 0x38000
	v_pk_fma_f32 v[214:215], v[114:115], v[188:189], v[126:127]
	v_add_co_u32_e32 v114, vcc, s10, v210
	v_pk_fma_f32 v[200:201], v[118:119], v[208:209], v[122:123]
	s_nop 0
	v_addc_co_u32_e32 v115, vcc, 0, v211, vcc
	v_pk_fma_f32 v[212:213], v[116:117], v[190:191], v[120:121]
	global_load_dwordx4 v[120:123], v[112:113], off nt
	global_load_dwordx4 v[116:119], v[112:113], off offset:512 nt
	global_load_dwordx4 v[124:127], v[114:115], off nt
	s_nop 0
	global_load_dwordx4 v[112:115], v[114:115], off offset:512 nt
	v_mul_f32_e32 v144, v157, v157
	v_mul_f32_e32 v145, v159, v159
	v_fmac_f32_e32 v144, v156, v156
	v_fmac_f32_e32 v145, v158, v158
	v_add_f32_e32 v144, v144, v145
	v_mul_f32_e32 v145, v153, v153
	v_mul_f32_e32 v146, v155, v155
	v_or_b32_e32 v198, 16, v174
	v_fmac_f32_e32 v145, v152, v152
	v_fmac_f32_e32 v146, v154, v154
	v_ashrrev_i32_e32 v199, 31, v198
	v_add_f32_e32 v145, v145, v146
	v_lshlrev_b64 v[198:199], 10, v[198:199]
	v_add_f32_e32 v224, v144, v145
	v_cndmask_b32_e64 v144, v159, v155, s[40:41]
	v_cndmask_b32_e64 v145, v158, v154, s[40:41]
	v_cndmask_b32_e64 v146, v157, v153, s[40:41]
	v_cndmask_b32_e64 v147, v156, v152, s[40:41]
	v_mov_b32_e32 v148, v193
	v_mov_b32_e32 v149, v193
	v_mov_b32_e32 v150, v193
	v_mov_b32_e32 v151, v193
	v_lshl_add_u64 v[198:199], v[198:199], 0, v[176:177]
	v_mov_b32_dpp v148, v147 row_ror:8 row_mask:0xf bank_mask:0xf
	v_mov_b32_dpp v149, v146 row_ror:8 row_mask:0xf bank_mask:0xf
	v_mov_b32_dpp v150, v145 row_ror:8 row_mask:0xf bank_mask:0xf
	v_mov_b32_dpp v151, v144 row_ror:8 row_mask:0xf bank_mask:0xf
	v_cndmask_b32_e64 v147, v151, v159, s[40:41]
	v_cndmask_b32_e64 v146, v150, v158, s[40:41]
	v_cndmask_b32_e64 v145, v149, v157, s[40:41]
	v_cndmask_b32_e64 v144, v148, v156, s[40:41]
	v_lshl_add_u64 v[220:221], v[198:199], 2, s[82:83]
	global_store_dwordx4 v[220:221], v[144:147], off nt
	v_cndmask_b32_e64 v151, v155, v151, s[40:41]
	v_cndmask_b32_e64 v150, v154, v150, s[40:41]
	v_add_co_u32_e32 v144, vcc, s23, v220
	v_cndmask_b32_e64 v149, v153, v149, s[40:41]
	v_cndmask_b32_e64 v148, v152, v148, s[40:41]
	v_addc_co_u32_e32 v145, vcc, 0, v221, vcc
	global_store_dwordx4 v[144:145], v[148:151], off nt
	v_pk_mul_f32 v[144:145], v[62:63], v[158:159]
	v_pk_mul_f32 v[146:147], v[60:61], v[156:157]
	v_pk_mul_f32 v[148:149], v[58:59], v[154:155]
	v_pk_mul_f32 v[150:151], v[56:57], v[152:153]
	v_cvt_pk_bf16_f32 v146, v146, v147
	v_cvt_pk_bf16_f32 v145, v144, v145
	v_lshl_add_u64 v[152:153], v[198:199], 1, s[8:9]
	v_cvt_pk_bf16_f32 v147, v150, v151
	v_cvt_pk_bf16_f32 v148, v148, v149
	v_mov_b32_e32 v150, v193
	v_cndmask_b32_e64 v149, v146, v147, s[40:41]
	v_cndmask_b32_e64 v144, v145, v148, s[40:41]
	v_mov_b32_e32 v151, v193
	v_mov_b32_dpp v150, v149 row_ror:8 row_mask:0xf bank_mask:0xf
	v_mov_b32_e32 v149, v193
	v_lshl_add_u64 v[222:223], v[220:221], 0, s[60:61]
	v_mov_b32_e32 v157, v193
	v_mov_b32_dpp v149, v144 row_ror:8 row_mask:0xf bank_mask:0xf
	v_cndmask_b32_e64 v144, v150, v146, s[40:41]
	v_cndmask_b32_e64 v145, v149, v145, s[40:41]
	global_store_dwordx2 v[152:153], v[144:145], off
	v_add_co_u32_e32 v144, vcc, s2, v152
	v_cndmask_b32_e64 v146, v147, v150, s[40:41]
	v_cndmask_b32_e64 v147, v148, v149, s[40:41]
	v_addc_co_u32_e32 v145, vcc, 0, v153, vcc
	global_store_dwordx2 v[144:145], v[146:147], off
	v_mul_f32_e32 v144, v213, v213
;     __device__ __forceinline__ void operator()(const f32x4 (&acc)[2][2][4][2], const pg8::Unit& u, int wr, int wc, int fr_, int fq_) const {
;     ...
;         for (int r = 0; r < 8; ++r) {
;             const int ai = r >> 2, m = r & 3;
;             const int grow = grow0 + ai * 128 + m * 16;
;             const size_t mo0 = (size_t)(mrow0 + ai * 128 + m * 16) * D + mcol, mo1 = mo0 + (size_t)8 * D;
;             f32x4 xo[2][2];
; #pragma unroll
;             for (int bj = 0; bj < 2; ++bj) {
;                 const f32x4 L1 = xi[r % RES_DEPTH][bj * 2], L2 = xi[r % RES_DEPTH][bj * 2 + 1];
;                 const f32x4 T = dpp_ror8(hi ? L1 : L2);
;                 const f32x4 x0 = hi ? T : L1, x1 = hi ? L2 : T;
;                 xo[bj][0] = x0 + gv[bj][0] * acc[ai][bj][m][0]; xo[bj][1] = x1 + gv[bj][1] * acc[ai][bj][m][1];
;             }
;             if (r + RES_DEPTH < 8) {
;                 const int r2 = r + RES_DEPTH;
; #pragma unroll
;                 for (int q = 0; q < 4; ++q) xi[r % RES_DEPTH][q] = *(const f32x4*)(rp0 + (size_t)((r2 >> 2) * 128 + (r2 & 3) * 16 + (q & 1) * 8) * D + (q >> 1) * 128);
;             }
;             float ss = 0.f;
; #pragma unroll
;             for (int bj = 0; bj < 2; ++bj) {
;                 const f32x4 a0 = xo[bj][0], a1 = xo[bj][1];
;                 ss += ((a0[0] * a0[0] + a0[1] * a0[1]) + (a0[2] * a0[2] + a0[3] * a0[3])) + ((a1[0] * a1[0] + a1[1] * a1[1]) + (a1[2] * a1[2] + a1[3] * a1[3]));
;                 const f32x4 T2 = dpp_ror8(hi ? a0 : a1);
;                 const f32x4 d1 = hi ? T2 : a0, d2 = hi ? a1 : T2;
;                 *(f32x4*)(out + mo0 + bj * 128) = d1; *(f32x4*)(out + mo1 + bj * 128) = d2;
;                 if (gm) { const f32x4 o0 = a0 * mv[bj][0], o1 = a1 * mv[bj][1];
;                     u32x2 w0, w1; w0.x = cvt_pk_bf16(o0[0], o0[1]); w0.y = cvt_pk_bf16(o0[2], o0[3]); w1.x = cvt_pk_bf16(o1[0], o1[1]); w1.y = cvt_pk_bf16(o1[2], o1[3]);
;                     const u32x2 T3 = dpp_ror8(hi ? w0 : w1);
;                     const u32x2 e1 = hi ? T3 : w0, e2 = hi ? w1 : T3;
;                     *(u32x2*)(xg + mo0 + bj * 128) = e1; *(u32x2*)(xg + mo1 + bj * 128) = e2; }
;             }
;             ss += __shfl_xor(ss, 16); ss += __shfl_xor(ss, 32);
;             if (fq == 0) rss[(size_t)grow * 16 + u.pn * 4 + wc] = ss;
	v_mul_f32_e32 v145, v201, v201
	v_fmac_f32_e32 v144, v212, v212
	v_fmac_f32_e32 v145, v200, v200
	v_add_f32_e32 v144, v144, v145
	v_mul_f32_e32 v145, v219, v219
	v_mul_f32_e32 v146, v215, v215
	v_fmac_f32_e32 v145, v218, v218
	v_fmac_f32_e32 v146, v214, v214
	v_add_f32_e32 v145, v145, v146
	v_add_f32_e32 v144, v144, v145
	v_add_f32_e32 v156, v224, v144
	v_cndmask_b32_e64 v144, v201, v215, s[40:41]
	v_cndmask_b32_e64 v145, v200, v214, s[40:41]
	v_cndmask_b32_e64 v146, v213, v219, s[40:41]
	v_cndmask_b32_e64 v147, v212, v218, s[40:41]
	v_mov_b32_e32 v148, v193
	v_mov_b32_e32 v149, v193
	v_mov_b32_e32 v150, v193
	v_mov_b32_dpp v148, v147 row_ror:8 row_mask:0xf bank_mask:0xf
	v_mov_b32_dpp v149, v146 row_ror:8 row_mask:0xf bank_mask:0xf
	v_mov_b32_dpp v150, v145 row_ror:8 row_mask:0xf bank_mask:0xf
	v_mov_b32_dpp v151, v144 row_ror:8 row_mask:0xf bank_mask:0xf
	v_cndmask_b32_e64 v147, v151, v201, s[40:41]
	v_cndmask_b32_e64 v146, v150, v200, s[40:41]
	v_cndmask_b32_e64 v145, v149, v213, s[40:41]
	v_cndmask_b32_e64 v144, v148, v212, s[40:41]
	v_cndmask_b32_e64 v151, v215, v151, s[40:41]
	v_cndmask_b32_e64 v150, v214, v150, s[40:41]
	v_cndmask_b32_e64 v149, v219, v149, s[40:41]
	v_cndmask_b32_e64 v148, v218, v148, s[40:41]
	global_store_dwordx4 v[220:221], v[144:147], off offset:512 nt
	global_store_dwordx4 v[222:223], v[148:151], off offset:512 nt
	s_mov_b64 s[26:27], 0x4000
	v_pk_mul_f32 v[144:145], v[54:55], v[200:201]
	v_pk_mul_f32 v[146:147], v[52:53], v[212:213]
	v_pk_mul_f32 v[150:151], v[48:49], v[218:219]
	v_cvt_pk_bf16_f32 v146, v146, v147
	v_cvt_pk_bf16_f32 v144, v144, v145
	v_pk_mul_f32 v[148:149], v[50:51], v[214:215]
	v_cvt_pk_bf16_f32 v150, v150, v151
	ds_bpermute_b32 v151, v175, v156
	v_cvt_pk_bf16_f32 v149, v148, v149
	v_cndmask_b32_e64 v147, v146, v150, s[40:41]
	v_cndmask_b32_e64 v145, v144, v149, s[40:41]
	v_mov_b32_e32 v148, v193
	v_lshl_add_u64 v[154:155], v[152:153], 0, s[26:27]
	v_mov_b32_dpp v157, v145 row_ror:8 row_mask:0xf bank_mask:0xf
	v_mov_b32_dpp v148, v147 row_ror:8 row_mask:0xf bank_mask:0xf
	v_cndmask_b32_e64 v147, v157, v144, s[40:41]
	s_waitcnt lgkmcnt(0)
	v_add_f32_e32 v144, v156, v151
	ds_bpermute_b32 v145, v197, v144
	v_cndmask_b32_e64 v146, v148, v146, s[40:41]
	v_cndmask_b32_e64 v148, v150, v148, s[40:41]
	v_cndmask_b32_e64 v149, v149, v157, s[40:41]
	global_store_dwordx2 v[152:153], v[146:147], off offset:256
	global_store_dwordx2 v[154:155], v[148:149], off offset:256
	s_and_saveexec_b64 s[26:27], s[38:39]
	s_cbranch_execz .LBB0_157
	v_or_b32_e32 v146, 16, v172
	v_ashrrev_i32_e32 v147, 31, v146
	v_lshlrev_b64 v[146:147], 6, v[146:147]
	v_lshl_add_u64 v[146:147], s[96:97], 0, v[146:147]
	v_lshl_add_u64 v[146:147], s[74:75], 2, v[146:147]
	s_lshl_b32 s10, s17, 2
	v_lshl_add_u64 v[146:147], v[146:147], 0, s[10:11]
	s_waitcnt lgkmcnt(0)
	v_add_f32_e32 v144, v144, v145
	global_store_dword v[146:147], v144, off
.LBB0_157:
	s_or_b64 exec, exec, s[26:27]
	s_waitcnt vmcnt(21)
	v_cndmask_b32_e64 v149, v136, v140, s[40:41]
	v_mov_b32_e32 v150, v193
	v_cndmask_b32_e64 v148, v137, v141, s[40:41]
	v_cndmask_b32_e64 v147, v138, v142, s[40:41]
	v_mov_b32_dpp v150, v149 row_ror:8 row_mask:0xf bank_mask:0xf
	v_mov_b32_e32 v149, v193
	v_cndmask_b32_e64 v146, v139, v143, s[40:41]
	v_cndmask_b32_e64 v136, v150, v136, s[40:41]
	v_mov_b32_dpp v149, v148 row_ror:8 row_mask:0xf bank_mask:0xf
	v_mov_b32_e32 v148, v193
	v_cndmask_b32_e64 v137, v149, v137, s[40:41]
	v_cndmask_b32_e64 v141, v141, v149, s[40:41]
	v_mov_b32_dpp v148, v147 row_ror:8 row_mask:0xf bank_mask:0xf
	v_mov_b32_e32 v147, v193
	v_cndmask_b32_e64 v142, v142, v148, s[40:41]
	v_cndmask_b32_e64 v138, v148, v138, s[40:41]
	v_mov_b32_dpp v147, v146 row_ror:8 row_mask:0xf bank_mask:0xf
	v_cndmask_b32_e64 v143, v143, v147, s[40:41]
	v_cndmask_b32_e64 v139, v147, v139, s[40:41]
	v_cndmask_b32_e64 v140, v140, v150, s[40:41]
	v_pk_fma_f32 v[136:137], v[108:109], v[180:181], v[136:137]
	v_pk_fma_f32 v[142:143], v[106:107], v[182:183], v[142:143]
	s_waitcnt vmcnt(20)
	v_cndmask_b32_e64 v106, v133, v129, s[40:41]
	v_cndmask_b32_e64 v107, v132, v128, s[40:41]
	v_mov_b32_e32 v108, v193
	v_mov_b32_e32 v109, v193
	v_pk_fma_f32 v[138:139], v[110:111], v[178:179], v[138:139]
	v_pk_fma_f32 v[140:141], v[104:105], v[184:185], v[140:141]
	v_cndmask_b32_e64 v104, v135, v131, s[40:41]
	v_cndmask_b32_e64 v105, v134, v130, s[40:41]
	v_mov_b32_dpp v108, v107 row_ror:8 row_mask:0xf bank_mask:0xf
	v_mov_b32_dpp v109, v106 row_ror:8 row_mask:0xf bank_mask:0xf
	v_mov_b32_e32 v110, v193
	v_mov_b32_e32 v111, v193
	s_mov_b32 s10, 0x80000
	v_mov_b32_dpp v110, v105 row_ror:8 row_mask:0xf bank_mask:0xf
	v_mov_b32_dpp v111, v104 row_ror:8 row_mask:0xf bank_mask:0xf
	v_cndmask_b32_e64 v105, v109, v133, s[40:41]
	v_cndmask_b32_e64 v104, v108, v132, s[40:41]
	v_cndmask_b32_e64 v109, v129, v109, s[40:41]
	v_cndmask_b32_e64 v108, v128, v108, s[40:41]
	v_pk_fma_f32 v[152:153], v[96:97], v[186:187], v[108:109]
	v_add_co_u32_e32 v96, vcc, s10, v210
	v_cndmask_b32_e64 v107, v111, v135, s[40:41]
	v_cndmask_b32_e64 v106, v110, v134, s[40:41]
	v_cndmask_b32_e64 v111, v131, v111, s[40:41]
	v_cndmask_b32_e64 v110, v130, v110, s[40:41]
	v_addc_co_u32_e32 v97, vcc, 0, v211, vcc
	s_mov_b32 s10, 0x88000
	v_pk_fma_f32 v[150:151], v[98:99], v[188:189], v[110:111]
	v_add_co_u32_e32 v98, vcc, s10, v210
	v_pk_fma_f32 v[146:147], v[102:103], v[208:209], v[106:107]
	s_nop 0
	v_addc_co_u32_e32 v99, vcc, 0, v211, vcc
	v_pk_fma_f32 v[148:149], v[100:101], v[190:191], v[104:105]
	global_load_dwordx4 v[104:107], v[96:97], off nt
	global_load_dwordx4 v[100:103], v[96:97], off offset:512 nt
	global_load_dwordx4 v[108:111], v[98:99], off nt
	s_nop 0
	global_load_dwordx4 v[96:99], v[98:99], off offset:512 nt
	v_mul_f32_e32 v128, v137, v137
	v_mul_f32_e32 v129, v139, v139
	v_fmac_f32_e32 v128, v136, v136
	v_fmac_f32_e32 v129, v138, v138
	v_add_f32_e32 v128, v128, v129
	v_mul_f32_e32 v129, v141, v141
	v_mul_f32_e32 v130, v143, v143
	v_or_b32_e32 v144, 32, v174
	v_fmac_f32_e32 v129, v140, v140
	v_fmac_f32_e32 v130, v142, v142
	s_waitcnt lgkmcnt(0)
;     __device__ __forceinline__ void operator()(const f32x4 (&acc)[2][2][4][2], const pg8::Unit& u, int wr, int wc, int fr_, int fq_) const {
;     ...
;         for (int r = 0; r < 8; ++r) {
;             const int ai = r >> 2, m = r & 3;
;             const int grow = grow0 + ai * 128 + m * 16;
;             const size_t mo0 = (size_t)(mrow0 + ai * 128 + m * 16) * D + mcol, mo1 = mo0 + (size_t)8 * D;
;             f32x4 xo[2][2];
; #pragma unroll
;             for (int bj = 0; bj < 2; ++bj) {
;                 const f32x4 L1 = xi[r % RES_DEPTH][bj * 2], L2 = xi[r % RES_DEPTH][bj * 2 + 1];
;                 const f32x4 T = dpp_ror8(hi ? L1 : L2);
;                 const f32x4 x0 = hi ? T : L1, x1 = hi ? L2 : T;
;                 xo[bj][0] = x0 + gv[bj][0] * acc[ai][bj][m][0]; xo[bj][1] = x1 + gv[bj][1] * acc[ai][bj][m][1];
;             }
;             if (r + RES_DEPTH < 8) {
;                 const int r2 = r + RES_DEPTH;
; #pragma unroll
;                 for (int q = 0; q < 4; ++q) xi[r % RES_DEPTH][q] = *(const f32x4*)(rp0 + (size_t)((r2 >> 2) * 128 + (r2 & 3) * 16 + (q & 1) * 8) * D + (q >> 1) * 128);
;             }
;             float ss = 0.f;
; #pragma unroll
;             for (int bj = 0; bj < 2; ++bj) {
;                 const f32x4 a0 = xo[bj][0], a1 = xo[bj][1];
;                 ss += ((a0[0] * a0[0] + a0[1] * a0[1]) + (a0[2] * a0[2] + a0[3] * a0[3])) + ((a1[0] * a1[0] + a1[1] * a1[1]) + (a1[2] * a1[2] + a1[3] * a1[3]));
;                 const f32x4 T2 = dpp_ror8(hi ? a0 : a1);
;                 const f32x4 d1 = hi ? T2 : a0, d2 = hi ? a1 : T2;
;                 *(f32x4*)(out + mo0 + bj * 128) = d1; *(f32x4*)(out + mo1 + bj * 128) = d2;
;                 if (gm) { const f32x4 o0 = a0 * mv[bj][0], o1 = a1 * mv[bj][1];
;                     u32x2 w0, w1; w0.x = cvt_pk_bf16(o0[0], o0[1]); w0.y = cvt_pk_bf16(o0[2], o0[3]); w1.x = cvt_pk_bf16(o1[0], o1[1]); w1.y = cvt_pk_bf16(o1[2], o1[3]);
;                     const u32x2 T3 = dpp_ror8(hi ? w0 : w1);
;                     const u32x2 e1 = hi ? T3 : w0, e2 = hi ? w1 : T3;
;                     *(u32x2*)(xg + mo0 + bj * 128) = e1; *(u32x2*)(xg + mo1 + bj * 128) = e2; }
;             }
;             ss += __shfl_xor(ss, 16); ss += __shfl_xor(ss, 32);
;             if (fq == 0) rss[(size_t)grow * 16 + u.pn * 4 + wc] = ss;
	v_ashrrev_i32_e32 v145, 31, v144
	v_add_f32_e32 v129, v129, v130
	v_lshlrev_b64 v[144:145], 10, v[144:145]
	v_add_f32_e32 v158, v128, v129
	v_cndmask_b32_e64 v128, v139, v143, s[40:41]
	v_cndmask_b32_e64 v129, v138, v142, s[40:41]
	v_cndmask_b32_e64 v130, v137, v141, s[40:41]
	v_cndmask_b32_e64 v131, v136, v140, s[40:41]
	v_mov_b32_e32 v132, v193
	v_mov_b32_e32 v133, v193
	v_mov_b32_e32 v134, v193
	v_mov_b32_e32 v135, v193
	v_lshl_add_u64 v[144:145], v[144:145], 0, v[176:177]
	v_mov_b32_dpp v132, v131 row_ror:8 row_mask:0xf bank_mask:0xf
	v_mov_b32_dpp v133, v130 row_ror:8 row_mask:0xf bank_mask:0xf
	v_mov_b32_dpp v134, v129 row_ror:8 row_mask:0xf bank_mask:0xf
	v_mov_b32_dpp v135, v128 row_ror:8 row_mask:0xf bank_mask:0xf
	v_cndmask_b32_e64 v131, v135, v139, s[40:41]
	v_cndmask_b32_e64 v130, v134, v138, s[40:41]
	v_cndmask_b32_e64 v129, v133, v137, s[40:41]
	v_cndmask_b32_e64 v128, v132, v136, s[40:41]
	v_lshl_add_u64 v[154:155], v[144:145], 2, s[82:83]
	global_store_dwordx4 v[154:155], v[128:131], off nt
	v_cndmask_b32_e64 v135, v143, v135, s[40:41]
	v_cndmask_b32_e64 v134, v142, v134, s[40:41]
	v_add_co_u32_e32 v128, vcc, s23, v154
	v_cndmask_b32_e64 v133, v141, v133, s[40:41]
	v_cndmask_b32_e64 v132, v140, v132, s[40:41]
	v_addc_co_u32_e32 v129, vcc, 0, v155, vcc
	global_store_dwordx4 v[128:129], v[132:135], off nt
	v_pk_mul_f32 v[128:129], v[62:63], v[138:139]
	v_pk_mul_f32 v[130:131], v[60:61], v[136:137]
	v_pk_mul_f32 v[132:133], v[58:59], v[142:143]
	v_pk_mul_f32 v[134:135], v[56:57], v[140:141]
	v_cvt_pk_bf16_f32 v130, v130, v131
	v_cvt_pk_bf16_f32 v129, v128, v129
	v_lshl_add_u64 v[136:137], v[144:145], 1, s[8:9]
	v_cvt_pk_bf16_f32 v131, v134, v135
	v_cvt_pk_bf16_f32 v132, v132, v133
	v_mov_b32_e32 v134, v193
	v_cndmask_b32_e64 v133, v130, v131, s[40:41]
	v_cndmask_b32_e64 v128, v129, v132, s[40:41]
	v_mov_b32_e32 v135, v193
	v_mov_b32_dpp v134, v133 row_ror:8 row_mask:0xf bank_mask:0xf
	v_mov_b32_e32 v133, v193
	v_lshl_add_u64 v[156:157], v[154:155], 0, s[60:61]
	v_mov_b32_e32 v141, v193
	v_mov_b32_dpp v133, v128 row_ror:8 row_mask:0xf bank_mask:0xf
	v_cndmask_b32_e64 v128, v134, v130, s[40:41]
	v_cndmask_b32_e64 v129, v133, v129, s[40:41]
	global_store_dwordx2 v[136:137], v[128:129], off
	v_add_co_u32_e32 v128, vcc, s2, v136
	v_cndmask_b32_e64 v130, v131, v134, s[40:41]
	v_cndmask_b32_e64 v131, v132, v133, s[40:41]
	v_addc_co_u32_e32 v129, vcc, 0, v137, vcc
	global_store_dwordx2 v[128:129], v[130:131], off
	v_mul_f32_e32 v128, v149, v149
	v_mul_f32_e32 v129, v147, v147
	v_fmac_f32_e32 v128, v148, v148
	v_fmac_f32_e32 v129, v146, v146
	v_add_f32_e32 v128, v128, v129
	v_mul_f32_e32 v129, v153, v153
	v_mul_f32_e32 v130, v151, v151
	v_fmac_f32_e32 v129, v152, v152
	v_fmac_f32_e32 v130, v150, v150
	v_add_f32_e32 v129, v129, v130
	v_add_f32_e32 v128, v128, v129
	v_add_f32_e32 v140, v158, v128
	v_cndmask_b32_e64 v128, v147, v151, s[40:41]
	v_cndmask_b32_e64 v129, v146, v150, s[40:41]
	v_cndmask_b32_e64 v130, v149, v153, s[40:41]
	v_cndmask_b32_e64 v131, v148, v152, s[40:41]
	v_mov_b32_e32 v132, v193
	v_mov_b32_e32 v133, v193
	v_mov_b32_e32 v134, v193
	v_mov_b32_dpp v132, v131 row_ror:8 row_mask:0xf bank_mask:0xf
	v_mov_b32_dpp v133, v130 row_ror:8 row_mask:0xf bank_mask:0xf
	v_mov_b32_dpp v134, v129 row_ror:8 row_mask:0xf bank_mask:0xf
	v_mov_b32_dpp v135, v128 row_ror:8 row_mask:0xf bank_mask:0xf
	v_cndmask_b32_e64 v131, v135, v147, s[40:41]
	v_cndmask_b32_e64 v130, v134, v146, s[40:41]
	v_cndmask_b32_e64 v129, v133, v149, s[40:41]
	v_cndmask_b32_e64 v128, v132, v148, s[40:41]
	v_cndmask_b32_e64 v135, v151, v135, s[40:41]
	v_cndmask_b32_e64 v134, v150, v134, s[40:41]
	v_cndmask_b32_e64 v133, v153, v133, s[40:41]
	v_cndmask_b32_e64 v132, v152, v132, s[40:41]
	global_store_dwordx4 v[154:155], v[128:131], off offset:512 nt
	global_store_dwordx4 v[156:157], v[132:135], off offset:512 nt
	s_mov_b64 s[26:27], 0x4000
	v_pk_mul_f32 v[128:129], v[54:55], v[146:147]
	v_pk_mul_f32 v[130:131], v[52:53], v[148:149]
	v_pk_mul_f32 v[134:135], v[48:49], v[152:153]
	v_cvt_pk_bf16_f32 v130, v130, v131
	v_cvt_pk_bf16_f32 v128, v128, v129
	v_pk_mul_f32 v[132:133], v[50:51], v[150:151]
	v_cvt_pk_bf16_f32 v134, v134, v135
	ds_bpermute_b32 v135, v175, v140
	v_cvt_pk_bf16_f32 v133, v132, v133
	v_cndmask_b32_e64 v131, v130, v134, s[40:41]
	v_cndmask_b32_e64 v129, v128, v133, s[40:41]
	v_mov_b32_e32 v132, v193
	v_lshl_add_u64 v[138:139], v[136:137], 0, s[26:27]
	v_mov_b32_dpp v141, v129 row_ror:8 row_mask:0xf bank_mask:0xf
	v_mov_b32_dpp v132, v131 row_ror:8 row_mask:0xf bank_mask:0xf
	v_cndmask_b32_e64 v131, v141, v128, s[40:41]
	s_waitcnt lgkmcnt(0)
	v_add_f32_e32 v128, v140, v135
	ds_bpermute_b32 v129, v197, v128
	v_cndmask_b32_e64 v130, v132, v130, s[40:41]
	v_cndmask_b32_e64 v132, v134, v132, s[40:41]
	v_cndmask_b32_e64 v133, v133, v141, s[40:41]
	global_store_dwordx2 v[136:137], v[130:131], off offset:256
	global_store_dwordx2 v[138:139], v[132:133], off offset:256
	s_and_saveexec_b64 s[26:27], s[38:39]
	v_readlane_b32 s95, v254, 26
	s_cbranch_execz .LBB0_159
	v_or_b32_e32 v130, 32, v172
	v_ashrrev_i32_e32 v131, 31, v130
	v_lshlrev_b64 v[130:131], 6, v[130:131]
	v_lshl_add_u64 v[130:131], s[96:97], 0, v[130:131]
	v_lshl_add_u64 v[130:131], s[74:75], 2, v[130:131]
	s_lshl_b32 s10, s17, 2
	v_lshl_add_u64 v[130:131], v[130:131], 0, s[10:11]
	s_waitcnt lgkmcnt(0)
	v_add_f32_e32 v128, v128, v129
	global_store_dword v[130:131], v128, off
; __device__ __forceinline__ unsigned cvt_pk_bf16(float lo, float hi) { unsigned r; asm volatile("v_cvt_pk_bf16_f32 %0, %1, %2" : "=v"(r) : "v"(lo), "v"(hi)); return r; }
;     __device__ __forceinline__ void operator()(const f32x4 (&acc)[2][2][4][2], const pg8::Unit& u, int wr, int wc, int fr_, int fq_) const {
;     ...
;         for (int r = 0; r < 8; ++r) {
;             const int ai = r >> 2, m = r & 3;
;             const int grow = grow0 + ai * 128 + m * 16;
;             const size_t mo0 = (size_t)(mrow0 + ai * 128 + m * 16) * D + mcol, mo1 = mo0 + (size_t)8 * D;
;             f32x4 xo[2][2];
; #pragma unroll
;             for (int bj = 0; bj < 2; ++bj) {
;                 const f32x4 L1 = xi[r % RES_DEPTH][bj * 2], L2 = xi[r % RES_DEPTH][bj * 2 + 1];
;                 const f32x4 T = dpp_ror8(hi ? L1 : L2);
;                 const f32x4 x0 = hi ? T : L1, x1 = hi ? L2 : T;
;                 xo[bj][0] = x0 + gv[bj][0] * acc[ai][bj][m][0]; xo[bj][1] = x1 + gv[bj][1] * acc[ai][bj][m][1];
;             }
;             if (r + RES_DEPTH < 8) {
;                 const int r2 = r + RES_DEPTH;
; #pragma unroll
;                 for (int q = 0; q < 4; ++q) xi[r % RES_DEPTH][q] = *(const f32x4*)(rp0 + (size_t)((r2 >> 2) * 128 + (r2 & 3) * 16 + (q & 1) * 8) * D + (q >> 1) * 128);
;             }
;             float ss = 0.f;
; #pragma unroll
;             for (int bj = 0; bj < 2; ++bj) {
;                 const f32x4 a0 = xo[bj][0], a1 = xo[bj][1];
;                 ss += ((a0[0] * a0[0] + a0[1] * a0[1]) + (a0[2] * a0[2] + a0[3] * a0[3])) + ((a1[0] * a1[0] + a1[1] * a1[1]) + (a1[2] * a1[2] + a1[3] * a1[3]));
;                 const f32x4 T2 = dpp_ror8(hi ? a0 : a1);
;                 const f32x4 d1 = hi ? T2 : a0, d2 = hi ? a1 : T2;
;                 *(f32x4*)(out + mo0 + bj * 128) = d1; *(f32x4*)(out + mo1 + bj * 128) = d2;
;                 if (gm) { const f32x4 o0 = a0 * mv[bj][0], o1 = a1 * mv[bj][1];
;                     u32x2 w0, w1; w0.x = cvt_pk_bf16(o0[0], o0[1]); w0.y = cvt_pk_bf16(o0[2], o0[3]); w1.x = cvt_pk_bf16(o1[0], o1[1]); w1.y = cvt_pk_bf16(o1[2], o1[3]);
;                     const u32x2 T3 = dpp_ror8(hi ? w0 : w1);
;                     const u32x2 e1 = hi ? T3 : w0, e2 = hi ? w1 : T3;
;                     *(u32x2*)(xg + mo0 + bj * 128) = e1; *(u32x2*)(xg + mo1 + bj * 128) = e2; }
;             }
.LBB0_159:
	s_or_b64 exec, exec, s[26:27]
	s_waitcnt vmcnt(21)
	v_cndmask_b32_e64 v133, v120, v124, s[40:41]
	v_mov_b32_e32 v134, v193
	v_cndmask_b32_e64 v132, v121, v125, s[40:41]
	v_cndmask_b32_e64 v131, v122, v126, s[40:41]
	v_mov_b32_dpp v134, v133 row_ror:8 row_mask:0xf bank_mask:0xf
	v_mov_b32_e32 v133, v193
	v_cndmask_b32_e64 v130, v123, v127, s[40:41]
	v_cndmask_b32_e64 v120, v134, v120, s[40:41]
	v_mov_b32_dpp v133, v132 row_ror:8 row_mask:0xf bank_mask:0xf
	v_mov_b32_e32 v132, v193
	v_cndmask_b32_e64 v121, v133, v121, s[40:41]
	v_cndmask_b32_e64 v125, v125, v133, s[40:41]
	v_mov_b32_dpp v132, v131 row_ror:8 row_mask:0xf bank_mask:0xf
	v_mov_b32_e32 v131, v193
	v_cndmask_b32_e64 v126, v126, v132, s[40:41]
	v_cndmask_b32_e64 v122, v132, v122, s[40:41]
	v_mov_b32_dpp v131, v130 row_ror:8 row_mask:0xf bank_mask:0xf
	v_cndmask_b32_e64 v127, v127, v131, s[40:41]
	v_cndmask_b32_e64 v123, v131, v123, s[40:41]
	v_cndmask_b32_e64 v124, v124, v134, s[40:41]
	v_pk_fma_f32 v[120:121], v[92:93], v[180:181], v[120:121]
	v_pk_fma_f32 v[126:127], v[90:91], v[182:183], v[126:127]
	s_waitcnt vmcnt(20)
	v_cndmask_b32_e64 v90, v117, v113, s[40:41]
	v_cndmask_b32_e64 v91, v116, v112, s[40:41]
	v_mov_b32_e32 v92, v193
	v_mov_b32_e32 v93, v193
	v_pk_fma_f32 v[122:123], v[94:95], v[178:179], v[122:123]
	v_pk_fma_f32 v[124:125], v[88:89], v[184:185], v[124:125]
	v_cndmask_b32_e64 v88, v119, v115, s[40:41]
	v_cndmask_b32_e64 v89, v118, v114, s[40:41]
	v_mov_b32_dpp v92, v91 row_ror:8 row_mask:0xf bank_mask:0xf
	v_mov_b32_dpp v93, v90 row_ror:8 row_mask:0xf bank_mask:0xf
	v_mov_b32_e32 v94, v193
	v_mov_b32_e32 v95, v193
	s_mov_b32 s10, 0x90000
	v_mov_b32_dpp v94, v89 row_ror:8 row_mask:0xf bank_mask:0xf
	v_mov_b32_dpp v95, v88 row_ror:8 row_mask:0xf bank_mask:0xf
	v_cndmask_b32_e64 v89, v93, v117, s[40:41]
	v_cndmask_b32_e64 v88, v92, v116, s[40:41]
	v_cndmask_b32_e64 v93, v113, v93, s[40:41]
	v_cndmask_b32_e64 v92, v112, v92, s[40:41]
	v_pk_fma_f32 v[136:137], v[80:81], v[186:187], v[92:93]
	v_add_co_u32_e32 v80, vcc, s10, v210
	v_cndmask_b32_e64 v91, v95, v119, s[40:41]
	v_cndmask_b32_e64 v90, v94, v118, s[40:41]
	v_cndmask_b32_e64 v95, v115, v95, s[40:41]
	v_cndmask_b32_e64 v94, v114, v94, s[40:41]
	v_addc_co_u32_e32 v81, vcc, 0, v211, vcc
	s_mov_b32 s10, 0x98000
	v_pk_fma_f32 v[134:135], v[82:83], v[188:189], v[94:95]
	v_add_co_u32_e32 v82, vcc, s10, v210
	v_pk_fma_f32 v[130:131], v[86:87], v[208:209], v[90:91]
	s_nop 0
	v_addc_co_u32_e32 v83, vcc, 0, v211, vcc
	v_pk_fma_f32 v[132:133], v[84:85], v[190:191], v[88:89]
	global_load_dwordx4 v[88:91], v[80:81], off nt
	global_load_dwordx4 v[84:87], v[80:81], off offset:512 nt
	global_load_dwordx4 v[92:95], v[82:83], off nt
	s_nop 0
	global_load_dwordx4 v[80:83], v[82:83], off offset:512 nt
	v_mul_f32_e32 v112, v121, v121
	v_mul_f32_e32 v113, v123, v123
	v_fmac_f32_e32 v112, v120, v120
	v_fmac_f32_e32 v113, v122, v122
	v_add_f32_e32 v112, v112, v113
	v_mul_f32_e32 v113, v125, v125
	v_mul_f32_e32 v114, v127, v127
	v_or_b32_e32 v128, 48, v174
	v_fmac_f32_e32 v113, v124, v124
	v_fmac_f32_e32 v114, v126, v126
	s_waitcnt lgkmcnt(0)
	v_ashrrev_i32_e32 v129, 31, v128
	v_add_f32_e32 v113, v113, v114
	v_lshlrev_b64 v[128:129], 10, v[128:129]
	v_add_f32_e32 v142, v112, v113
	v_cndmask_b32_e64 v112, v123, v127, s[40:41]
	v_cndmask_b32_e64 v113, v122, v126, s[40:41]
	v_cndmask_b32_e64 v114, v121, v125, s[40:41]
	v_cndmask_b32_e64 v115, v120, v124, s[40:41]
	v_mov_b32_e32 v116, v193
	v_mov_b32_e32 v117, v193
	v_mov_b32_e32 v118, v193
	v_mov_b32_e32 v119, v193
	v_lshl_add_u64 v[128:129], v[128:129], 0, v[176:177]
	v_mov_b32_dpp v116, v115 row_ror:8 row_mask:0xf bank_mask:0xf
	v_mov_b32_dpp v117, v114 row_ror:8 row_mask:0xf bank_mask:0xf
	v_mov_b32_dpp v118, v113 row_ror:8 row_mask:0xf bank_mask:0xf
	v_mov_b32_dpp v119, v112 row_ror:8 row_mask:0xf bank_mask:0xf
	v_cndmask_b32_e64 v115, v119, v123, s[40:41]
	v_cndmask_b32_e64 v114, v118, v122, s[40:41]
	v_cndmask_b32_e64 v113, v117, v121, s[40:41]
	v_cndmask_b32_e64 v112, v116, v120, s[40:41]
	v_lshl_add_u64 v[138:139], v[128:129], 2, s[82:83]
	global_store_dwordx4 v[138:139], v[112:115], off nt
	v_cndmask_b32_e64 v119, v127, v119, s[40:41]
	v_cndmask_b32_e64 v118, v126, v118, s[40:41]
	v_add_co_u32_e32 v112, vcc, s23, v138
	v_cndmask_b32_e64 v117, v125, v117, s[40:41]
	v_cndmask_b32_e64 v116, v124, v116, s[40:41]
	v_addc_co_u32_e32 v113, vcc, 0, v139, vcc
	global_store_dwordx4 v[112:113], v[116:119], off nt
	v_pk_mul_f32 v[112:113], v[62:63], v[122:123]
	v_pk_mul_f32 v[114:115], v[60:61], v[120:121]
	v_pk_mul_f32 v[116:117], v[58:59], v[126:127]
	v_pk_mul_f32 v[118:119], v[56:57], v[124:125]
	v_cvt_pk_bf16_f32 v114, v114, v115
	v_cvt_pk_bf16_f32 v113, v112, v113
	v_lshl_add_u64 v[120:121], v[128:129], 1, s[8:9]
	v_cvt_pk_bf16_f32 v115, v118, v119
	v_cvt_pk_bf16_f32 v116, v116, v117
	v_mov_b32_e32 v118, v193
	v_cndmask_b32_e64 v117, v114, v115, s[40:41]
	v_cndmask_b32_e64 v112, v113, v116, s[40:41]
	v_mov_b32_e32 v119, v193
	v_mov_b32_dpp v118, v117 row_ror:8 row_mask:0xf bank_mask:0xf
	v_mov_b32_e32 v117, v193
	v_lshl_add_u64 v[140:141], v[138:139], 0, s[60:61]
	v_mov_b32_e32 v125, v193
	v_mov_b32_dpp v117, v112 row_ror:8 row_mask:0xf bank_mask:0xf
	v_cndmask_b32_e64 v112, v118, v114, s[40:41]
	v_cndmask_b32_e64 v113, v117, v113, s[40:41]
	global_store_dwordx2 v[120:121], v[112:113], off
	v_add_co_u32_e32 v112, vcc, s2, v120
	v_cndmask_b32_e64 v114, v115, v118, s[40:41]
	v_cndmask_b32_e64 v115, v116, v117, s[40:41]
	v_addc_co_u32_e32 v113, vcc, 0, v121, vcc
	global_store_dwordx2 v[112:113], v[114:115], off
	v_mul_f32_e32 v112, v133, v133
	v_mul_f32_e32 v113, v131, v131
;     __device__ __forceinline__ void operator()(const f32x4 (&acc)[2][2][4][2], const pg8::Unit& u, int wr, int wc, int fr_, int fq_) const {
;     ...
;         for (int r = 0; r < 8; ++r) {
;             const int ai = r >> 2, m = r & 3;
;             const int grow = grow0 + ai * 128 + m * 16;
;             const size_t mo0 = (size_t)(mrow0 + ai * 128 + m * 16) * D + mcol, mo1 = mo0 + (size_t)8 * D;
;             f32x4 xo[2][2];
; #pragma unroll
;             for (int bj = 0; bj < 2; ++bj) {
;                 const f32x4 L1 = xi[r % RES_DEPTH][bj * 2], L2 = xi[r % RES_DEPTH][bj * 2 + 1];
;                 const f32x4 T = dpp_ror8(hi ? L1 : L2);
;                 const f32x4 x0 = hi ? T : L1, x1 = hi ? L2 : T;
;                 xo[bj][0] = x0 + gv[bj][0] * acc[ai][bj][m][0]; xo[bj][1] = x1 + gv[bj][1] * acc[ai][bj][m][1];
;             }
;             if (r + RES_DEPTH < 8) {
;                 const int r2 = r + RES_DEPTH;
; #pragma unroll
;                 for (int q = 0; q < 4; ++q) xi[r % RES_DEPTH][q] = *(const f32x4*)(rp0 + (size_t)((r2 >> 2) * 128 + (r2 & 3) * 16 + (q & 1) * 8) * D + (q >> 1) * 128);
;             }
;             float ss = 0.f;
; #pragma unroll
;             for (int bj = 0; bj < 2; ++bj) {
;                 const f32x4 a0 = xo[bj][0], a1 = xo[bj][1];
;                 ss += ((a0[0] * a0[0] + a0[1] * a0[1]) + (a0[2] * a0[2] + a0[3] * a0[3])) + ((a1[0] * a1[0] + a1[1] * a1[1]) + (a1[2] * a1[2] + a1[3] * a1[3]));
;                 const f32x4 T2 = dpp_ror8(hi ? a0 : a1);
;                 const f32x4 d1 = hi ? T2 : a0, d2 = hi ? a1 : T2;
;                 *(f32x4*)(out + mo0 + bj * 128) = d1; *(f32x4*)(out + mo1 + bj * 128) = d2;
;                 if (gm) { const f32x4 o0 = a0 * mv[bj][0], o1 = a1 * mv[bj][1];
;                     u32x2 w0, w1; w0.x = cvt_pk_bf16(o0[0], o0[1]); w0.y = cvt_pk_bf16(o0[2], o0[3]); w1.x = cvt_pk_bf16(o1[0], o1[1]); w1.y = cvt_pk_bf16(o1[2], o1[3]);
;                     const u32x2 T3 = dpp_ror8(hi ? w0 : w1);
;                     const u32x2 e1 = hi ? T3 : w0, e2 = hi ? w1 : T3;
;                     *(u32x2*)(xg + mo0 + bj * 128) = e1; *(u32x2*)(xg + mo1 + bj * 128) = e2; }
;             }
;             ss += __shfl_xor(ss, 16); ss += __shfl_xor(ss, 32);
;             if (fq == 0) rss[(size_t)grow * 16 + u.pn * 4 + wc] = ss;
	v_fmac_f32_e32 v112, v132, v132
	v_fmac_f32_e32 v113, v130, v130
	v_add_f32_e32 v112, v112, v113
	v_mul_f32_e32 v113, v137, v137
	v_mul_f32_e32 v114, v135, v135
	v_fmac_f32_e32 v113, v136, v136
	v_fmac_f32_e32 v114, v134, v134
	v_add_f32_e32 v113, v113, v114
	v_add_f32_e32 v112, v112, v113
	v_add_f32_e32 v124, v142, v112
	v_cndmask_b32_e64 v112, v131, v135, s[40:41]
	v_cndmask_b32_e64 v113, v130, v134, s[40:41]
	v_cndmask_b32_e64 v114, v133, v137, s[40:41]
	v_cndmask_b32_e64 v115, v132, v136, s[40:41]
	v_mov_b32_e32 v116, v193
	v_mov_b32_e32 v117, v193
	v_mov_b32_e32 v118, v193
	v_mov_b32_dpp v116, v115 row_ror:8 row_mask:0xf bank_mask:0xf
	v_mov_b32_dpp v117, v114 row_ror:8 row_mask:0xf bank_mask:0xf
	v_mov_b32_dpp v118, v113 row_ror:8 row_mask:0xf bank_mask:0xf
	v_mov_b32_dpp v119, v112 row_ror:8 row_mask:0xf bank_mask:0xf
	v_cndmask_b32_e64 v115, v119, v131, s[40:41]
	v_cndmask_b32_e64 v114, v118, v130, s[40:41]
	v_cndmask_b32_e64 v113, v117, v133, s[40:41]
	v_cndmask_b32_e64 v112, v116, v132, s[40:41]
	v_cndmask_b32_e64 v119, v135, v119, s[40:41]
	v_cndmask_b32_e64 v118, v134, v118, s[40:41]
	v_cndmask_b32_e64 v117, v137, v117, s[40:41]
	v_cndmask_b32_e64 v116, v136, v116, s[40:41]
	global_store_dwordx4 v[138:139], v[112:115], off offset:512 nt
	global_store_dwordx4 v[140:141], v[116:119], off offset:512 nt
	s_mov_b64 s[26:27], 0x4000
	v_pk_mul_f32 v[112:113], v[54:55], v[130:131]
	v_pk_mul_f32 v[114:115], v[52:53], v[132:133]
	v_pk_mul_f32 v[118:119], v[48:49], v[136:137]
	v_cvt_pk_bf16_f32 v114, v114, v115
	v_cvt_pk_bf16_f32 v112, v112, v113
	v_pk_mul_f32 v[116:117], v[50:51], v[134:135]
	v_cvt_pk_bf16_f32 v118, v118, v119
	ds_bpermute_b32 v119, v175, v124
	v_cvt_pk_bf16_f32 v117, v116, v117
	v_cndmask_b32_e64 v115, v114, v118, s[40:41]
	v_cndmask_b32_e64 v113, v112, v117, s[40:41]
	v_mov_b32_e32 v116, v193
	v_lshl_add_u64 v[122:123], v[120:121], 0, s[26:27]
	v_mov_b32_dpp v125, v113 row_ror:8 row_mask:0xf bank_mask:0xf
	v_mov_b32_dpp v116, v115 row_ror:8 row_mask:0xf bank_mask:0xf
	v_cndmask_b32_e64 v115, v125, v112, s[40:41]
	s_waitcnt lgkmcnt(0)
	v_add_f32_e32 v112, v124, v119
	ds_bpermute_b32 v113, v197, v112
	v_cndmask_b32_e64 v114, v116, v114, s[40:41]
	v_cndmask_b32_e64 v116, v118, v116, s[40:41]
	v_cndmask_b32_e64 v117, v117, v125, s[40:41]
	global_store_dwordx2 v[120:121], v[114:115], off offset:256
	global_store_dwordx2 v[122:123], v[116:117], off offset:256
	s_and_saveexec_b64 s[26:27], s[38:39]
	s_cbranch_execz .LBB0_161
	v_or_b32_e32 v114, 48, v172
	v_ashrrev_i32_e32 v115, 31, v114
	v_lshlrev_b64 v[114:115], 6, v[114:115]
	v_lshl_add_u64 v[114:115], s[96:97], 0, v[114:115]
	v_lshl_add_u64 v[114:115], s[74:75], 2, v[114:115]
	s_lshl_b32 s10, s17, 2
	v_lshl_add_u64 v[114:115], v[114:115], 0, s[10:11]
	s_waitcnt lgkmcnt(0)
	v_add_f32_e32 v112, v112, v113
	global_store_dword v[114:115], v112, off
.LBB0_161:
	s_or_b64 exec, exec, s[26:27]
	s_waitcnt vmcnt(21)
	v_cndmask_b32_e64 v117, v104, v108, s[40:41]
	v_mov_b32_e32 v118, v193
	v_cndmask_b32_e64 v116, v105, v109, s[40:41]
	v_cndmask_b32_e64 v115, v106, v110, s[40:41]
	v_mov_b32_dpp v118, v117 row_ror:8 row_mask:0xf bank_mask:0xf
	v_mov_b32_e32 v117, v193
	v_cndmask_b32_e64 v114, v107, v111, s[40:41]
	v_cndmask_b32_e64 v104, v118, v104, s[40:41]
	v_mov_b32_dpp v117, v116 row_ror:8 row_mask:0xf bank_mask:0xf
	v_mov_b32_e32 v116, v193
	v_cndmask_b32_e64 v105, v117, v105, s[40:41]
	v_cndmask_b32_e64 v109, v109, v117, s[40:41]
	v_mov_b32_dpp v116, v115 row_ror:8 row_mask:0xf bank_mask:0xf
	v_mov_b32_e32 v115, v193
	v_cndmask_b32_e64 v110, v110, v116, s[40:41]
	v_cndmask_b32_e64 v106, v116, v106, s[40:41]
	v_mov_b32_dpp v115, v114 row_ror:8 row_mask:0xf bank_mask:0xf
	v_cndmask_b32_e64 v111, v111, v115, s[40:41]
	v_cndmask_b32_e64 v107, v115, v107, s[40:41]
	v_cndmask_b32_e64 v108, v108, v118, s[40:41]
	v_pk_fma_f32 v[104:105], v[76:77], v[180:181], v[104:105]
	v_pk_fma_f32 v[110:111], v[74:75], v[182:183], v[110:111]
	s_waitcnt vmcnt(20)
	v_cndmask_b32_e64 v74, v101, v97, s[40:41]
	v_cndmask_b32_e64 v75, v100, v96, s[40:41]
	v_mov_b32_e32 v76, v193
	v_mov_b32_e32 v77, v193
	v_pk_fma_f32 v[106:107], v[78:79], v[178:179], v[106:107]
	v_pk_fma_f32 v[108:109], v[72:73], v[184:185], v[108:109]
	v_cndmask_b32_e64 v72, v103, v99, s[40:41]
	v_cndmask_b32_e64 v73, v102, v98, s[40:41]
	v_mov_b32_dpp v76, v75 row_ror:8 row_mask:0xf bank_mask:0xf
	v_mov_b32_dpp v77, v74 row_ror:8 row_mask:0xf bank_mask:0xf
	v_mov_b32_e32 v78, v193
	v_mov_b32_e32 v79, v193
	s_mov_b32 s10, 0xa0000
	v_mov_b32_dpp v78, v73 row_ror:8 row_mask:0xf bank_mask:0xf
	v_mov_b32_dpp v79, v72 row_ror:8 row_mask:0xf bank_mask:0xf
	v_cndmask_b32_e64 v73, v77, v101, s[40:41]
	v_cndmask_b32_e64 v72, v76, v100, s[40:41]
	v_pk_fma_f32 v[116:117], v[68:69], v[190:191], v[72:73]
	v_add_co_u32_e32 v68, vcc, s10, v210
	s_mov_b32 s10, 0xa8000
	s_nop 0
	v_addc_co_u32_e32 v69, vcc, 0, v211, vcc
	v_add_co_u32_e32 v72, vcc, s10, v210
	v_cndmask_b32_e64 v75, v79, v103, s[40:41]
	v_cndmask_b32_e64 v74, v78, v102, s[40:41]
	v_cndmask_b32_e64 v77, v97, v77, s[40:41]
	v_cndmask_b32_e64 v76, v96, v76, s[40:41]
	v_cndmask_b32_e64 v79, v99, v79, s[40:41]
	v_cndmask_b32_e64 v78, v98, v78, s[40:41]
	v_addc_co_u32_e32 v73, vcc, 0, v211, vcc
	v_pk_fma_f32 v[114:115], v[70:71], v[208:209], v[74:75]
	v_pk_fma_f32 v[118:119], v[66:67], v[188:189], v[78:79]
	v_pk_fma_f32 v[120:121], v[64:65], v[186:187], v[76:77]
	global_load_dwordx4 v[64:67], v[68:69], off nt
	global_load_dwordx4 v[76:79], v[68:69], off offset:512 nt
	s_nop 0
	global_load_dwordx4 v[68:71], v[72:73], off nt
	s_nop 0
	global_load_dwordx4 v[72:75], v[72:73], off offset:512 nt
	v_mul_f32_e32 v96, v105, v105
	v_mul_f32_e32 v97, v107, v107
	v_fmac_f32_e32 v96, v104, v104
	v_fmac_f32_e32 v97, v106, v106
	v_add_f32_e32 v96, v96, v97
	v_mul_f32_e32 v97, v109, v109
	v_mul_f32_e32 v98, v111, v111
	v_add_u32_e32 v112, 0x80, v174
	v_fmac_f32_e32 v97, v108, v108
	v_fmac_f32_e32 v98, v110, v110
	s_waitcnt lgkmcnt(0)
;     __device__ __forceinline__ void operator()(const f32x4 (&acc)[2][2][4][2], const pg8::Unit& u, int wr, int wc, int fr_, int fq_) const {
;     ...
;         for (int r = 0; r < 8; ++r) {
;             const int ai = r >> 2, m = r & 3;
;             const int grow = grow0 + ai * 128 + m * 16;
;             const size_t mo0 = (size_t)(mrow0 + ai * 128 + m * 16) * D + mcol, mo1 = mo0 + (size_t)8 * D;
;             f32x4 xo[2][2];
; #pragma unroll
;             for (int bj = 0; bj < 2; ++bj) {
;                 const f32x4 L1 = xi[r % RES_DEPTH][bj * 2], L2 = xi[r % RES_DEPTH][bj * 2 + 1];
;                 const f32x4 T = dpp_ror8(hi ? L1 : L2);
;                 const f32x4 x0 = hi ? T : L1, x1 = hi ? L2 : T;
;                 xo[bj][0] = x0 + gv[bj][0] * acc[ai][bj][m][0]; xo[bj][1] = x1 + gv[bj][1] * acc[ai][bj][m][1];
;             }
;             if (r + RES_DEPTH < 8) {
;                 const int r2 = r + RES_DEPTH;
; #pragma unroll
;                 for (int q = 0; q < 4; ++q) xi[r % RES_DEPTH][q] = *(const f32x4*)(rp0 + (size_t)((r2 >> 2) * 128 + (r2 & 3) * 16 + (q & 1) * 8) * D + (q >> 1) * 128);
;             }
;             float ss = 0.f;
; #pragma unroll
;             for (int bj = 0; bj < 2; ++bj) {
;                 const f32x4 a0 = xo[bj][0], a1 = xo[bj][1];
;                 ss += ((a0[0] * a0[0] + a0[1] * a0[1]) + (a0[2] * a0[2] + a0[3] * a0[3])) + ((a1[0] * a1[0] + a1[1] * a1[1]) + (a1[2] * a1[2] + a1[3] * a1[3]));
;                 const f32x4 T2 = dpp_ror8(hi ? a0 : a1);
;                 const f32x4 d1 = hi ? T2 : a0, d2 = hi ? a1 : T2;
;                 *(f32x4*)(out + mo0 + bj * 128) = d1; *(f32x4*)(out + mo1 + bj * 128) = d2;
;                 if (gm) { const f32x4 o0 = a0 * mv[bj][0], o1 = a1 * mv[bj][1];
;                     u32x2 w0, w1; w0.x = cvt_pk_bf16(o0[0], o0[1]); w0.y = cvt_pk_bf16(o0[2], o0[3]); w1.x = cvt_pk_bf16(o1[0], o1[1]); w1.y = cvt_pk_bf16(o1[2], o1[3]);
;                     const u32x2 T3 = dpp_ror8(hi ? w0 : w1);
;                     const u32x2 e1 = hi ? T3 : w0, e2 = hi ? w1 : T3;
;                     *(u32x2*)(xg + mo0 + bj * 128) = e1; *(u32x2*)(xg + mo1 + bj * 128) = e2; }
;             }
;             ss += __shfl_xor(ss, 16); ss += __shfl_xor(ss, 32);
;             if (fq == 0) rss[(size_t)grow * 16 + u.pn * 4 + wc] = ss;
	v_ashrrev_i32_e32 v113, 31, v112
	v_add_f32_e32 v97, v97, v98
	v_lshlrev_b64 v[112:113], 10, v[112:113]
	v_add_f32_e32 v126, v96, v97
	v_cndmask_b32_e64 v96, v107, v111, s[40:41]
	v_cndmask_b32_e64 v97, v106, v110, s[40:41]
	v_cndmask_b32_e64 v98, v105, v109, s[40:41]
	v_cndmask_b32_e64 v99, v104, v108, s[40:41]
	v_mov_b32_e32 v100, v193
	v_mov_b32_e32 v101, v193
	v_mov_b32_e32 v102, v193
	v_mov_b32_e32 v103, v193
	v_lshl_add_u64 v[112:113], v[112:113], 0, v[176:177]
	v_mov_b32_dpp v100, v99 row_ror:8 row_mask:0xf bank_mask:0xf
	v_mov_b32_dpp v101, v98 row_ror:8 row_mask:0xf bank_mask:0xf
	v_mov_b32_dpp v102, v97 row_ror:8 row_mask:0xf bank_mask:0xf
	v_mov_b32_dpp v103, v96 row_ror:8 row_mask:0xf bank_mask:0xf
	v_cndmask_b32_e64 v99, v103, v107, s[40:41]
	v_cndmask_b32_e64 v98, v102, v106, s[40:41]
	v_cndmask_b32_e64 v97, v101, v105, s[40:41]
	v_cndmask_b32_e64 v96, v100, v104, s[40:41]
	v_lshl_add_u64 v[122:123], v[112:113], 2, s[82:83]
	global_store_dwordx4 v[122:123], v[96:99], off nt
	v_cndmask_b32_e64 v103, v111, v103, s[40:41]
	v_cndmask_b32_e64 v102, v110, v102, s[40:41]
	v_add_co_u32_e32 v96, vcc, s23, v122
	v_cndmask_b32_e64 v101, v109, v101, s[40:41]
	v_cndmask_b32_e64 v100, v108, v100, s[40:41]
	v_addc_co_u32_e32 v97, vcc, 0, v123, vcc
	global_store_dwordx4 v[96:97], v[100:103], off nt
	v_pk_mul_f32 v[96:97], v[62:63], v[106:107]
	v_pk_mul_f32 v[98:99], v[60:61], v[104:105]
	v_pk_mul_f32 v[100:101], v[58:59], v[110:111]
	v_pk_mul_f32 v[102:103], v[56:57], v[108:109]
	v_cvt_pk_bf16_f32 v98, v98, v99
	v_cvt_pk_bf16_f32 v97, v96, v97
	v_lshl_add_u64 v[104:105], v[112:113], 1, s[8:9]
	v_cvt_pk_bf16_f32 v99, v102, v103
	v_cvt_pk_bf16_f32 v100, v100, v101
	v_mov_b32_e32 v102, v193
	v_cndmask_b32_e64 v101, v98, v99, s[40:41]
	v_cndmask_b32_e64 v96, v97, v100, s[40:41]
	v_mov_b32_e32 v103, v193
	v_mov_b32_dpp v102, v101 row_ror:8 row_mask:0xf bank_mask:0xf
	v_mov_b32_e32 v101, v193
	v_lshl_add_u64 v[124:125], v[122:123], 0, s[60:61]
	v_mov_b32_e32 v109, v193
	v_mov_b32_dpp v101, v96 row_ror:8 row_mask:0xf bank_mask:0xf
	v_cndmask_b32_e64 v96, v102, v98, s[40:41]
	v_cndmask_b32_e64 v97, v101, v97, s[40:41]
	global_store_dwordx2 v[104:105], v[96:97], off
	v_add_co_u32_e32 v96, vcc, s2, v104
	v_cndmask_b32_e64 v98, v99, v102, s[40:41]
	v_cndmask_b32_e64 v99, v100, v101, s[40:41]
	v_addc_co_u32_e32 v97, vcc, 0, v105, vcc
	global_store_dwordx2 v[96:97], v[98:99], off
	v_mul_f32_e32 v96, v117, v117
	v_mul_f32_e32 v97, v115, v115
	v_fmac_f32_e32 v96, v116, v116
	v_fmac_f32_e32 v97, v114, v114
	v_add_f32_e32 v96, v96, v97
	v_mul_f32_e32 v97, v121, v121
	v_mul_f32_e32 v98, v119, v119
	v_fmac_f32_e32 v97, v120, v120
	v_fmac_f32_e32 v98, v118, v118
	v_add_f32_e32 v97, v97, v98
	v_add_f32_e32 v96, v96, v97
	v_add_f32_e32 v108, v126, v96
	v_cndmask_b32_e64 v96, v115, v119, s[40:41]
	v_cndmask_b32_e64 v97, v114, v118, s[40:41]
	v_cndmask_b32_e64 v98, v117, v121, s[40:41]
	v_cndmask_b32_e64 v99, v116, v120, s[40:41]
	v_mov_b32_e32 v100, v193
	v_mov_b32_e32 v101, v193
	v_mov_b32_e32 v102, v193
	v_mov_b32_dpp v100, v99 row_ror:8 row_mask:0xf bank_mask:0xf
	v_mov_b32_dpp v101, v98 row_ror:8 row_mask:0xf bank_mask:0xf
	v_mov_b32_dpp v102, v97 row_ror:8 row_mask:0xf bank_mask:0xf
	v_mov_b32_dpp v103, v96 row_ror:8 row_mask:0xf bank_mask:0xf
	v_cndmask_b32_e64 v99, v103, v115, s[40:41]
	v_cndmask_b32_e64 v98, v102, v114, s[40:41]
	v_cndmask_b32_e64 v97, v101, v117, s[40:41]
	v_cndmask_b32_e64 v96, v100, v116, s[40:41]
	v_cndmask_b32_e64 v103, v119, v103, s[40:41]
	v_cndmask_b32_e64 v102, v118, v102, s[40:41]
	v_cndmask_b32_e64 v101, v121, v101, s[40:41]
	v_cndmask_b32_e64 v100, v120, v100, s[40:41]
	global_store_dwordx4 v[122:123], v[96:99], off offset:512 nt
	global_store_dwordx4 v[124:125], v[100:103], off offset:512 nt
	s_mov_b64 s[26:27], 0x4000
	v_pk_mul_f32 v[96:97], v[54:55], v[114:115]
	v_pk_mul_f32 v[98:99], v[52:53], v[116:117]
	v_pk_mul_f32 v[102:103], v[48:49], v[120:121]
	v_cvt_pk_bf16_f32 v98, v98, v99
	v_cvt_pk_bf16_f32 v96, v96, v97
	v_pk_mul_f32 v[100:101], v[50:51], v[118:119]
	v_cvt_pk_bf16_f32 v102, v102, v103
	ds_bpermute_b32 v103, v175, v108
	v_cvt_pk_bf16_f32 v101, v100, v101
	v_cndmask_b32_e64 v99, v98, v102, s[40:41]
	v_cndmask_b32_e64 v97, v96, v101, s[40:41]
	v_mov_b32_e32 v100, v193
	v_lshl_add_u64 v[106:107], v[104:105], 0, s[26:27]
	v_mov_b32_dpp v109, v97 row_ror:8 row_mask:0xf bank_mask:0xf
	v_mov_b32_dpp v100, v99 row_ror:8 row_mask:0xf bank_mask:0xf
	v_cndmask_b32_e64 v99, v109, v96, s[40:41]
	s_waitcnt lgkmcnt(0)
	v_add_f32_e32 v96, v108, v103
	ds_bpermute_b32 v97, v197, v96
	v_cndmask_b32_e64 v98, v100, v98, s[40:41]
	v_cndmask_b32_e64 v100, v102, v100, s[40:41]
	v_cndmask_b32_e64 v101, v101, v109, s[40:41]
	global_store_dwordx2 v[104:105], v[98:99], off offset:256
	global_store_dwordx2 v[106:107], v[100:101], off offset:256
	s_and_saveexec_b64 s[26:27], s[38:39]
	s_cbranch_execz .LBB0_163
	v_lshlrev_b64 v[98:99], 6, v[172:173]
	v_lshl_add_u64 v[98:99], s[96:97], 0, v[98:99]
	v_lshl_add_u64 v[98:99], s[74:75], 2, v[98:99]
	s_lshl_b32 s10, s17, 2
	v_lshl_add_u64 v[98:99], v[98:99], 0, s[10:11]
	s_waitcnt lgkmcnt(0)
	v_add_f32_e32 v100, v96, v97
	v_add_co_u32_e32 v96, vcc, 0x2000, v98
	s_nop 1
	v_addc_co_u32_e32 v97, vcc, 0, v99, vcc
	global_store_dword v[96:97], v100, off
; __device__ __forceinline__ unsigned cvt_pk_bf16(float lo, float hi) { unsigned r; asm volatile("v_cvt_pk_bf16_f32 %0, %1, %2" : "=v"(r) : "v"(lo), "v"(hi)); return r; }
;     __device__ __forceinline__ void operator()(const f32x4 (&acc)[2][2][4][2], const pg8::Unit& u, int wr, int wc, int fr_, int fq_) const {
;     ...
;         for (int r = 0; r < 8; ++r) {
;             const int ai = r >> 2, m = r & 3;
;             const int grow = grow0 + ai * 128 + m * 16;
;             const size_t mo0 = (size_t)(mrow0 + ai * 128 + m * 16) * D + mcol, mo1 = mo0 + (size_t)8 * D;
;             f32x4 xo[2][2];
; #pragma unroll
;             for (int bj = 0; bj < 2; ++bj) {
;                 const f32x4 L1 = xi[r % RES_DEPTH][bj * 2], L2 = xi[r % RES_DEPTH][bj * 2 + 1];
;                 const f32x4 T = dpp_ror8(hi ? L1 : L2);
;                 const f32x4 x0 = hi ? T : L1, x1 = hi ? L2 : T;
;                 xo[bj][0] = x0 + gv[bj][0] * acc[ai][bj][m][0]; xo[bj][1] = x1 + gv[bj][1] * acc[ai][bj][m][1];
;             }
;             if (r + RES_DEPTH < 8) {
;                 const int r2 = r + RES_DEPTH;
; #pragma unroll
;                 for (int q = 0; q < 4; ++q) xi[r % RES_DEPTH][q] = *(const f32x4*)(rp0 + (size_t)((r2 >> 2) * 128 + (r2 & 3) * 16 + (q & 1) * 8) * D + (q >> 1) * 128);
;             }
;             float ss = 0.f;
; #pragma unroll
;             for (int bj = 0; bj < 2; ++bj) {
;                 const f32x4 a0 = xo[bj][0], a1 = xo[bj][1];
;                 ss += ((a0[0] * a0[0] + a0[1] * a0[1]) + (a0[2] * a0[2] + a0[3] * a0[3])) + ((a1[0] * a1[0] + a1[1] * a1[1]) + (a1[2] * a1[2] + a1[3] * a1[3]));
;                 const f32x4 T2 = dpp_ror8(hi ? a0 : a1);
;                 const f32x4 d1 = hi ? T2 : a0, d2 = hi ? a1 : T2;
;                 *(f32x4*)(out + mo0 + bj * 128) = d1; *(f32x4*)(out + mo1 + bj * 128) = d2;
;                 if (gm) { const f32x4 o0 = a0 * mv[bj][0], o1 = a1 * mv[bj][1];
;                     u32x2 w0, w1; w0.x = cvt_pk_bf16(o0[0], o0[1]); w0.y = cvt_pk_bf16(o0[2], o0[3]); w1.x = cvt_pk_bf16(o1[0], o1[1]); w1.y = cvt_pk_bf16(o1[2], o1[3]);
;                     const u32x2 T3 = dpp_ror8(hi ? w0 : w1);
;                     const u32x2 e1 = hi ? T3 : w0, e2 = hi ? w1 : T3;
;                     *(u32x2*)(xg + mo0 + bj * 128) = e1; *(u32x2*)(xg + mo1 + bj * 128) = e2; }
;             }
.LBB0_163:
	s_or_b64 exec, exec, s[26:27]
	s_waitcnt vmcnt(21)
	v_cndmask_b32_e64 v101, v88, v92, s[40:41]
	v_mov_b32_e32 v102, v193
	v_cndmask_b32_e64 v100, v89, v93, s[40:41]
	v_cndmask_b32_e64 v99, v90, v94, s[40:41]
	v_mov_b32_dpp v102, v101 row_ror:8 row_mask:0xf bank_mask:0xf
	v_mov_b32_e32 v101, v193
	v_cndmask_b32_e64 v98, v91, v95, s[40:41]
	v_cndmask_b32_e64 v88, v102, v88, s[40:41]
	v_mov_b32_dpp v101, v100 row_ror:8 row_mask:0xf bank_mask:0xf
	v_mov_b32_e32 v100, v193
	v_cndmask_b32_e64 v89, v101, v89, s[40:41]
	v_cndmask_b32_e64 v93, v93, v101, s[40:41]
	v_mov_b32_dpp v100, v99 row_ror:8 row_mask:0xf bank_mask:0xf
	v_mov_b32_e32 v99, v193
	v_cndmask_b32_e64 v94, v94, v100, s[40:41]
	v_cndmask_b32_e64 v90, v100, v90, s[40:41]
	v_mov_b32_dpp v99, v98 row_ror:8 row_mask:0xf bank_mask:0xf
	v_cndmask_b32_e64 v95, v95, v99, s[40:41]
	v_cndmask_b32_e64 v91, v99, v91, s[40:41]
	v_cndmask_b32_e64 v92, v92, v102, s[40:41]
	v_pk_fma_f32 v[88:89], v[44:45], v[180:181], v[88:89]
	v_pk_fma_f32 v[94:95], v[42:43], v[182:183], v[94:95]
	s_waitcnt vmcnt(20)
	v_cndmask_b32_e64 v42, v85, v81, s[40:41]
	v_cndmask_b32_e64 v43, v84, v80, s[40:41]
	v_mov_b32_e32 v44, v193
	v_mov_b32_e32 v45, v193
	v_pk_fma_f32 v[90:91], v[46:47], v[178:179], v[90:91]
	v_pk_fma_f32 v[92:93], v[40:41], v[184:185], v[92:93]
	v_cndmask_b32_e64 v40, v87, v83, s[40:41]
	v_cndmask_b32_e64 v41, v86, v82, s[40:41]
	v_mov_b32_dpp v44, v43 row_ror:8 row_mask:0xf bank_mask:0xf
	v_mov_b32_dpp v45, v42 row_ror:8 row_mask:0xf bank_mask:0xf
	v_mov_b32_e32 v46, v193
	v_mov_b32_e32 v47, v193
	s_mov_b32 s10, 0xb0000
	v_mov_b32_dpp v46, v41 row_ror:8 row_mask:0xf bank_mask:0xf
	v_mov_b32_dpp v47, v40 row_ror:8 row_mask:0xf bank_mask:0xf
	v_cndmask_b32_e64 v41, v45, v85, s[40:41]
	v_cndmask_b32_e64 v40, v44, v84, s[40:41]
	v_pk_fma_f32 v[100:101], v[36:37], v[190:191], v[40:41]
	v_add_co_u32_e32 v36, vcc, s10, v210
	s_mov_b32 s10, 0xb8000
	s_nop 0
	v_addc_co_u32_e32 v37, vcc, 0, v211, vcc
	v_add_co_u32_e32 v40, vcc, s10, v210
	v_cndmask_b32_e64 v43, v47, v87, s[40:41]
	v_cndmask_b32_e64 v42, v46, v86, s[40:41]
	v_cndmask_b32_e64 v45, v81, v45, s[40:41]
	v_cndmask_b32_e64 v44, v80, v44, s[40:41]
	v_cndmask_b32_e64 v47, v83, v47, s[40:41]
	v_cndmask_b32_e64 v46, v82, v46, s[40:41]
	v_addc_co_u32_e32 v41, vcc, 0, v211, vcc
	v_pk_fma_f32 v[98:99], v[38:39], v[208:209], v[42:43]
	v_pk_fma_f32 v[102:103], v[34:35], v[188:189], v[46:47]
	v_pk_fma_f32 v[104:105], v[32:33], v[186:187], v[44:45]
	global_load_dwordx4 v[32:35], v[36:37], off nt
	global_load_dwordx4 v[44:47], v[36:37], off offset:512 nt
	s_nop 0
	global_load_dwordx4 v[36:39], v[40:41], off nt
	s_nop 0
	global_load_dwordx4 v[40:43], v[40:41], off offset:512 nt
	v_mul_f32_e32 v80, v89, v89
	v_mul_f32_e32 v81, v91, v91
	v_fmac_f32_e32 v80, v88, v88
	v_fmac_f32_e32 v81, v90, v90
	v_add_f32_e32 v80, v80, v81
	v_mul_f32_e32 v81, v93, v93
	v_mul_f32_e32 v82, v95, v95
	v_add_u32_e32 v96, 0x90, v174
	v_fmac_f32_e32 v81, v92, v92
	v_fmac_f32_e32 v82, v94, v94
	s_waitcnt lgkmcnt(0)
	v_ashrrev_i32_e32 v97, 31, v96
	v_add_f32_e32 v81, v81, v82
	v_lshlrev_b64 v[96:97], 10, v[96:97]
	v_add_f32_e32 v110, v80, v81
	v_cndmask_b32_e64 v80, v91, v95, s[40:41]
	v_cndmask_b32_e64 v81, v90, v94, s[40:41]
	v_cndmask_b32_e64 v82, v89, v93, s[40:41]
	v_cndmask_b32_e64 v83, v88, v92, s[40:41]
	v_mov_b32_e32 v84, v193
	v_mov_b32_e32 v85, v193
	v_mov_b32_e32 v86, v193
	v_mov_b32_e32 v87, v193
	v_lshl_add_u64 v[96:97], v[96:97], 0, v[176:177]
	v_mov_b32_dpp v84, v83 row_ror:8 row_mask:0xf bank_mask:0xf
	v_mov_b32_dpp v85, v82 row_ror:8 row_mask:0xf bank_mask:0xf
	v_mov_b32_dpp v86, v81 row_ror:8 row_mask:0xf bank_mask:0xf
	v_mov_b32_dpp v87, v80 row_ror:8 row_mask:0xf bank_mask:0xf
	v_cndmask_b32_e64 v83, v87, v91, s[40:41]
	v_cndmask_b32_e64 v82, v86, v90, s[40:41]
	v_cndmask_b32_e64 v81, v85, v89, s[40:41]
	v_cndmask_b32_e64 v80, v84, v88, s[40:41]
	v_lshl_add_u64 v[106:107], v[96:97], 2, s[82:83]
	global_store_dwordx4 v[106:107], v[80:83], off nt
	v_cndmask_b32_e64 v87, v95, v87, s[40:41]
	v_cndmask_b32_e64 v86, v94, v86, s[40:41]
	v_add_co_u32_e32 v80, vcc, s23, v106
	v_cndmask_b32_e64 v85, v93, v85, s[40:41]
	v_cndmask_b32_e64 v84, v92, v84, s[40:41]
	v_addc_co_u32_e32 v81, vcc, 0, v107, vcc
	global_store_dwordx4 v[80:81], v[84:87], off nt
	v_pk_mul_f32 v[80:81], v[62:63], v[90:91]
	v_pk_mul_f32 v[82:83], v[60:61], v[88:89]
	v_pk_mul_f32 v[84:85], v[58:59], v[94:95]
	v_pk_mul_f32 v[86:87], v[56:57], v[92:93]
	v_cvt_pk_bf16_f32 v82, v82, v83
	v_cvt_pk_bf16_f32 v81, v80, v81
	v_lshl_add_u64 v[88:89], v[96:97], 1, s[8:9]
	v_cvt_pk_bf16_f32 v83, v86, v87
	v_cvt_pk_bf16_f32 v84, v84, v85
	v_mov_b32_e32 v86, v193
	v_cndmask_b32_e64 v85, v82, v83, s[40:41]
	v_cndmask_b32_e64 v80, v81, v84, s[40:41]
	v_mov_b32_e32 v87, v193
	v_mov_b32_dpp v86, v85 row_ror:8 row_mask:0xf bank_mask:0xf
	v_mov_b32_e32 v85, v193
	v_lshl_add_u64 v[108:109], v[106:107], 0, s[60:61]
	v_mov_b32_e32 v93, v193
	v_mov_b32_dpp v85, v80 row_ror:8 row_mask:0xf bank_mask:0xf
	v_cndmask_b32_e64 v80, v86, v82, s[40:41]
	v_cndmask_b32_e64 v81, v85, v81, s[40:41]
	global_store_dwordx2 v[88:89], v[80:81], off
	v_add_co_u32_e32 v80, vcc, s2, v88
	v_cndmask_b32_e64 v82, v83, v86, s[40:41]
	v_cndmask_b32_e64 v83, v84, v85, s[40:41]
	v_addc_co_u32_e32 v81, vcc, 0, v89, vcc
	global_store_dwordx2 v[80:81], v[82:83], off
	v_mul_f32_e32 v80, v101, v101
	v_mul_f32_e32 v81, v99, v99
	v_fmac_f32_e32 v80, v100, v100
	v_fmac_f32_e32 v81, v98, v98
	v_add_f32_e32 v80, v80, v81
	v_mul_f32_e32 v81, v105, v105
	v_mul_f32_e32 v82, v103, v103
	v_fmac_f32_e32 v81, v104, v104
	v_fmac_f32_e32 v82, v102, v102
;     __device__ __forceinline__ void operator()(const f32x4 (&acc)[2][2][4][2], const pg8::Unit& u, int wr, int wc, int fr_, int fq_) const {
;     ...
;         for (int r = 0; r < 8; ++r) {
;             const int ai = r >> 2, m = r & 3;
;             const int grow = grow0 + ai * 128 + m * 16;
;             const size_t mo0 = (size_t)(mrow0 + ai * 128 + m * 16) * D + mcol, mo1 = mo0 + (size_t)8 * D;
;             f32x4 xo[2][2];
; #pragma unroll
;             for (int bj = 0; bj < 2; ++bj) {
;                 const f32x4 L1 = xi[r % RES_DEPTH][bj * 2], L2 = xi[r % RES_DEPTH][bj * 2 + 1];
;                 const f32x4 T = dpp_ror8(hi ? L1 : L2);
;                 const f32x4 x0 = hi ? T : L1, x1 = hi ? L2 : T;
;                 xo[bj][0] = x0 + gv[bj][0] * acc[ai][bj][m][0]; xo[bj][1] = x1 + gv[bj][1] * acc[ai][bj][m][1];
;             }
;             if (r + RES_DEPTH < 8) {
;                 const int r2 = r + RES_DEPTH;
; #pragma unroll
;                 for (int q = 0; q < 4; ++q) xi[r % RES_DEPTH][q] = *(const f32x4*)(rp0 + (size_t)((r2 >> 2) * 128 + (r2 & 3) * 16 + (q & 1) * 8) * D + (q >> 1) * 128);
;             }
;             float ss = 0.f;
; #pragma unroll
;             for (int bj = 0; bj < 2; ++bj) {
;                 const f32x4 a0 = xo[bj][0], a1 = xo[bj][1];
;                 ss += ((a0[0] * a0[0] + a0[1] * a0[1]) + (a0[2] * a0[2] + a0[3] * a0[3])) + ((a1[0] * a1[0] + a1[1] * a1[1]) + (a1[2] * a1[2] + a1[3] * a1[3]));
;                 const f32x4 T2 = dpp_ror8(hi ? a0 : a1);
;                 const f32x4 d1 = hi ? T2 : a0, d2 = hi ? a1 : T2;
;                 *(f32x4*)(out + mo0 + bj * 128) = d1; *(f32x4*)(out + mo1 + bj * 128) = d2;
;                 if (gm) { const f32x4 o0 = a0 * mv[bj][0], o1 = a1 * mv[bj][1];
;                     u32x2 w0, w1; w0.x = cvt_pk_bf16(o0[0], o0[1]); w0.y = cvt_pk_bf16(o0[2], o0[3]); w1.x = cvt_pk_bf16(o1[0], o1[1]); w1.y = cvt_pk_bf16(o1[2], o1[3]);
;                     const u32x2 T3 = dpp_ror8(hi ? w0 : w1);
;                     const u32x2 e1 = hi ? T3 : w0, e2 = hi ? w1 : T3;
;                     *(u32x2*)(xg + mo0 + bj * 128) = e1; *(u32x2*)(xg + mo1 + bj * 128) = e2; }
;             }
;             ss += __shfl_xor(ss, 16); ss += __shfl_xor(ss, 32);
;             if (fq == 0) rss[(size_t)grow * 16 + u.pn * 4 + wc] = ss;
	v_add_f32_e32 v81, v81, v82
	v_add_f32_e32 v80, v80, v81
	v_add_f32_e32 v92, v110, v80
	v_cndmask_b32_e64 v80, v99, v103, s[40:41]
	v_cndmask_b32_e64 v81, v98, v102, s[40:41]
	v_cndmask_b32_e64 v82, v101, v105, s[40:41]
	v_cndmask_b32_e64 v83, v100, v104, s[40:41]
	v_mov_b32_e32 v84, v193
	v_mov_b32_e32 v85, v193
	v_mov_b32_e32 v86, v193
	v_mov_b32_dpp v84, v83 row_ror:8 row_mask:0xf bank_mask:0xf
	v_mov_b32_dpp v85, v82 row_ror:8 row_mask:0xf bank_mask:0xf
	v_mov_b32_dpp v86, v81 row_ror:8 row_mask:0xf bank_mask:0xf
	v_mov_b32_dpp v87, v80 row_ror:8 row_mask:0xf bank_mask:0xf
	v_cndmask_b32_e64 v83, v87, v99, s[40:41]
	v_cndmask_b32_e64 v82, v86, v98, s[40:41]
	v_cndmask_b32_e64 v81, v85, v101, s[40:41]
	v_cndmask_b32_e64 v80, v84, v100, s[40:41]
	v_cndmask_b32_e64 v87, v103, v87, s[40:41]
	v_cndmask_b32_e64 v86, v102, v86, s[40:41]
	v_cndmask_b32_e64 v85, v105, v85, s[40:41]
	v_cndmask_b32_e64 v84, v104, v84, s[40:41]
	global_store_dwordx4 v[106:107], v[80:83], off offset:512 nt
	global_store_dwordx4 v[108:109], v[84:87], off offset:512 nt
	s_mov_b64 s[26:27], 0x4000
	v_pk_mul_f32 v[80:81], v[54:55], v[98:99]
	v_pk_mul_f32 v[82:83], v[52:53], v[100:101]
	v_pk_mul_f32 v[86:87], v[48:49], v[104:105]
	v_cvt_pk_bf16_f32 v82, v82, v83
	v_cvt_pk_bf16_f32 v80, v80, v81
	v_pk_mul_f32 v[84:85], v[50:51], v[102:103]
	v_cvt_pk_bf16_f32 v86, v86, v87
	ds_bpermute_b32 v87, v175, v92
	v_cvt_pk_bf16_f32 v85, v84, v85
	v_cndmask_b32_e64 v83, v82, v86, s[40:41]
	v_cndmask_b32_e64 v81, v80, v85, s[40:41]
	v_mov_b32_e32 v84, v193
	v_lshl_add_u64 v[90:91], v[88:89], 0, s[26:27]
	v_mov_b32_dpp v93, v81 row_ror:8 row_mask:0xf bank_mask:0xf
	v_mov_b32_dpp v84, v83 row_ror:8 row_mask:0xf bank_mask:0xf
	v_cndmask_b32_e64 v83, v93, v80, s[40:41]
	s_waitcnt lgkmcnt(0)
	v_add_f32_e32 v80, v92, v87
	ds_bpermute_b32 v81, v197, v80
	v_cndmask_b32_e64 v82, v84, v82, s[40:41]
	v_cndmask_b32_e64 v84, v86, v84, s[40:41]
	v_cndmask_b32_e64 v85, v85, v93, s[40:41]
	global_store_dwordx2 v[88:89], v[82:83], off offset:256
	global_store_dwordx2 v[90:91], v[84:85], off offset:256
	s_and_saveexec_b64 s[26:27], s[38:39]
	s_cbranch_execz .LBB0_165
	v_lshlrev_b64 v[82:83], 6, v[172:173]
	v_lshl_add_u64 v[82:83], s[96:97], 0, v[82:83]
	v_lshl_add_u64 v[82:83], s[74:75], 2, v[82:83]
	s_lshl_b32 s10, s17, 2
	v_lshl_add_u64 v[82:83], v[82:83], 0, s[10:11]
	s_waitcnt lgkmcnt(0)
	v_add_f32_e32 v84, v80, v81
	v_add_co_u32_e32 v80, vcc, 0x2000, v82
	s_nop 1
	v_addc_co_u32_e32 v81, vcc, 0, v83, vcc
	global_store_dword v[80:81], v84, off offset:1024
.LBB0_165:
	s_or_b64 exec, exec, s[26:27]
	s_waitcnt vmcnt(21)
	v_cndmask_b32_e64 v85, v64, v68, s[40:41]
	v_mov_b32_e32 v86, v193
	v_cndmask_b32_e64 v84, v65, v69, s[40:41]
	s_waitcnt vmcnt(20)
	v_cndmask_b32_e64 v89, v76, v72, s[40:41]
	v_mov_b32_dpp v86, v85 row_ror:8 row_mask:0xf bank_mask:0xf
	v_mov_b32_e32 v85, v193
	v_mov_b32_e32 v90, v193
	v_cndmask_b32_e64 v83, v66, v70, s[40:41]
	v_mov_b32_dpp v85, v84 row_ror:8 row_mask:0xf bank_mask:0xf
	v_mov_b32_e32 v84, v193
	v_cndmask_b32_e64 v88, v77, v73, s[40:41]
	v_mov_b32_dpp v90, v89 row_ror:8 row_mask:0xf bank_mask:0xf
	v_mov_b32_e32 v89, v193
	v_cndmask_b32_e64 v82, v67, v71, s[40:41]
	v_mov_b32_dpp v84, v83 row_ror:8 row_mask:0xf bank_mask:0xf
	v_mov_b32_e32 v83, v193
	v_cndmask_b32_e64 v87, v78, v74, s[40:41]
	v_mov_b32_dpp v89, v88 row_ror:8 row_mask:0xf bank_mask:0xf
	v_mov_b32_e32 v88, v193
	v_mov_b32_dpp v83, v82 row_ror:8 row_mask:0xf bank_mask:0xf
	v_cndmask_b32_e64 v82, v79, v75, s[40:41]
	v_mov_b32_dpp v88, v87 row_ror:8 row_mask:0xf bank_mask:0xf
	v_mov_b32_e32 v87, v193
	v_cndmask_b32_e64 v73, v73, v89, s[40:41]
	v_cndmask_b32_e64 v72, v72, v90, s[40:41]
	v_mov_b32_dpp v87, v82 row_ror:8 row_mask:0xf bank_mask:0xf
	v_cndmask_b32_e64 v75, v75, v87, s[40:41]
	v_cndmask_b32_e64 v74, v74, v88, s[40:41]
	v_pk_fma_f32 v[74:75], v[18:19], v[188:189], v[74:75]
	v_pk_fma_f32 v[72:73], v[16:17], v[186:187], v[72:73]
	v_cndmask_b32_e64 v17, v71, v83, s[40:41]
	v_cndmask_b32_e64 v16, v70, v84, s[40:41]
	v_cndmask_b32_e64 v19, v69, v85, s[40:41]
	v_cndmask_b32_e64 v18, v68, v86, s[40:41]
	v_pk_fma_f32 v[28:29], v[28:29], v[184:185], v[18:19]
	v_pk_fma_f32 v[30:31], v[30:31], v[182:183], v[16:17]
	v_cndmask_b32_e64 v17, v83, v67, s[40:41]
	v_cndmask_b32_e64 v16, v84, v66, s[40:41]
	v_cndmask_b32_e64 v19, v85, v65, s[40:41]
	v_cndmask_b32_e64 v18, v86, v64, s[40:41]
	v_pk_fma_f32 v[24:25], v[24:25], v[180:181], v[18:19]
	v_pk_fma_f32 v[26:27], v[26:27], v[178:179], v[16:17]
	v_mul_f32_e32 v16, v25, v25
	v_mul_f32_e32 v17, v27, v27
	v_fmac_f32_e32 v16, v24, v24
	v_fmac_f32_e32 v17, v26, v26
	v_add_f32_e32 v16, v16, v17
	v_mul_f32_e32 v17, v29, v29
	v_mul_f32_e32 v18, v31, v31
	v_add_u32_e32 v80, 0xa0, v174
	v_fmac_f32_e32 v17, v28, v28
	v_fmac_f32_e32 v18, v30, v30
	s_waitcnt lgkmcnt(0)
;     __device__ __forceinline__ void operator()(const f32x4 (&acc)[2][2][4][2], const pg8::Unit& u, int wr, int wc, int fr_, int fq_) const {
;     ...
;         for (int r = 0; r < 8; ++r) {
;             const int ai = r >> 2, m = r & 3;
;             const int grow = grow0 + ai * 128 + m * 16;
;             const size_t mo0 = (size_t)(mrow0 + ai * 128 + m * 16) * D + mcol, mo1 = mo0 + (size_t)8 * D;
;             f32x4 xo[2][2];
; #pragma unroll
;             for (int bj = 0; bj < 2; ++bj) {
;                 const f32x4 L1 = xi[r % RES_DEPTH][bj * 2], L2 = xi[r % RES_DEPTH][bj * 2 + 1];
;                 const f32x4 T = dpp_ror8(hi ? L1 : L2);
;                 const f32x4 x0 = hi ? T : L1, x1 = hi ? L2 : T;
;                 xo[bj][0] = x0 + gv[bj][0] * acc[ai][bj][m][0]; xo[bj][1] = x1 + gv[bj][1] * acc[ai][bj][m][1];
;             }
;             if (r + RES_DEPTH < 8) {
;                 const int r2 = r + RES_DEPTH;
; #pragma unroll
;                 for (int q = 0; q < 4; ++q) xi[r % RES_DEPTH][q] = *(const f32x4*)(rp0 + (size_t)((r2 >> 2) * 128 + (r2 & 3) * 16 + (q & 1) * 8) * D + (q >> 1) * 128);
;             }
;             float ss = 0.f;
; #pragma unroll
;             for (int bj = 0; bj < 2; ++bj) {
;                 const f32x4 a0 = xo[bj][0], a1 = xo[bj][1];
;                 ss += ((a0[0] * a0[0] + a0[1] * a0[1]) + (a0[2] * a0[2] + a0[3] * a0[3])) + ((a1[0] * a1[0] + a1[1] * a1[1]) + (a1[2] * a1[2] + a1[3] * a1[3]));
;                 const f32x4 T2 = dpp_ror8(hi ? a0 : a1);
;                 const f32x4 d1 = hi ? T2 : a0, d2 = hi ? a1 : T2;
;                 *(f32x4*)(out + mo0 + bj * 128) = d1; *(f32x4*)(out + mo1 + bj * 128) = d2;
;                 if (gm) { const f32x4 o0 = a0 * mv[bj][0], o1 = a1 * mv[bj][1];
;                     u32x2 w0, w1; w0.x = cvt_pk_bf16(o0[0], o0[1]); w0.y = cvt_pk_bf16(o0[2], o0[3]); w1.x = cvt_pk_bf16(o1[0], o1[1]); w1.y = cvt_pk_bf16(o1[2], o1[3]);
;                     const u32x2 T3 = dpp_ror8(hi ? w0 : w1);
;                     const u32x2 e1 = hi ? T3 : w0, e2 = hi ? w1 : T3;
;                     *(u32x2*)(xg + mo0 + bj * 128) = e1; *(u32x2*)(xg + mo1 + bj * 128) = e2; }
;             }
;             ss += __shfl_xor(ss, 16); ss += __shfl_xor(ss, 32);
;             if (fq == 0) rss[(size_t)grow * 16 + u.pn * 4 + wc] = ss;
	v_ashrrev_i32_e32 v81, 31, v80
	v_cndmask_b32_e64 v77, v89, v77, s[40:41]
	v_cndmask_b32_e64 v76, v90, v76, s[40:41]
	v_cndmask_b32_e64 v79, v87, v79, s[40:41]
	v_cndmask_b32_e64 v78, v88, v78, s[40:41]
	v_add_f32_e32 v17, v17, v18
	v_lshlrev_b64 v[80:81], 10, v[80:81]
	v_pk_fma_f32 v[78:79], v[22:23], v[208:209], v[78:79]
	v_pk_fma_f32 v[76:77], v[20:21], v[190:191], v[76:77]
	v_add_f32_e32 v68, v17, v16
	v_cndmask_b32_e64 v16, v27, v31, s[40:41]
	v_cndmask_b32_e64 v17, v26, v30, s[40:41]
	v_cndmask_b32_e64 v18, v25, v29, s[40:41]
	v_cndmask_b32_e64 v19, v24, v28, s[40:41]
	v_mov_b32_e32 v20, v193
	v_mov_b32_e32 v21, v193
	v_mov_b32_e32 v22, v193
	v_mov_b32_e32 v23, v193
	v_lshl_add_u64 v[80:81], v[80:81], 0, v[176:177]
	v_mov_b32_dpp v20, v19 row_ror:8 row_mask:0xf bank_mask:0xf
	v_mov_b32_dpp v21, v18 row_ror:8 row_mask:0xf bank_mask:0xf
	v_mov_b32_dpp v22, v17 row_ror:8 row_mask:0xf bank_mask:0xf
	v_mov_b32_dpp v23, v16 row_ror:8 row_mask:0xf bank_mask:0xf
	v_cndmask_b32_e64 v19, v23, v27, s[40:41]
	v_cndmask_b32_e64 v18, v22, v26, s[40:41]
	v_cndmask_b32_e64 v17, v21, v25, s[40:41]
	v_cndmask_b32_e64 v16, v20, v24, s[40:41]
	v_lshl_add_u64 v[64:65], v[80:81], 2, s[82:83]
	global_store_dwordx4 v[64:65], v[16:19], off nt
	v_cndmask_b32_e64 v23, v31, v23, s[40:41]
	v_cndmask_b32_e64 v22, v30, v22, s[40:41]
	v_add_co_u32_e32 v16, vcc, s23, v64
	v_cndmask_b32_e64 v21, v29, v21, s[40:41]
	v_cndmask_b32_e64 v20, v28, v20, s[40:41]
	v_addc_co_u32_e32 v17, vcc, 0, v65, vcc
	global_store_dwordx4 v[16:17], v[20:23], off nt
	v_pk_mul_f32 v[16:17], v[62:63], v[26:27]
	v_pk_mul_f32 v[18:19], v[60:61], v[24:25]
	v_pk_mul_f32 v[20:21], v[58:59], v[30:31]
	v_pk_mul_f32 v[22:23], v[56:57], v[28:29]
	v_cvt_pk_bf16_f32 v18, v18, v19
	v_cvt_pk_bf16_f32 v17, v16, v17
	v_lshl_add_u64 v[24:25], v[80:81], 1, s[8:9]
	v_cvt_pk_bf16_f32 v19, v22, v23
	v_cvt_pk_bf16_f32 v20, v20, v21
	v_mov_b32_e32 v22, v193
	v_cndmask_b32_e64 v21, v18, v19, s[40:41]
	v_cndmask_b32_e64 v16, v17, v20, s[40:41]
	v_mov_b32_e32 v23, v193
	v_mov_b32_dpp v22, v21 row_ror:8 row_mask:0xf bank_mask:0xf
	v_mov_b32_e32 v21, v193
	v_lshl_add_u64 v[66:67], v[64:65], 0, s[60:61]
	v_mov_b32_e32 v29, v193
	v_mov_b32_dpp v21, v16 row_ror:8 row_mask:0xf bank_mask:0xf
	v_cndmask_b32_e64 v16, v22, v18, s[40:41]
	v_cndmask_b32_e64 v17, v21, v17, s[40:41]
	global_store_dwordx2 v[24:25], v[16:17], off
	v_add_co_u32_e32 v16, vcc, s2, v24
	v_cndmask_b32_e64 v18, v19, v22, s[40:41]
	v_cndmask_b32_e64 v19, v20, v21, s[40:41]
	v_addc_co_u32_e32 v17, vcc, 0, v25, vcc
	global_store_dwordx2 v[16:17], v[18:19], off
	v_mul_f32_e32 v16, v77, v77
	v_mul_f32_e32 v17, v79, v79
	v_fmac_f32_e32 v16, v76, v76
	v_fmac_f32_e32 v17, v78, v78
	v_add_f32_e32 v16, v16, v17
	v_mul_f32_e32 v17, v73, v73
	v_mul_f32_e32 v18, v75, v75
	v_fmac_f32_e32 v17, v72, v72
	v_fmac_f32_e32 v18, v74, v74
	v_add_f32_e32 v17, v17, v18
	v_add_f32_e32 v16, v16, v17
	v_add_f32_e32 v28, v68, v16
	v_cndmask_b32_e64 v16, v79, v75, s[40:41]
	v_cndmask_b32_e64 v17, v78, v74, s[40:41]
	v_cndmask_b32_e64 v18, v77, v73, s[40:41]
	v_cndmask_b32_e64 v19, v76, v72, s[40:41]
	v_mov_b32_e32 v20, v193
	v_mov_b32_e32 v21, v193
	v_mov_b32_e32 v22, v193
	v_mov_b32_dpp v20, v19 row_ror:8 row_mask:0xf bank_mask:0xf
	v_mov_b32_dpp v21, v18 row_ror:8 row_mask:0xf bank_mask:0xf
	v_mov_b32_dpp v22, v17 row_ror:8 row_mask:0xf bank_mask:0xf
	v_mov_b32_dpp v23, v16 row_ror:8 row_mask:0xf bank_mask:0xf
	v_cndmask_b32_e64 v19, v23, v79, s[40:41]
	v_cndmask_b32_e64 v18, v22, v78, s[40:41]
	v_cndmask_b32_e64 v17, v21, v77, s[40:41]
	v_cndmask_b32_e64 v16, v20, v76, s[40:41]
	v_cndmask_b32_e64 v23, v75, v23, s[40:41]
	v_cndmask_b32_e64 v22, v74, v22, s[40:41]
	v_cndmask_b32_e64 v21, v73, v21, s[40:41]
	v_cndmask_b32_e64 v20, v72, v20, s[40:41]
	global_store_dwordx4 v[64:65], v[16:19], off offset:512 nt
	global_store_dwordx4 v[66:67], v[20:23], off offset:512 nt
	s_mov_b64 s[26:27], 0x4000
	v_pk_mul_f32 v[16:17], v[54:55], v[78:79]
	v_pk_mul_f32 v[18:19], v[52:53], v[76:77]
	v_pk_mul_f32 v[22:23], v[48:49], v[72:73]
	v_cvt_pk_bf16_f32 v18, v18, v19
	v_cvt_pk_bf16_f32 v16, v16, v17
	v_pk_mul_f32 v[20:21], v[50:51], v[74:75]
	v_cvt_pk_bf16_f32 v22, v22, v23
	ds_bpermute_b32 v23, v175, v28
	v_cvt_pk_bf16_f32 v21, v20, v21
	v_cndmask_b32_e64 v19, v18, v22, s[40:41]
	v_cndmask_b32_e64 v17, v16, v21, s[40:41]
	v_mov_b32_e32 v20, v193
	v_lshl_add_u64 v[26:27], v[24:25], 0, s[26:27]
	v_mov_b32_dpp v29, v17 row_ror:8 row_mask:0xf bank_mask:0xf
	v_mov_b32_dpp v20, v19 row_ror:8 row_mask:0xf bank_mask:0xf
	v_cndmask_b32_e64 v19, v29, v16, s[40:41]
	s_waitcnt lgkmcnt(0)
	v_add_f32_e32 v16, v28, v23
	ds_bpermute_b32 v17, v197, v16
	v_cndmask_b32_e64 v18, v20, v18, s[40:41]
	v_cndmask_b32_e64 v20, v22, v20, s[40:41]
	v_cndmask_b32_e64 v21, v21, v29, s[40:41]
	global_store_dwordx2 v[24:25], v[18:19], off offset:256
	global_store_dwordx2 v[26:27], v[20:21], off offset:256
	s_and_saveexec_b64 s[26:27], s[38:39]
	s_cbranch_execz .LBB0_167
	v_lshlrev_b64 v[18:19], 6, v[172:173]
	v_lshl_add_u64 v[18:19], s[96:97], 0, v[18:19]
	v_lshl_add_u64 v[18:19], s[74:75], 2, v[18:19]
	s_lshl_b32 s10, s17, 2
	v_lshl_add_u64 v[18:19], v[18:19], 0, s[10:11]
	s_waitcnt lgkmcnt(0)
	v_add_f32_e32 v20, v16, v17
	v_add_co_u32_e32 v16, vcc, 0x2000, v18
	s_nop 1
	v_addc_co_u32_e32 v17, vcc, 0, v19, vcc
	global_store_dword v[16:17], v20, off offset:2048
;     __device__ __forceinline__ void operator()(const f32x4 (&acc)[2][2][4][2], const pg8::Unit& u, int wr, int wc, int fr_, int fq_) const {
;     ...
;         for (int r = 0; r < 8; ++r) {
;             const int ai = r >> 2, m = r & 3;
;             const int grow = grow0 + ai * 128 + m * 16;
;             const size_t mo0 = (size_t)(mrow0 + ai * 128 + m * 16) * D + mcol, mo1 = mo0 + (size_t)8 * D;
;             f32x4 xo[2][2];
; #pragma unroll
;             for (int bj = 0; bj < 2; ++bj) {
;                 const f32x4 L1 = xi[r % RES_DEPTH][bj * 2], L2 = xi[r % RES_DEPTH][bj * 2 + 1];
;                 const f32x4 T = dpp_ror8(hi ? L1 : L2);
;                 const f32x4 x0 = hi ? T : L1, x1 = hi ? L2 : T;
;                 xo[bj][0] = x0 + gv[bj][0] * acc[ai][bj][m][0]; xo[bj][1] = x1 + gv[bj][1] * acc[ai][bj][m][1];
;             }
;             if (r + RES_DEPTH < 8) {
;                 const int r2 = r + RES_DEPTH;
; #pragma unroll
;                 for (int q = 0; q < 4; ++q) xi[r % RES_DEPTH][q] = *(const f32x4*)(rp0 + (size_t)((r2 >> 2) * 128 + (r2 & 3) * 16 + (q & 1) * 8) * D + (q >> 1) * 128);
;             }
;             float ss = 0.f;
; #pragma unroll
;             for (int bj = 0; bj < 2; ++bj) {
;                 const f32x4 a0 = xo[bj][0], a1 = xo[bj][1];
;                 ss += ((a0[0] * a0[0] + a0[1] * a0[1]) + (a0[2] * a0[2] + a0[3] * a0[3])) + ((a1[0] * a1[0] + a1[1] * a1[1]) + (a1[2] * a1[2] + a1[3] * a1[3]));
;                 const f32x4 T2 = dpp_ror8(hi ? a0 : a1);
;                 const f32x4 d1 = hi ? T2 : a0, d2 = hi ? a1 : T2;
;                 *(f32x4*)(out + mo0 + bj * 128) = d1; *(f32x4*)(out + mo1 + bj * 128) = d2;
;                 if (gm) { const f32x4 o0 = a0 * mv[bj][0], o1 = a1 * mv[bj][1];
;                     u32x2 w0, w1; w0.x = cvt_pk_bf16(o0[0], o0[1]); w0.y = cvt_pk_bf16(o0[2], o0[3]); w1.x = cvt_pk_bf16(o1[0], o1[1]); w1.y = cvt_pk_bf16(o1[2], o1[3]);
;                     const u32x2 T3 = dpp_ror8(hi ? w0 : w1);
;                     const u32x2 e1 = hi ? T3 : w0, e2 = hi ? w1 : T3;
;                     *(u32x2*)(xg + mo0 + bj * 128) = e1; *(u32x2*)(xg + mo1 + bj * 128) = e2; }
;             }
;             ss += __shfl_xor(ss, 16); ss += __shfl_xor(ss, 32);
;             if (fq == 0) rss[(size_t)grow * 16 + u.pn * 4 + wc] = ss;
.LBB0_167:
	s_or_b64 exec, exec, s[26:27]
	s_waitcnt vmcnt(17)
	v_cndmask_b32_e64 v18, v35, v39, s[40:41]
	v_cndmask_b32_e64 v19, v34, v38, s[40:41]
	v_cndmask_b32_e64 v20, v33, v37, s[40:41]
	v_cndmask_b32_e64 v21, v32, v36, s[40:41]
	v_mov_b32_e32 v26, v193
	v_mov_b32_e32 v27, v193
	v_mov_b32_e32 v28, v193
	v_mov_b32_e32 v29, v193
	v_mov_b32_dpp v26, v21 row_ror:8 row_mask:0xf bank_mask:0xf
	v_mov_b32_dpp v27, v20 row_ror:8 row_mask:0xf bank_mask:0xf
	v_mov_b32_dpp v28, v19 row_ror:8 row_mask:0xf bank_mask:0xf
	v_mov_b32_dpp v29, v18 row_ror:8 row_mask:0xf bank_mask:0xf
	s_waitcnt vmcnt(16)
	v_cndmask_b32_e64 v18, v47, v43, s[40:41]
	v_cndmask_b32_e64 v19, v46, v42, s[40:41]
	v_cndmask_b32_e64 v20, v45, v41, s[40:41]
	v_cndmask_b32_e64 v21, v44, v40, s[40:41]
	v_mov_b32_e32 v22, v193
	v_mov_b32_e32 v23, v193
	v_mov_b32_e32 v24, v193
	v_mov_b32_e32 v25, v193
	v_mov_b32_dpp v22, v21 row_ror:8 row_mask:0xf bank_mask:0xf
	v_mov_b32_dpp v23, v20 row_ror:8 row_mask:0xf bank_mask:0xf
	v_mov_b32_dpp v24, v19 row_ror:8 row_mask:0xf bank_mask:0xf
	v_mov_b32_dpp v25, v18 row_ror:8 row_mask:0xf bank_mask:0xf
	v_cndmask_b32_e64 v19, v23, v45, s[40:41]
	v_cndmask_b32_e64 v18, v22, v44, s[40:41]
	v_cndmask_b32_e64 v21, v25, v47, s[40:41]
	v_cndmask_b32_e64 v20, v24, v46, s[40:41]
	v_cndmask_b32_e64 v23, v41, v23, s[40:41]
	v_cndmask_b32_e64 v22, v40, v22, s[40:41]
	v_cndmask_b32_e64 v25, v43, v25, s[40:41]
	v_cndmask_b32_e64 v24, v42, v24, s[40:41]
	v_pk_fma_f32 v[10:11], v[10:11], v[208:209], v[20:21]
	v_pk_fma_f32 v[8:9], v[8:9], v[190:191], v[18:19]
	v_pk_fma_f32 v[18:19], v[2:3], v[188:189], v[24:25]
	v_pk_fma_f32 v[20:21], v[0:1], v[186:187], v[22:23]
	v_cndmask_b32_e64 v1, v39, v29, s[40:41]
	v_cndmask_b32_e64 v0, v38, v28, s[40:41]
	v_cndmask_b32_e64 v3, v37, v27, s[40:41]
	v_cndmask_b32_e64 v2, v36, v26, s[40:41]
	v_pk_fma_f32 v[12:13], v[12:13], v[184:185], v[2:3]
	v_pk_fma_f32 v[14:15], v[14:15], v[182:183], v[0:1]
	v_cndmask_b32_e64 v1, v29, v35, s[40:41]
	v_cndmask_b32_e64 v0, v28, v34, s[40:41]
	v_cndmask_b32_e64 v3, v27, v33, s[40:41]
	v_cndmask_b32_e64 v2, v26, v32, s[40:41]
	v_pk_fma_f32 v[22:23], v[4:5], v[180:181], v[2:3]
	v_pk_fma_f32 v[24:25], v[6:7], v[178:179], v[0:1]
	v_mul_f32_e32 v0, v23, v23
	v_mul_f32_e32 v1, v25, v25
	v_fmac_f32_e32 v0, v22, v22
	v_fmac_f32_e32 v1, v24, v24
	v_add_f32_e32 v0, v0, v1
	v_mul_f32_e32 v1, v13, v13
	v_mul_f32_e32 v2, v15, v15
	v_add_u32_e32 v16, 0xb0, v174
	v_fmac_f32_e32 v1, v12, v12
	v_fmac_f32_e32 v2, v14, v14
	s_waitcnt lgkmcnt(0)
	v_ashrrev_i32_e32 v17, 31, v16
	v_add_f32_e32 v1, v1, v2
	v_lshlrev_b64 v[16:17], 10, v[16:17]
	v_add_f32_e32 v30, v1, v0
	v_cndmask_b32_e64 v0, v25, v15, s[40:41]
	v_cndmask_b32_e64 v1, v24, v14, s[40:41]
	v_cndmask_b32_e64 v2, v23, v13, s[40:41]
	v_cndmask_b32_e64 v3, v22, v12, s[40:41]
	v_mov_b32_e32 v4, v193
	v_mov_b32_e32 v5, v193
	v_mov_b32_e32 v6, v193
	v_mov_b32_e32 v7, v193
	v_lshl_add_u64 v[16:17], v[16:17], 0, v[176:177]
	v_mov_b32_dpp v4, v3 row_ror:8 row_mask:0xf bank_mask:0xf
	v_mov_b32_dpp v5, v2 row_ror:8 row_mask:0xf bank_mask:0xf
	v_mov_b32_dpp v6, v1 row_ror:8 row_mask:0xf bank_mask:0xf
	v_mov_b32_dpp v7, v0 row_ror:8 row_mask:0xf bank_mask:0xf
	v_cndmask_b32_e64 v3, v7, v25, s[40:41]
	v_cndmask_b32_e64 v2, v6, v24, s[40:41]
	v_cndmask_b32_e64 v1, v5, v23, s[40:41]
	v_cndmask_b32_e64 v0, v4, v22, s[40:41]
	v_lshl_add_u64 v[26:27], v[16:17], 2, s[82:83]
	global_store_dwordx4 v[26:27], v[0:3], off nt
	v_cndmask_b32_e64 v7, v15, v7, s[40:41]
	v_cndmask_b32_e64 v6, v14, v6, s[40:41]
	v_add_co_u32_e32 v0, vcc, s23, v26
	v_cndmask_b32_e64 v5, v13, v5, s[40:41]
	v_cndmask_b32_e64 v4, v12, v4, s[40:41]
	v_addc_co_u32_e32 v1, vcc, 0, v27, vcc
	global_store_dwordx4 v[0:1], v[4:7], off nt
	v_pk_mul_f32 v[0:1], v[62:63], v[24:25]
	v_pk_mul_f32 v[2:3], v[60:61], v[22:23]
	v_pk_mul_f32 v[4:5], v[58:59], v[14:15]
	v_pk_mul_f32 v[6:7], v[56:57], v[12:13]
	v_cvt_pk_bf16_f32 v2, v2, v3
	v_cvt_pk_bf16_f32 v1, v0, v1
	v_lshl_add_u64 v[12:13], v[16:17], 1, s[8:9]
	v_cvt_pk_bf16_f32 v3, v6, v7
	v_cvt_pk_bf16_f32 v4, v4, v5
	v_mov_b32_e32 v6, v193
	v_cndmask_b32_e64 v5, v2, v3, s[40:41]
	v_cndmask_b32_e64 v0, v1, v4, s[40:41]
	v_mov_b32_e32 v7, v193
	v_mov_b32_dpp v6, v5 row_ror:8 row_mask:0xf bank_mask:0xf
	v_mov_b32_e32 v5, v193
	v_lshl_add_u64 v[28:29], v[26:27], 0, s[60:61]
	s_mov_b64 s[26:27], 0x4000
	v_mov_b32_dpp v5, v0 row_ror:8 row_mask:0xf bank_mask:0xf
	v_cndmask_b32_e64 v0, v6, v2, s[40:41]
	v_cndmask_b32_e64 v1, v5, v1, s[40:41]
	global_store_dwordx2 v[12:13], v[0:1], off
	v_add_co_u32_e32 v0, vcc, s2, v12
	v_cndmask_b32_e64 v2, v3, v6, s[40:41]
	v_cndmask_b32_e64 v3, v4, v5, s[40:41]
	v_addc_co_u32_e32 v1, vcc, 0, v13, vcc
	global_store_dwordx2 v[0:1], v[2:3], off
	v_mul_f32_e32 v0, v9, v9
	v_mul_f32_e32 v1, v11, v11
	v_fmac_f32_e32 v0, v8, v8
	v_fmac_f32_e32 v1, v10, v10
	v_add_f32_e32 v0, v0, v1
	v_mul_f32_e32 v1, v21, v21
	v_mul_f32_e32 v2, v19, v19
	v_fmac_f32_e32 v1, v20, v20
	v_fmac_f32_e32 v2, v18, v18
	v_add_f32_e32 v1, v1, v2
	v_add_f32_e32 v0, v0, v1
	v_add_f32_e32 v16, v30, v0
	v_cndmask_b32_e64 v0, v11, v19, s[40:41]
	v_cndmask_b32_e64 v1, v10, v18, s[40:41]
	v_cndmask_b32_e64 v2, v9, v21, s[40:41]
	v_cndmask_b32_e64 v3, v8, v20, s[40:41]
	v_mov_b32_e32 v4, v193
	v_mov_b32_e32 v5, v193
	v_mov_b32_e32 v6, v193
	v_mov_b32_dpp v4, v3 row_ror:8 row_mask:0xf bank_mask:0xf
	v_mov_b32_dpp v5, v2 row_ror:8 row_mask:0xf bank_mask:0xf
	v_mov_b32_dpp v6, v1 row_ror:8 row_mask:0xf bank_mask:0xf
	v_mov_b32_dpp v7, v0 row_ror:8 row_mask:0xf bank_mask:0xf
	v_cndmask_b32_e64 v3, v7, v11, s[40:41]
	v_cndmask_b32_e64 v2, v6, v10, s[40:41]
	v_cndmask_b32_e64 v1, v5, v9, s[40:41]
	v_cndmask_b32_e64 v0, v4, v8, s[40:41]
	v_cndmask_b32_e64 v7, v19, v7, s[40:41]
	v_cndmask_b32_e64 v6, v18, v6, s[40:41]
	v_cndmask_b32_e64 v5, v21, v5, s[40:41]
	v_cndmask_b32_e64 v4, v20, v4, s[40:41]
	global_store_dwordx4 v[26:27], v[0:3], off offset:512 nt
	global_store_dwordx4 v[28:29], v[4:7], off offset:512 nt
	v_lshl_add_u64 v[14:15], v[12:13], 0, s[26:27]
	v_pk_mul_f32 v[0:1], v[54:55], v[10:11]
	v_pk_mul_f32 v[2:3], v[52:53], v[8:9]
	v_pk_mul_f32 v[6:7], v[48:49], v[20:21]
	v_cvt_pk_bf16_f32 v2, v2, v3
	v_cvt_pk_bf16_f32 v0, v0, v1
	v_pk_mul_f32 v[4:5], v[50:51], v[18:19]
	v_cvt_pk_bf16_f32 v6, v6, v7
	ds_bpermute_b32 v7, v175, v16
	v_cvt_pk_bf16_f32 v5, v4, v5
	v_mov_b32_e32 v8, v193
	v_cndmask_b32_e64 v1, v0, v5, s[40:41]
	v_cndmask_b32_e64 v3, v2, v6, s[40:41]
	v_mov_b32_e32 v4, v193
	v_mov_b32_dpp v8, v1 row_ror:8 row_mask:0xf bank_mask:0xf
	v_cndmask_b32_e64 v5, v5, v8, s[40:41]
	v_mov_b32_dpp v4, v3 row_ror:8 row_mask:0xf bank_mask:0xf
	v_cndmask_b32_e64 v3, v8, v0, s[40:41]
	s_waitcnt lgkmcnt(0)
	v_add_f32_e32 v0, v16, v7
	ds_bpermute_b32 v1, v197, v0
	v_cndmask_b32_e64 v2, v4, v2, s[40:41]
	v_cndmask_b32_e64 v4, v6, v4, s[40:41]
	global_store_dwordx2 v[12:13], v[2:3], off offset:256
	global_store_dwordx2 v[14:15], v[4:5], off offset:256
	s_and_saveexec_b64 s[26:27], s[38:39]
	s_cbranch_execz .LBB0_169
;     __device__ __forceinline__ void operator()(const f32x4 (&acc)[2][2][4][2], const pg8::Unit& u, int wr, int wc, int fr_, int fq_) const {
;     ...
;             ss += __shfl_xor(ss, 16); ss += __shfl_xor(ss, 32);
;             if (fq == 0) rss[(size_t)grow * 16 + u.pn * 4 + wc] = ss;
	v_lshlrev_b64 v[2:3], 6, v[172:173]
	v_lshl_add_u64 v[2:3], s[96:97], 0, v[2:3]
	v_lshl_add_u64 v[2:3], s[74:75], 2, v[2:3]
	s_lshl_b32 s10, s17, 2
	v_lshl_add_u64 v[2:3], v[2:3], 0, s[10:11]
	s_waitcnt lgkmcnt(0)
	v_add_f32_e32 v4, v0, v1
	v_add_co_u32_e32 v0, vcc, 0x2000, v2
	s_nop 1
	v_addc_co_u32_e32 v1, vcc, 0, v3, vcc
	global_store_dword v[0:1], v4, off offset:3072

;     __device__ __forceinline__ void operator()(const f32x4 (&acc)[2][2][4][2], const pg8::Unit& u, int wr, int wc, int fr_, int fq_) const {
;         const int lane_ = pg8::lane_id_v(); const int fr = lane_ & 15, fq = lane_ >> 4;
;         const bool hi = (fr & 8) != 0; const int r8 = fr & 7;
;         const int grow0 = rowbase + u.pm * 256 + wr * 64 + fr;
;         const int mrow0 = rowbase + u.pm * 256 + wr * 64 + r8;
;         const int b = batch_of(rowbase + u.pm * 256);
;         const int col0 = u.pn * 256 + wc * 32 + 4 * fq;
;         const int mcol = col0 + (hi ? 16 : 0);
;         const float* rp0 = (first ? (mrow0 < MP ? xp + (size_t)mrow0 * D : xs + (size_t)(mrow0 - MP) * D) : out + (size_t)mrow0 * D) + mcol;
;         f32x4 xi[RES_DEPTH][4];
; #pragma unroll
;         for (int r = 0; r < RES_DEPTH; ++r)
; #pragma unroll
;             for (int q = 0; q < 4; ++q) xi[r][q] = *(const f32x4*)(rp0 + (size_t)((r >> 2) * 128 + (r & 3) * 16 + (q & 1) * 8) * D + (q >> 1) * 128);
;         const float* gp = gate + (size_t)b * NMOD + col0;
;         f32x4 gv[2][2], mv[2][2];
; #pragma unroll
;         for (int bj = 0; bj < 2; ++bj)
; #pragma unroll
;             for (int n = 0; n < 2; ++n) { gv[bj][n] = *(const f32x4*)(gp + bj * 128 + n * 16) * coef;
;                 mv[bj][n] = gm ? *(const f32x4*)(gm + b * D + col0 + bj * 128 + n * 16) : (f32x4){0.f, 0.f, 0.f, 0.f}; }
; #pragma unroll
;         for (int r = 0; r < 8; ++r) {
;             const int ai = r >> 2, m = r & 3;
;             const int grow = grow0 + ai * 128 + m * 16;
;             const size_t mo0 = (size_t)(mrow0 + ai * 128 + m * 16) * D + mcol, mo1 = mo0 + (size_t)8 * D;
;             f32x4 xo[2][2];
; #pragma unroll
;             for (int bj = 0; bj < 2; ++bj) {
;                 const f32x4 L1 = xi[r % RES_DEPTH][bj * 2], L2 = xi[r % RES_DEPTH][bj * 2 + 1];
;                 const f32x4 T = dpp_ror8(hi ? L1 : L2);
;                 const f32x4 x0 = hi ? T : L1, x1 = hi ? L2 : T;
;                 xo[bj][0] = x0 + gv[bj][0] * acc[ai][bj][m][0]; xo[bj][1] = x1 + gv[bj][1] * acc[ai][bj][m][1];
;             }
;             if (r + RES_DEPTH < 8) {
;                 const int r2 = r + RES_DEPTH;
; #pragma unroll
;                 for (int q = 0; q < 4; ++q) xi[r % RES_DEPTH][q] = *(const f32x4*)(rp0 + (size_t)((r2 >> 2) * 128 + (r2 & 3) * 16 + (q & 1) * 8) * D + (q >> 1) * 128);
.LBB0_301:
	s_add_i32 s27, s38, 0xffff8000
	s_lshr_b32 s27, s27, 14
	s_ashr_i32 s26, s38, 12
	s_add_i32 s27, s27, 8
	s_cmp_lt_i32 s38, 0x8000
	s_cselect_b32 s38, s26, s27
	s_lshl_b32 s26, s2, 8
	v_ashrrev_i32_e32 v44, 2, v242
	s_or_b32 s26, s26, s15
	v_and_b32_e32 v44, -4, v44
	v_and_b32_e32 v192, 8, v242
	v_add_u32_e32 v44, s26, v44
	v_lshl_add_u32 v218, v192, 1, v44
	v_lshlrev_b64 v[42:43], 12, v[42:43]
	v_lshl_add_u64 v[40:41], v[40:41], 0, v[42:43]
	v_ashrrev_i32_e32 v219, 31, v218
	v_lshl_add_u64 v[220:221], v[218:219], 2, v[40:41]
	s_mov_b32 s26, 0x8000
	v_add_co_u32_e32 v40, vcc, s26, v220
	s_mov_b32 s26, 0x10000
	s_nop 0
	v_addc_co_u32_e32 v41, vcc, 0, v221, vcc
	global_load_dwordx4 v[152:155], v[220:221], off nt
	global_load_dwordx4 v[172:175], v[220:221], off offset:512 nt
	global_load_dwordx4 v[156:159], v[40:41], off nt
	global_load_dwordx4 v[168:171], v[40:41], off offset:512 nt
	v_add_co_u32_e32 v40, vcc, s26, v220
	s_mov_b32 s26, 0x18000
	s_nop 0
	v_addc_co_u32_e32 v41, vcc, 0, v221, vcc
	v_add_co_u32_e32 v42, vcc, s26, v220
	s_mul_i32 s26, s38, 0x9000
	v_readlane_b32 s39, v254, 56
	s_mul_hi_i32 s27, s38, 0x9000
	s_add_u32 s26, s39, s26
	v_readlane_b32 s39, v254, 57
	v_ashrrev_i32_e32 v45, 31, v44
	v_addc_co_u32_e32 v43, vcc, 0, v221, vcc
	global_load_dwordx4 v[160:163], v[40:41], off nt
	global_load_dwordx4 v[148:151], v[40:41], off offset:512 nt
	global_load_dwordx4 v[164:167], v[42:43], off nt
	global_load_dwordx4 v[144:147], v[42:43], off offset:512 nt
	s_addc_u32 s27, s39, s27
	v_lshlrev_b64 v[40:41], 2, v[44:45]
	v_lshl_add_u64 v[42:43], s[26:27], 0, v[40:41]
	global_load_dwordx4 v[184:187], v[42:43], off nt
	v_readlane_b32 s26, v254, 58
	v_readlane_b32 s27, v254, 59
	v_mov_b32_e32 v48, 0
	v_mov_b32_e32 v52, 0
	v_lshl_add_u64 v[40:41], s[26:27], 0, v[40:41]
	s_lshl_b32 s26, s38, 10
	s_ashr_i32 s27, s26, 31
	v_lshl_add_u64 v[222:223], s[26:27], 2, v[40:41]
	v_readlane_b32 s26, v254, 60
	v_readlane_b32 s27, v254, 61
	s_andn2_b64 vcc, exec, s[26:27]
	v_mov_b32_e32 v53, 0
	v_cndmask_b32_e64 v40, 0, 1, s[26:27]
	v_cmp_ne_u32_e64 s[38:39], 1, v40
	v_mov_b32_e32 v54, 0
	v_mov_b32_e32 v55, 0
	s_mov_b64 s[76:77], s[62:63]
	s_cbranch_vccnz .LBB0_303
	global_load_dwordx4 v[52:55], v[222:223], off nt
.LBB0_303:
	global_load_dwordx4 v[188:191], v[42:43], off offset:64 nt
	s_and_b64 vcc, exec, s[38:39]
	v_mov_b32_e32 v49, 0
	v_mov_b32_e32 v50, 0
	v_mov_b32_e32 v51, 0
	s_cbranch_vccnz .LBB0_305
	global_load_dwordx4 v[48:51], v[222:223], off offset:64 nt
.LBB0_305:
	global_load_dwordx4 v[176:179], v[42:43], off offset:512 nt
	v_mov_b32_e32 v40, 0
	s_and_b64 vcc, exec, s[38:39]
	v_mov_b32_e32 v44, 0
	v_mov_b32_e32 v45, 0
	v_mov_b32_e32 v46, 0
	v_mov_b32_e32 v47, 0
	s_cbranch_vccnz .LBB0_307
	global_load_dwordx4 v[44:47], v[222:223], off offset:512 nt
.LBB0_307:
	global_load_dwordx4 v[180:183], v[42:43], off offset:576 nt
	s_and_b64 vcc, exec, s[38:39]
	v_mov_b32_e32 v41, 0
	v_mov_b32_e32 v42, 0
	v_mov_b32_e32 v43, 0
	s_cbranch_vccnz .LBB0_309
	global_load_dwordx4 v[40:43], v[222:223], off offset:576 nt
.LBB0_309:
	v_cmp_eq_u32_e64 s[40:41], 0, v192
	v_lshlrev_b64 v[198:199], 10, v[216:217]
	v_mov_b32_e32 v201, v193
	s_waitcnt vmcnt(0)
	v_cndmask_b32_e64 v200, v152, v156, s[40:41]
	v_lshl_add_u64 v[230:231], v[198:199], 0, v[218:219]
	v_cndmask_b32_e64 v199, v153, v157, s[40:41]
	v_mov_b32_dpp v201, v200 row_ror:8 row_mask:0xf bank_mask:0xf
	v_mov_b32_e32 v200, v193
	v_pk_mul_f32 v[188:189], v[188:189], 0.5 op_sel_hi:[1,0]
	v_cndmask_b32_e64 v156, v156, v201, s[40:41]
	v_mov_b32_dpp v200, v199 row_ror:8 row_mask:0xf bank_mask:0xf
	v_cndmask_b32_e64 v157, v157, v200, s[40:41]
	v_cndmask_b32_e64 v198, v154, v158, s[40:41]
	v_mov_b32_e32 v199, v193
	v_pk_fma_f32 v[224:225], v[128:129], v[188:189], v[156:157]
	v_cndmask_b32_e64 v128, v175, v171, s[40:41]
	v_mov_b32_e32 v244, 0
	s_mov_b32 s26, 0x20000
	v_cndmask_b32_e64 v192, v155, v159, s[40:41]
	v_mov_b32_dpp v199, v198 row_ror:8 row_mask:0xf bank_mask:0xf
	v_mov_b32_e32 v198, v193
	v_cndmask_b32_e64 v129, v174, v170, s[40:41]
	v_mov_b32_e32 v217, 0
	v_mov_b32_dpp v244, v128 row_ror:8 row_mask:0xf bank_mask:0xf
	v_add_co_u32_e32 v128, vcc, s26, v220
	v_pk_mul_f32 v[184:185], v[184:185], 0.5 op_sel_hi:[1,0]
	v_mov_b32_dpp v198, v192 row_ror:8 row_mask:0xf bank_mask:0xf
	v_cndmask_b32_e64 v153, v200, v153, s[40:41]
	v_cndmask_b32_e64 v152, v201, v152, s[40:41]
	v_mov_b32_dpp v217, v129 row_ror:8 row_mask:0xf bank_mask:0xf
	v_addc_co_u32_e32 v129, vcc, 0, v221, vcc
	s_mov_b32 s26, 0x28000
	v_pk_mul_f32 v[190:191], v[190:191], 0.5 op_sel_hi:[1,0]
	v_cndmask_b32_e64 v159, v159, v198, s[40:41]
	v_cndmask_b32_e64 v158, v158, v199, s[40:41]
	v_pk_fma_f32 v[228:229], v[132:133], v[184:185], v[152:153]
	v_add_co_u32_e32 v132, vcc, s26, v220
	v_pk_mul_f32 v[186:187], v[186:187], 0.5 op_sel_hi:[1,0]
	v_cndmask_b32_e64 v155, v198, v155, s[40:41]
	v_cndmask_b32_e64 v154, v199, v154, s[40:41]
	v_pk_fma_f32 v[222:223], v[130:131], v[190:191], v[158:159]
	v_cndmask_b32_e64 v130, v173, v169, s[40:41]
	v_cndmask_b32_e64 v131, v172, v168, s[40:41]
	v_mov_b32_e32 v192, 0
	v_mov_b32_e32 v243, 0
	v_addc_co_u32_e32 v133, vcc, 0, v221, vcc
	v_pk_fma_f32 v[226:227], v[134:135], v[186:187], v[154:155]
	v_mov_b32_dpp v192, v131 row_ror:8 row_mask:0xf bank_mask:0xf
	v_mov_b32_dpp v243, v130 row_ror:8 row_mask:0xf bank_mask:0xf
	global_load_dwordx4 v[152:155], v[128:129], off nt
	global_load_dwordx4 v[156:159], v[132:133], off nt
	s_nop 0
	global_load_dwordx4 v[128:131], v[128:129], off offset:512 nt
	s_nop 0
	global_load_dwordx4 v[132:135], v[132:133], off offset:512 nt
	v_cndmask_b32_e64 v200, v229, v225, s[40:41]
	v_mov_b32_e32 v233, v193
	v_cndmask_b32_e64 v199, v226, v222, s[40:41]
	v_cndmask_b32_e64 v198, v227, v223, s[40:41]
	v_mov_b32_dpp v233, v200 row_ror:8 row_mask:0xf bank_mask:0xf
	v_mov_b32_e32 v200, v193
	v_cndmask_b32_e64 v201, v228, v224, s[40:41]
	v_mov_b32_e32 v232, v193
	v_mov_b32_dpp v200, v199 row_ror:8 row_mask:0xf bank_mask:0xf
	v_mov_b32_e32 v199, v193
	v_mov_b32_dpp v232, v201 row_ror:8 row_mask:0xf bank_mask:0xf
	v_cndmask_b32_e64 v248, v200, v226, s[40:41]
	v_mov_b32_dpp v199, v198 row_ror:8 row_mask:0xf bank_mask:0xf
	v_cndmask_b32_e64 v249, v199, v227, s[40:41]
	v_cndmask_b32_e64 v247, v233, v229, s[40:41]
	v_cndmask_b32_e64 v246, v232, v228, s[40:41]
	v_cndmask_b32_e64 v201, v223, v199, s[40:41]
	v_cndmask_b32_e64 v199, v225, v233, s[40:41]
	v_cndmask_b32_e64 v198, v224, v232, s[40:41]
	v_lshl_add_u64 v[232:233], v[230:231], 2, s[82:83]
	global_store_dwordx4 v[232:233], v[246:249], off nt
	v_cndmask_b32_e64 v200, v222, v200, s[40:41]
	v_lshl_add_u64 v[230:231], v[230:231], 1, s[8:9]
	v_add_co_u32_e32 v246, vcc, 0x8000, v232
	s_nop 1
	v_addc_co_u32_e32 v247, vcc, 0, v233, vcc
	s_and_b64 vcc, exec, s[38:39]
	global_store_dwordx4 v[246:247], v[198:201], off nt
	s_cbranch_vccnz .LBB0_311
; __device__ __forceinline__ unsigned cvt_pk_bf16(float lo, float hi) { unsigned r; asm volatile("v_cvt_pk_bf16_f32 %0, %1, %2" : "=v"(r) : "v"(lo), "v"(hi)); return r; }
;     __device__ __forceinline__ void operator()(const f32x4 (&acc)[2][2][4][2], const pg8::Unit& u, int wr, int wc, int fr_, int fq_) const {
;     ...
;         for (int r = 0; r < 8; ++r) {
;             const int ai = r >> 2, m = r & 3;
;             const int grow = grow0 + ai * 128 + m * 16;
;             const size_t mo0 = (size_t)(mrow0 + ai * 128 + m * 16) * D + mcol, mo1 = mo0 + (size_t)8 * D;
;             f32x4 xo[2][2];
; #pragma unroll
;             for (int bj = 0; bj < 2; ++bj) {
;                 const f32x4 L1 = xi[r % RES_DEPTH][bj * 2], L2 = xi[r % RES_DEPTH][bj * 2 + 1];
;                 const f32x4 T = dpp_ror8(hi ? L1 : L2);
;                 const f32x4 x0 = hi ? T : L1, x1 = hi ? L2 : T;
;                 xo[bj][0] = x0 + gv[bj][0] * acc[ai][bj][m][0]; xo[bj][1] = x1 + gv[bj][1] * acc[ai][bj][m][1];
;             }
;             if (r + RES_DEPTH < 8) {
;                 const int r2 = r + RES_DEPTH;
; #pragma unroll
;                 for (int q = 0; q < 4; ++q) xi[r % RES_DEPTH][q] = *(const f32x4*)(rp0 + (size_t)((r2 >> 2) * 128 + (r2 & 3) * 16 + (q & 1) * 8) * D + (q >> 1) * 128);
;             }
;             float ss = 0.f;
; #pragma unroll
;             for (int bj = 0; bj < 2; ++bj) {
;                 const f32x4 a0 = xo[bj][0], a1 = xo[bj][1];
;                 ss += ((a0[0] * a0[0] + a0[1] * a0[1]) + (a0[2] * a0[2] + a0[3] * a0[3])) + ((a1[0] * a1[0] + a1[1] * a1[1]) + (a1[2] * a1[2] + a1[3] * a1[3]));
;                 const f32x4 T2 = dpp_ror8(hi ? a0 : a1);
;                 const f32x4 d1 = hi ? T2 : a0, d2 = hi ? a1 : T2;
;                 *(f32x4*)(out + mo0 + bj * 128) = d1; *(f32x4*)(out + mo1 + bj * 128) = d2;
;                 if (gm) { const f32x4 o0 = a0 * mv[bj][0], o1 = a1 * mv[bj][1];
;                     u32x2 w0, w1; w0.x = cvt_pk_bf16(o0[0], o0[1]); w0.y = cvt_pk_bf16(o0[2], o0[3]); w1.x = cvt_pk_bf16(o1[0], o1[1]); w1.y = cvt_pk_bf16(o1[2], o1[3]);
;                     const u32x2 T3 = dpp_ror8(hi ? w0 : w1);
;                     const u32x2 e1 = hi ? T3 : w0, e2 = hi ? w1 : T3;
;                     *(u32x2*)(xg + mo0 + bj * 128) = e1; *(u32x2*)(xg + mo1 + bj * 128) = e2; }
	s_nop 0
	v_pk_mul_f32 v[198:199], v[54:55], v[226:227]
	v_pk_mul_f32 v[200:201], v[52:53], v[228:229]
	v_pk_mul_f32 v[246:247], v[50:51], v[222:223]
	v_pk_mul_f32 v[248:249], v[48:49], v[224:225]
	v_cvt_pk_bf16_f32 v200, v200, v201
	v_cvt_pk_bf16_f32 v198, v198, v199
	s_nop 0
	v_cvt_pk_bf16_f32 v245, v248, v249
	v_cvt_pk_bf16_f32 v201, v246, v247
	v_mov_b32_e32 v247, v193
	v_cndmask_b32_e64 v246, v200, v245, s[40:41]
	v_cndmask_b32_e64 v199, v198, v201, s[40:41]
	s_nop 0
	v_mov_b32_dpp v247, v246 row_ror:8 row_mask:0xf bank_mask:0xf
	v_mov_b32_e32 v246, v193
	s_nop 1
	v_mov_b32_dpp v246, v199 row_ror:8 row_mask:0xf bank_mask:0xf
	v_cndmask_b32_e64 v199, v246, v198, s[40:41]
	v_cndmask_b32_e64 v198, v247, v200, s[40:41]
	global_store_dwordx2 v[230:231], v[198:199], off
	v_add_co_u32_e32 v198, vcc, 0x4000, v230
	v_cndmask_b32_e64 v201, v201, v246, s[40:41]
	v_cndmask_b32_e64 v200, v245, v247, s[40:41]
	v_addc_co_u32_e32 v199, vcc, 0, v231, vcc
	global_store_dwordx2 v[198:199], v[200:201], off
.LBB0_311:
	v_pk_mul_f32 v[182:183], v[182:183], 0.5 op_sel_hi:[1,0]
	v_pk_mul_f32 v[180:181], v[180:181], 0.5 op_sel_hi:[1,0]
	v_pk_mul_f32 v[178:179], v[178:179], 0.5 op_sel_hi:[1,0]
	v_pk_mul_f32 v[176:177], v[176:177], 0.5 op_sel_hi:[1,0]
	v_cndmask_b32_e64 v173, v243, v173, s[40:41]
	v_cndmask_b32_e64 v172, v192, v172, s[40:41]
	v_cndmask_b32_e64 v175, v244, v175, s[40:41]
	v_cndmask_b32_e64 v174, v217, v174, s[40:41]
	v_cndmask_b32_e64 v169, v169, v243, s[40:41]
	v_cndmask_b32_e64 v168, v168, v192, s[40:41]
	v_cndmask_b32_e64 v171, v171, v244, s[40:41]
	v_cndmask_b32_e64 v170, v170, v217, s[40:41]
	v_pk_fma_f32 v[142:143], v[142:143], v[178:179], v[174:175]
	v_pk_fma_f32 v[140:141], v[140:141], v[176:177], v[172:173]
	v_pk_fma_f32 v[138:139], v[138:139], v[182:183], v[170:171]
	v_pk_fma_f32 v[136:137], v[136:137], v[180:181], v[168:169]
	v_cndmask_b32_e64 v168, v143, v139, s[40:41]
	v_cndmask_b32_e64 v169, v142, v138, s[40:41]
	v_cndmask_b32_e64 v170, v141, v137, s[40:41]
	v_cndmask_b32_e64 v171, v140, v136, s[40:41]
	v_mov_b32_e32 v172, v193
	v_mov_b32_e32 v173, v193
	v_mov_b32_e32 v174, v193
	v_mov_b32_e32 v175, v193
	v_mov_b32_dpp v172, v171 row_ror:8 row_mask:0xf bank_mask:0xf
	v_mov_b32_dpp v173, v170 row_ror:8 row_mask:0xf bank_mask:0xf
	v_mov_b32_dpp v174, v169 row_ror:8 row_mask:0xf bank_mask:0xf
	v_mov_b32_dpp v175, v168 row_ror:8 row_mask:0xf bank_mask:0xf
	v_lshl_add_u64 v[198:199], v[232:233], 0, s[60:61]
	v_cndmask_b32_e64 v171, v175, v143, s[40:41]
	v_cndmask_b32_e64 v170, v174, v142, s[40:41]
	v_cndmask_b32_e64 v169, v173, v141, s[40:41]
	v_cndmask_b32_e64 v168, v172, v140, s[40:41]
	v_cndmask_b32_e64 v175, v139, v175, s[40:41]
	v_cndmask_b32_e64 v174, v138, v174, s[40:41]
	v_cndmask_b32_e64 v173, v137, v173, s[40:41]
	v_cndmask_b32_e64 v172, v136, v172, s[40:41]
	s_and_b64 vcc, exec, s[38:39]
	global_store_dwordx4 v[232:233], v[168:171], off offset:512 nt
	global_store_dwordx4 v[198:199], v[172:175], off offset:512 nt
	s_cbranch_vccnz .LBB0_313
	v_pk_mul_f32 v[168:169], v[46:47], v[142:143]
	v_pk_mul_f32 v[170:171], v[44:45], v[140:141]
	v_pk_mul_f32 v[172:173], v[42:43], v[138:139]
	v_pk_mul_f32 v[174:175], v[40:41], v[136:137]
	v_cvt_pk_bf16_f32 v170, v170, v171
	v_cvt_pk_bf16_f32 v168, v168, v169
	s_nop 0
	v_cvt_pk_bf16_f32 v174, v174, v175
	v_cvt_pk_bf16_f32 v171, v172, v173
	v_mov_b32_e32 v173, v193
	v_cndmask_b32_e64 v172, v170, v174, s[40:41]
	v_cndmask_b32_e64 v169, v168, v171, s[40:41]
	s_nop 0
	v_mov_b32_dpp v173, v172 row_ror:8 row_mask:0xf bank_mask:0xf
	v_mov_b32_e32 v172, v193
	s_nop 1
	v_mov_b32_dpp v172, v169 row_ror:8 row_mask:0xf bank_mask:0xf
	v_cndmask_b32_e64 v169, v172, v168, s[40:41]
	v_cndmask_b32_e64 v168, v173, v170, s[40:41]
	global_store_dwordx2 v[230:231], v[168:169], off offset:256
	v_add_co_u32_e32 v168, vcc, 0x4000, v230
	v_cndmask_b32_e64 v171, v171, v172, s[40:41]
	v_cndmask_b32_e64 v170, v174, v173, s[40:41]
	v_addc_co_u32_e32 v169, vcc, 0, v231, vcc
	global_store_dwordx2 v[168:169], v[170:171], off offset:256

; __device__ __forceinline__ unsigned cvt_pk_bf16(float lo, float hi) { unsigned r; asm volatile("v_cvt_pk_bf16_f32 %0, %1, %2" : "=v"(r) : "v"(lo), "v"(hi)); return r; }
;     __device__ __forceinline__ void operator()(const f32x4 (&acc)[2][2][4][2], const pg8::Unit& u, int wr, int wc, int fr_, int fq_) const {
;     ...
;         for (int r = 0; r < 8; ++r) {
;             const int ai = r >> 2, m = r & 3;
;             const int grow = grow0 + ai * 128 + m * 16;
;             const size_t mo0 = (size_t)(mrow0 + ai * 128 + m * 16) * D + mcol, mo1 = mo0 + (size_t)8 * D;
;             f32x4 xo[2][2];
; #pragma unroll
;             for (int bj = 0; bj < 2; ++bj) {
;                 const f32x4 L1 = xi[r % RES_DEPTH][bj * 2], L2 = xi[r % RES_DEPTH][bj * 2 + 1];
;                 const f32x4 T = dpp_ror8(hi ? L1 : L2);
;                 const f32x4 x0 = hi ? T : L1, x1 = hi ? L2 : T;
;                 xo[bj][0] = x0 + gv[bj][0] * acc[ai][bj][m][0]; xo[bj][1] = x1 + gv[bj][1] * acc[ai][bj][m][1];
;             }
;             if (r + RES_DEPTH < 8) {
;                 const int r2 = r + RES_DEPTH;
; #pragma unroll
;                 for (int q = 0; q < 4; ++q) xi[r % RES_DEPTH][q] = *(const f32x4*)(rp0 + (size_t)((r2 >> 2) * 128 + (r2 & 3) * 16 + (q & 1) * 8) * D + (q >> 1) * 128);
;             }
;             float ss = 0.f;
; #pragma unroll
;             for (int bj = 0; bj < 2; ++bj) {
;                 const f32x4 a0 = xo[bj][0], a1 = xo[bj][1];
;                 ss += ((a0[0] * a0[0] + a0[1] * a0[1]) + (a0[2] * a0[2] + a0[3] * a0[3])) + ((a1[0] * a1[0] + a1[1] * a1[1]) + (a1[2] * a1[2] + a1[3] * a1[3]));
;                 const f32x4 T2 = dpp_ror8(hi ? a0 : a1);
;                 const f32x4 d1 = hi ? T2 : a0, d2 = hi ? a1 : T2;
;                 *(f32x4*)(out + mo0 + bj * 128) = d1; *(f32x4*)(out + mo1 + bj * 128) = d2;
;                 if (gm) { const f32x4 o0 = a0 * mv[bj][0], o1 = a1 * mv[bj][1];
;                     u32x2 w0, w1; w0.x = cvt_pk_bf16(o0[0], o0[1]); w0.y = cvt_pk_bf16(o0[2], o0[3]); w1.x = cvt_pk_bf16(o1[0], o1[1]); w1.y = cvt_pk_bf16(o1[2], o1[3]);
;                     const u32x2 T3 = dpp_ror8(hi ? w0 : w1);
;                     const u32x2 e1 = hi ? T3 : w0, e2 = hi ? w1 : T3;
;                     *(u32x2*)(xg + mo0 + bj * 128) = e1; *(u32x2*)(xg + mo1 + bj * 128) = e2; }
;             }
.LBB0_315:
	s_or_b64 exec, exec, s[26:27]
	v_or_b32_e32 v136, 16, v216
	s_waitcnt lgkmcnt(0)
	v_ashrrev_i32_e32 v137, 31, v136
	v_lshlrev_b64 v[136:137], 10, v[136:137]
	v_cndmask_b32_e64 v138, v161, v165, s[40:41]
	v_cndmask_b32_e64 v139, v160, v164, s[40:41]
	v_mov_b32_e32 v140, v193
	v_mov_b32_e32 v141, v193
	v_lshl_add_u64 v[170:171], v[136:137], 0, v[218:219]
	v_cndmask_b32_e64 v136, v163, v167, s[40:41]
	v_cndmask_b32_e64 v137, v162, v166, s[40:41]
	v_mov_b32_dpp v140, v139 row_ror:8 row_mask:0xf bank_mask:0xf
	v_mov_b32_dpp v141, v138 row_ror:8 row_mask:0xf bank_mask:0xf
	v_mov_b32_e32 v142, v193
	v_mov_b32_e32 v143, v193
	v_mov_b32_e32 v223, 0
	v_mov_b32_dpp v142, v137 row_ror:8 row_mask:0xf bank_mask:0xf
	v_mov_b32_dpp v143, v136 row_ror:8 row_mask:0xf bank_mask:0xf
	v_cndmask_b32_e64 v137, v141, v161, s[40:41]
	v_cndmask_b32_e64 v136, v140, v160, s[40:41]
	v_cndmask_b32_e64 v141, v165, v141, s[40:41]
	v_cndmask_b32_e64 v140, v164, v140, s[40:41]
	v_cndmask_b32_e64 v139, v143, v163, s[40:41]
	v_cndmask_b32_e64 v138, v142, v162, s[40:41]
	v_pk_fma_f32 v[162:163], v[120:121], v[188:189], v[140:141]
	v_cndmask_b32_e64 v120, v151, v147, s[40:41]
	s_mov_b32 s2, 0x30000
	v_cndmask_b32_e64 v121, v150, v146, s[40:41]
	v_mov_b32_e32 v217, 0
	v_mov_b32_dpp v223, v120 row_ror:8 row_mask:0xf bank_mask:0xf
	v_add_co_u32_e32 v120, vcc, s2, v220
	v_mov_b32_dpp v217, v121 row_ror:8 row_mask:0xf bank_mask:0xf
	s_nop 0
	v_addc_co_u32_e32 v121, vcc, 0, v221, vcc
	s_mov_b32 s2, 0x38000
	v_cndmask_b32_e64 v143, v167, v143, s[40:41]
	v_cndmask_b32_e64 v142, v166, v142, s[40:41]
	v_pk_fma_f32 v[166:167], v[124:125], v[184:185], v[136:137]
	v_add_co_u32_e32 v124, vcc, s2, v220
	v_pk_fma_f32 v[160:161], v[122:123], v[190:191], v[142:143]
	v_cndmask_b32_e64 v122, v149, v145, s[40:41]
	v_cndmask_b32_e64 v123, v148, v144, s[40:41]
	v_mov_b32_e32 v192, 0
	v_mov_b32_e32 v222, 0
	v_addc_co_u32_e32 v125, vcc, 0, v221, vcc
	v_pk_fma_f32 v[164:165], v[126:127], v[186:187], v[138:139]
	v_mov_b32_dpp v192, v123 row_ror:8 row_mask:0xf bank_mask:0xf
	v_mov_b32_dpp v222, v122 row_ror:8 row_mask:0xf bank_mask:0xf
	global_load_dwordx4 v[136:139], v[120:121], off nt
	global_load_dwordx4 v[140:143], v[124:125], off nt
	s_nop 0
	global_load_dwordx4 v[120:123], v[120:121], off offset:512 nt
	s_nop 0
	global_load_dwordx4 v[124:127], v[124:125], off offset:512 nt
	v_cndmask_b32_e64 v173, v164, v160, s[40:41]
	v_mov_b32_e32 v226, v193
	v_cndmask_b32_e64 v172, v165, v161, s[40:41]
	v_cndmask_b32_e64 v198, v167, v163, s[40:41]
	v_cndmask_b32_e64 v199, v166, v162, s[40:41]
	v_mov_b32_e32 v224, v193
	v_mov_b32_e32 v225, v193
	v_mov_b32_dpp v226, v173 row_ror:8 row_mask:0xf bank_mask:0xf
	v_mov_b32_e32 v173, v193
	v_mov_b32_dpp v224, v199 row_ror:8 row_mask:0xf bank_mask:0xf
	v_mov_b32_dpp v225, v198 row_ror:8 row_mask:0xf bank_mask:0xf
	v_mov_b32_dpp v173, v172 row_ror:8 row_mask:0xf bank_mask:0xf
	v_cndmask_b32_e64 v201, v173, v165, s[40:41]
	v_cndmask_b32_e64 v200, v226, v164, s[40:41]
	v_cndmask_b32_e64 v199, v225, v167, s[40:41]
	v_cndmask_b32_e64 v198, v224, v166, s[40:41]
	v_cndmask_b32_e64 v227, v161, v173, s[40:41]
	v_lshl_add_u64 v[172:173], v[170:171], 2, s[82:83]
	global_store_dwordx4 v[172:173], v[198:201], off nt
	v_cndmask_b32_e64 v226, v160, v226, s[40:41]
	v_cndmask_b32_e64 v225, v163, v225, s[40:41]
	v_add_co_u32_e32 v198, vcc, 0x8000, v172
	v_cndmask_b32_e64 v224, v162, v224, s[40:41]
	s_nop 0
	v_addc_co_u32_e32 v199, vcc, 0, v173, vcc
	s_and_b64 vcc, exec, s[38:39]
	v_lshl_add_u64 v[170:171], v[170:171], 1, s[8:9]
	global_store_dwordx4 v[198:199], v[224:227], off nt
	s_cbranch_vccnz .LBB0_317
	v_pk_mul_f32 v[198:199], v[54:55], v[164:165]
	v_pk_mul_f32 v[200:201], v[52:53], v[166:167]
	v_pk_mul_f32 v[224:225], v[50:51], v[160:161]
	v_pk_mul_f32 v[226:227], v[48:49], v[162:163]
	v_cvt_pk_bf16_f32 v200, v200, v201
	v_cvt_pk_bf16_f32 v198, v198, v199
	s_nop 0
	v_cvt_pk_bf16_f32 v226, v226, v227
	v_cvt_pk_bf16_f32 v201, v224, v225
	v_mov_b32_e32 v225, v193
	v_cndmask_b32_e64 v224, v200, v226, s[40:41]
	v_cndmask_b32_e64 v199, v198, v201, s[40:41]
	s_nop 0
	v_mov_b32_dpp v225, v224 row_ror:8 row_mask:0xf bank_mask:0xf
	v_mov_b32_e32 v224, v193
	s_nop 1
	v_mov_b32_dpp v224, v199 row_ror:8 row_mask:0xf bank_mask:0xf
	v_cndmask_b32_e64 v199, v224, v198, s[40:41]
	v_cndmask_b32_e64 v198, v225, v200, s[40:41]
	global_store_dwordx2 v[170:171], v[198:199], off
	v_add_co_u32_e32 v198, vcc, 0x4000, v170
	v_cndmask_b32_e64 v201, v201, v224, s[40:41]
	v_cndmask_b32_e64 v200, v226, v225, s[40:41]
	v_addc_co_u32_e32 v199, vcc, 0, v171, vcc
	global_store_dwordx2 v[198:199], v[200:201], off
; __device__ __forceinline__ unsigned cvt_pk_bf16(float lo, float hi) { unsigned r; asm volatile("v_cvt_pk_bf16_f32 %0, %1, %2" : "=v"(r) : "v"(lo), "v"(hi)); return r; }
;     __device__ __forceinline__ void operator()(const f32x4 (&acc)[2][2][4][2], const pg8::Unit& u, int wr, int wc, int fr_, int fq_) const {
;     ...
;         for (int r = 0; r < 8; ++r) {
;             const int ai = r >> 2, m = r & 3;
;             const int grow = grow0 + ai * 128 + m * 16;
;             const size_t mo0 = (size_t)(mrow0 + ai * 128 + m * 16) * D + mcol, mo1 = mo0 + (size_t)8 * D;
;             f32x4 xo[2][2];
; #pragma unroll
;             for (int bj = 0; bj < 2; ++bj) {
;                 const f32x4 L1 = xi[r % RES_DEPTH][bj * 2], L2 = xi[r % RES_DEPTH][bj * 2 + 1];
;                 const f32x4 T = dpp_ror8(hi ? L1 : L2);
;                 const f32x4 x0 = hi ? T : L1, x1 = hi ? L2 : T;
;                 xo[bj][0] = x0 + gv[bj][0] * acc[ai][bj][m][0]; xo[bj][1] = x1 + gv[bj][1] * acc[ai][bj][m][1];
;             }
;             if (r + RES_DEPTH < 8) {
;                 const int r2 = r + RES_DEPTH;
; #pragma unroll
;                 for (int q = 0; q < 4; ++q) xi[r % RES_DEPTH][q] = *(const f32x4*)(rp0 + (size_t)((r2 >> 2) * 128 + (r2 & 3) * 16 + (q & 1) * 8) * D + (q >> 1) * 128);
;             }
;             float ss = 0.f;
; #pragma unroll
;             for (int bj = 0; bj < 2; ++bj) {
;                 const f32x4 a0 = xo[bj][0], a1 = xo[bj][1];
;                 ss += ((a0[0] * a0[0] + a0[1] * a0[1]) + (a0[2] * a0[2] + a0[3] * a0[3])) + ((a1[0] * a1[0] + a1[1] * a1[1]) + (a1[2] * a1[2] + a1[3] * a1[3]));
;                 const f32x4 T2 = dpp_ror8(hi ? a0 : a1);
;                 const f32x4 d1 = hi ? T2 : a0, d2 = hi ? a1 : T2;
;                 *(f32x4*)(out + mo0 + bj * 128) = d1; *(f32x4*)(out + mo1 + bj * 128) = d2;
;                 if (gm) { const f32x4 o0 = a0 * mv[bj][0], o1 = a1 * mv[bj][1];
;                     u32x2 w0, w1; w0.x = cvt_pk_bf16(o0[0], o0[1]); w0.y = cvt_pk_bf16(o0[2], o0[3]); w1.x = cvt_pk_bf16(o1[0], o1[1]); w1.y = cvt_pk_bf16(o1[2], o1[3]);
;                     const u32x2 T3 = dpp_ror8(hi ? w0 : w1);
;                     const u32x2 e1 = hi ? T3 : w0, e2 = hi ? w1 : T3;
;                     *(u32x2*)(xg + mo0 + bj * 128) = e1; *(u32x2*)(xg + mo1 + bj * 128) = e2; }
.LBB0_317:
	v_cndmask_b32_e64 v149, v222, v149, s[40:41]
	v_cndmask_b32_e64 v148, v192, v148, s[40:41]
	v_cndmask_b32_e64 v151, v223, v151, s[40:41]
	v_cndmask_b32_e64 v150, v217, v150, s[40:41]
	v_cndmask_b32_e64 v145, v145, v222, s[40:41]
	v_cndmask_b32_e64 v144, v144, v192, s[40:41]
	v_cndmask_b32_e64 v147, v147, v223, s[40:41]
	v_cndmask_b32_e64 v146, v146, v217, s[40:41]
	v_pk_fma_f32 v[118:119], v[118:119], v[178:179], v[150:151]
	v_pk_fma_f32 v[116:117], v[116:117], v[176:177], v[148:149]
	v_pk_fma_f32 v[114:115], v[114:115], v[182:183], v[146:147]
	v_pk_fma_f32 v[112:113], v[112:113], v[180:181], v[144:145]
	v_cndmask_b32_e64 v144, v119, v115, s[40:41]
	v_cndmask_b32_e64 v145, v118, v114, s[40:41]
	v_cndmask_b32_e64 v146, v117, v113, s[40:41]
	v_cndmask_b32_e64 v147, v116, v112, s[40:41]
	v_mov_b32_e32 v148, v193
	v_mov_b32_e32 v149, v193
	v_mov_b32_e32 v150, v193
	v_mov_b32_e32 v151, v193
	v_mov_b32_dpp v148, v147 row_ror:8 row_mask:0xf bank_mask:0xf
	v_mov_b32_dpp v149, v146 row_ror:8 row_mask:0xf bank_mask:0xf
	v_mov_b32_dpp v150, v145 row_ror:8 row_mask:0xf bank_mask:0xf
	v_mov_b32_dpp v151, v144 row_ror:8 row_mask:0xf bank_mask:0xf
	v_lshl_add_u64 v[198:199], v[172:173], 0, s[60:61]
	v_cndmask_b32_e64 v147, v151, v119, s[40:41]
	v_cndmask_b32_e64 v146, v150, v118, s[40:41]
	v_cndmask_b32_e64 v145, v149, v117, s[40:41]
	v_cndmask_b32_e64 v144, v148, v116, s[40:41]
	v_cndmask_b32_e64 v151, v115, v151, s[40:41]
	v_cndmask_b32_e64 v150, v114, v150, s[40:41]
	v_cndmask_b32_e64 v149, v113, v149, s[40:41]
	v_cndmask_b32_e64 v148, v112, v148, s[40:41]
	s_and_b64 vcc, exec, s[38:39]
	global_store_dwordx4 v[172:173], v[144:147], off offset:512 nt
	global_store_dwordx4 v[198:199], v[148:151], off offset:512 nt
	s_cbranch_vccnz .LBB0_319
	v_pk_mul_f32 v[144:145], v[46:47], v[118:119]
	v_pk_mul_f32 v[146:147], v[44:45], v[116:117]
	v_pk_mul_f32 v[148:149], v[42:43], v[114:115]
	v_pk_mul_f32 v[150:151], v[40:41], v[112:113]
	v_cvt_pk_bf16_f32 v146, v146, v147
	v_cvt_pk_bf16_f32 v144, v144, v145
	s_nop 0
	v_cvt_pk_bf16_f32 v150, v150, v151
	v_cvt_pk_bf16_f32 v147, v148, v149
	v_mov_b32_e32 v149, v193
	v_cndmask_b32_e64 v148, v146, v150, s[40:41]
	v_cndmask_b32_e64 v145, v144, v147, s[40:41]
	s_nop 0
	v_mov_b32_dpp v149, v148 row_ror:8 row_mask:0xf bank_mask:0xf
	v_mov_b32_e32 v148, v193
	s_nop 1
	v_mov_b32_dpp v148, v145 row_ror:8 row_mask:0xf bank_mask:0xf
	v_cndmask_b32_e64 v145, v148, v144, s[40:41]
	v_cndmask_b32_e64 v144, v149, v146, s[40:41]
	global_store_dwordx2 v[170:171], v[144:145], off offset:256
	v_add_co_u32_e32 v144, vcc, 0x4000, v170
	v_cndmask_b32_e64 v147, v147, v148, s[40:41]
	v_cndmask_b32_e64 v146, v150, v149, s[40:41]
	v_addc_co_u32_e32 v145, vcc, 0, v171, vcc
	global_store_dwordx2 v[144:145], v[146:147], off offset:256

; __device__ __forceinline__ unsigned cvt_pk_bf16(float lo, float hi) { unsigned r; asm volatile("v_cvt_pk_bf16_f32 %0, %1, %2" : "=v"(r) : "v"(lo), "v"(hi)); return r; }
;     __device__ __forceinline__ void operator()(const f32x4 (&acc)[2][2][4][2], const pg8::Unit& u, int wr, int wc, int fr_, int fq_) const {
;     ...
;         for (int r = 0; r < 8; ++r) {
;             const int ai = r >> 2, m = r & 3;
;             const int grow = grow0 + ai * 128 + m * 16;
;             const size_t mo0 = (size_t)(mrow0 + ai * 128 + m * 16) * D + mcol, mo1 = mo0 + (size_t)8 * D;
;             f32x4 xo[2][2];
; #pragma unroll
;             for (int bj = 0; bj < 2; ++bj) {
;                 const f32x4 L1 = xi[r % RES_DEPTH][bj * 2], L2 = xi[r % RES_DEPTH][bj * 2 + 1];
;                 const f32x4 T = dpp_ror8(hi ? L1 : L2);
;                 const f32x4 x0 = hi ? T : L1, x1 = hi ? L2 : T;
;                 xo[bj][0] = x0 + gv[bj][0] * acc[ai][bj][m][0]; xo[bj][1] = x1 + gv[bj][1] * acc[ai][bj][m][1];
;             }
;             if (r + RES_DEPTH < 8) {
;                 const int r2 = r + RES_DEPTH;
; #pragma unroll
;                 for (int q = 0; q < 4; ++q) xi[r % RES_DEPTH][q] = *(const f32x4*)(rp0 + (size_t)((r2 >> 2) * 128 + (r2 & 3) * 16 + (q & 1) * 8) * D + (q >> 1) * 128);
;             }
;             float ss = 0.f;
; #pragma unroll
;             for (int bj = 0; bj < 2; ++bj) {
;                 const f32x4 a0 = xo[bj][0], a1 = xo[bj][1];
;                 ss += ((a0[0] * a0[0] + a0[1] * a0[1]) + (a0[2] * a0[2] + a0[3] * a0[3])) + ((a1[0] * a1[0] + a1[1] * a1[1]) + (a1[2] * a1[2] + a1[3] * a1[3]));
;                 const f32x4 T2 = dpp_ror8(hi ? a0 : a1);
;                 const f32x4 d1 = hi ? T2 : a0, d2 = hi ? a1 : T2;
;                 *(f32x4*)(out + mo0 + bj * 128) = d1; *(f32x4*)(out + mo1 + bj * 128) = d2;
;                 if (gm) { const f32x4 o0 = a0 * mv[bj][0], o1 = a1 * mv[bj][1];
;                     u32x2 w0, w1; w0.x = cvt_pk_bf16(o0[0], o0[1]); w0.y = cvt_pk_bf16(o0[2], o0[3]); w1.x = cvt_pk_bf16(o1[0], o1[1]); w1.y = cvt_pk_bf16(o1[2], o1[3]);
;                     const u32x2 T3 = dpp_ror8(hi ? w0 : w1);
;                     const u32x2 e1 = hi ? T3 : w0, e2 = hi ? w1 : T3;
;                     *(u32x2*)(xg + mo0 + bj * 128) = e1; *(u32x2*)(xg + mo1 + bj * 128) = e2; }
;             }
.LBB0_321:
	s_or_b64 exec, exec, s[26:27]
	v_or_b32_e32 v112, 32, v216
	s_waitcnt lgkmcnt(0)
	v_ashrrev_i32_e32 v113, 31, v112
	v_lshlrev_b64 v[112:113], 10, v[112:113]
	s_waitcnt vmcnt(14)
	v_cndmask_b32_e64 v114, v153, v157, s[40:41]
	v_cndmask_b32_e64 v115, v152, v156, s[40:41]
	v_mov_b32_e32 v116, v193
	v_mov_b32_e32 v117, v193
	v_lshl_add_u64 v[160:161], v[112:113], 0, v[218:219]
	v_cndmask_b32_e64 v112, v155, v159, s[40:41]
	v_cndmask_b32_e64 v113, v154, v158, s[40:41]
	v_mov_b32_dpp v116, v115 row_ror:8 row_mask:0xf bank_mask:0xf
	v_mov_b32_dpp v117, v114 row_ror:8 row_mask:0xf bank_mask:0xf
	v_mov_b32_e32 v118, v193
	v_mov_b32_e32 v119, v193
	s_mov_b32 s2, 0x80000
	v_mov_b32_dpp v118, v113 row_ror:8 row_mask:0xf bank_mask:0xf
	v_mov_b32_dpp v119, v112 row_ror:8 row_mask:0xf bank_mask:0xf
	v_cndmask_b32_e64 v113, v117, v153, s[40:41]
	v_cndmask_b32_e64 v112, v116, v152, s[40:41]
	v_cndmask_b32_e64 v117, v157, v117, s[40:41]
	v_cndmask_b32_e64 v116, v156, v116, s[40:41]
	v_cndmask_b32_e64 v115, v119, v155, s[40:41]
	v_cndmask_b32_e64 v119, v159, v119, s[40:41]
	v_pk_fma_f32 v[146:147], v[104:105], v[188:189], v[116:117]
	s_waitcnt vmcnt(12)
	v_cndmask_b32_e64 v104, v131, v135, s[40:41]
	v_mov_b32_e32 v159, 0
	v_cndmask_b32_e64 v105, v130, v134, s[40:41]
	v_mov_b32_e32 v157, 0
	v_mov_b32_dpp v159, v104 row_ror:8 row_mask:0xf bank_mask:0xf
	v_add_co_u32_e32 v104, vcc, s2, v220
	v_mov_b32_dpp v157, v105 row_ror:8 row_mask:0xf bank_mask:0xf
	s_nop 0
	v_addc_co_u32_e32 v105, vcc, 0, v221, vcc
	s_mov_b32 s2, 0x88000
	v_cndmask_b32_e64 v114, v118, v154, s[40:41]
	v_cndmask_b32_e64 v118, v158, v118, s[40:41]
	v_pk_fma_f32 v[150:151], v[108:109], v[184:185], v[112:113]
	v_add_co_u32_e32 v108, vcc, s2, v220
	v_pk_fma_f32 v[144:145], v[106:107], v[190:191], v[118:119]
	v_cndmask_b32_e64 v106, v129, v133, s[40:41]
	v_cndmask_b32_e64 v107, v128, v132, s[40:41]
	v_mov_b32_e32 v156, 0
	v_mov_b32_e32 v158, 0
	v_addc_co_u32_e32 v109, vcc, 0, v221, vcc
	v_pk_fma_f32 v[148:149], v[110:111], v[186:187], v[114:115]
	v_mov_b32_dpp v156, v107 row_ror:8 row_mask:0xf bank_mask:0xf
	v_mov_b32_dpp v158, v106 row_ror:8 row_mask:0xf bank_mask:0xf
	global_load_dwordx4 v[112:115], v[104:105], off nt
	global_load_dwordx4 v[116:119], v[108:109], off nt
	s_nop 0
	global_load_dwordx4 v[104:107], v[104:105], off offset:512 nt
	s_nop 0
	global_load_dwordx4 v[108:111], v[108:109], off offset:512 nt
	v_cndmask_b32_e64 v155, v150, v146, s[40:41]
	v_mov_b32_e32 v166, v193
	v_cndmask_b32_e64 v154, v151, v147, s[40:41]
	v_cndmask_b32_e64 v153, v148, v144, s[40:41]
	v_mov_b32_dpp v166, v155 row_ror:8 row_mask:0xf bank_mask:0xf
	v_mov_b32_e32 v155, v193
	v_cndmask_b32_e64 v152, v149, v145, s[40:41]
	v_cndmask_b32_e64 v170, v146, v166, s[40:41]
	v_mov_b32_dpp v155, v154 row_ror:8 row_mask:0xf bank_mask:0xf
	v_mov_b32_e32 v154, v193
	v_cndmask_b32_e64 v163, v155, v151, s[40:41]
	v_cndmask_b32_e64 v171, v147, v155, s[40:41]
	v_mov_b32_dpp v154, v153 row_ror:8 row_mask:0xf bank_mask:0xf
	v_mov_b32_e32 v153, v193
	v_cndmask_b32_e64 v164, v154, v148, s[40:41]
	v_cndmask_b32_e64 v172, v144, v154, s[40:41]
	v_lshl_add_u64 v[154:155], v[160:161], 2, s[82:83]
	v_mov_b32_dpp v153, v152 row_ror:8 row_mask:0xf bank_mask:0xf
	v_add_co_u32_e32 v152, vcc, 0x8000, v154
	v_cndmask_b32_e64 v165, v153, v149, s[40:41]
	v_cndmask_b32_e64 v173, v145, v153, s[40:41]
	v_addc_co_u32_e32 v153, vcc, 0, v155, vcc
	v_cndmask_b32_e64 v162, v166, v150, s[40:41]
	global_store_dwordx4 v[152:153], v[170:173], off nt
	s_and_b64 vcc, exec, s[38:39]
	v_lshl_add_u64 v[152:153], v[160:161], 1, s[8:9]
	global_store_dwordx4 v[154:155], v[162:165], off nt
	s_cbranch_vccnz .LBB0_323
	v_pk_mul_f32 v[160:161], v[54:55], v[148:149]
	v_pk_mul_f32 v[162:163], v[52:53], v[150:151]
	v_pk_mul_f32 v[164:165], v[50:51], v[144:145]
	v_pk_mul_f32 v[166:167], v[48:49], v[146:147]
	v_cvt_pk_bf16_f32 v162, v162, v163
	v_cvt_pk_bf16_f32 v160, v160, v161
	s_nop 0
	v_cvt_pk_bf16_f32 v166, v166, v167
	v_cvt_pk_bf16_f32 v163, v164, v165
	v_mov_b32_e32 v165, v193
	v_cndmask_b32_e64 v164, v162, v166, s[40:41]
	v_cndmask_b32_e64 v161, v160, v163, s[40:41]
	s_nop 0
	v_mov_b32_dpp v165, v164 row_ror:8 row_mask:0xf bank_mask:0xf
	v_mov_b32_e32 v164, v193
	s_nop 1
	v_mov_b32_dpp v164, v161 row_ror:8 row_mask:0xf bank_mask:0xf
	v_cndmask_b32_e64 v161, v164, v160, s[40:41]
	v_cndmask_b32_e64 v160, v165, v162, s[40:41]
	global_store_dwordx2 v[152:153], v[160:161], off
	v_add_co_u32_e32 v160, vcc, 0x4000, v152
	v_cndmask_b32_e64 v163, v163, v164, s[40:41]
	v_cndmask_b32_e64 v162, v166, v165, s[40:41]
	v_addc_co_u32_e32 v161, vcc, 0, v153, vcc
	global_store_dwordx2 v[160:161], v[162:163], off
; __device__ __forceinline__ unsigned cvt_pk_bf16(float lo, float hi) { unsigned r; asm volatile("v_cvt_pk_bf16_f32 %0, %1, %2" : "=v"(r) : "v"(lo), "v"(hi)); return r; }
;     __device__ __forceinline__ void operator()(const f32x4 (&acc)[2][2][4][2], const pg8::Unit& u, int wr, int wc, int fr_, int fq_) const {
;     ...
;         for (int r = 0; r < 8; ++r) {
;             const int ai = r >> 2, m = r & 3;
;             const int grow = grow0 + ai * 128 + m * 16;
;             const size_t mo0 = (size_t)(mrow0 + ai * 128 + m * 16) * D + mcol, mo1 = mo0 + (size_t)8 * D;
;             f32x4 xo[2][2];
; #pragma unroll
;             for (int bj = 0; bj < 2; ++bj) {
;                 const f32x4 L1 = xi[r % RES_DEPTH][bj * 2], L2 = xi[r % RES_DEPTH][bj * 2 + 1];
;                 const f32x4 T = dpp_ror8(hi ? L1 : L2);
;                 const f32x4 x0 = hi ? T : L1, x1 = hi ? L2 : T;
;                 xo[bj][0] = x0 + gv[bj][0] * acc[ai][bj][m][0]; xo[bj][1] = x1 + gv[bj][1] * acc[ai][bj][m][1];
;             }
;             if (r + RES_DEPTH < 8) {
;                 const int r2 = r + RES_DEPTH;
; #pragma unroll
;                 for (int q = 0; q < 4; ++q) xi[r % RES_DEPTH][q] = *(const f32x4*)(rp0 + (size_t)((r2 >> 2) * 128 + (r2 & 3) * 16 + (q & 1) * 8) * D + (q >> 1) * 128);
;             }
;             float ss = 0.f;
; #pragma unroll
;             for (int bj = 0; bj < 2; ++bj) {
;                 const f32x4 a0 = xo[bj][0], a1 = xo[bj][1];
;                 ss += ((a0[0] * a0[0] + a0[1] * a0[1]) + (a0[2] * a0[2] + a0[3] * a0[3])) + ((a1[0] * a1[0] + a1[1] * a1[1]) + (a1[2] * a1[2] + a1[3] * a1[3]));
;                 const f32x4 T2 = dpp_ror8(hi ? a0 : a1);
;                 const f32x4 d1 = hi ? T2 : a0, d2 = hi ? a1 : T2;
;                 *(f32x4*)(out + mo0 + bj * 128) = d1; *(f32x4*)(out + mo1 + bj * 128) = d2;
;                 if (gm) { const f32x4 o0 = a0 * mv[bj][0], o1 = a1 * mv[bj][1];
;                     u32x2 w0, w1; w0.x = cvt_pk_bf16(o0[0], o0[1]); w0.y = cvt_pk_bf16(o0[2], o0[3]); w1.x = cvt_pk_bf16(o1[0], o1[1]); w1.y = cvt_pk_bf16(o1[2], o1[3]);
;                     const u32x2 T3 = dpp_ror8(hi ? w0 : w1);
;                     const u32x2 e1 = hi ? T3 : w0, e2 = hi ? w1 : T3;
;                     *(u32x2*)(xg + mo0 + bj * 128) = e1; *(u32x2*)(xg + mo1 + bj * 128) = e2; }
.LBB0_323:
	v_cndmask_b32_e64 v129, v158, v129, s[40:41]
	v_cndmask_b32_e64 v128, v156, v128, s[40:41]
	v_cndmask_b32_e64 v131, v159, v131, s[40:41]
	v_cndmask_b32_e64 v130, v157, v130, s[40:41]
	v_cndmask_b32_e64 v133, v133, v158, s[40:41]
	v_cndmask_b32_e64 v132, v132, v156, s[40:41]
	v_cndmask_b32_e64 v135, v135, v159, s[40:41]
	v_cndmask_b32_e64 v134, v134, v157, s[40:41]
	v_pk_fma_f32 v[102:103], v[102:103], v[178:179], v[130:131]
	v_pk_fma_f32 v[100:101], v[100:101], v[176:177], v[128:129]
	v_pk_fma_f32 v[98:99], v[98:99], v[182:183], v[134:135]
	v_pk_fma_f32 v[96:97], v[96:97], v[180:181], v[132:133]
	v_cndmask_b32_e64 v128, v103, v99, s[40:41]
	v_cndmask_b32_e64 v129, v102, v98, s[40:41]
	v_cndmask_b32_e64 v130, v101, v97, s[40:41]
	v_cndmask_b32_e64 v131, v100, v96, s[40:41]
	v_mov_b32_e32 v132, v193
	v_mov_b32_e32 v133, v193
	v_mov_b32_e32 v134, v193
	v_mov_b32_e32 v135, v193
	v_mov_b32_dpp v132, v131 row_ror:8 row_mask:0xf bank_mask:0xf
	v_mov_b32_dpp v133, v130 row_ror:8 row_mask:0xf bank_mask:0xf
	v_mov_b32_dpp v134, v129 row_ror:8 row_mask:0xf bank_mask:0xf
	v_mov_b32_dpp v135, v128 row_ror:8 row_mask:0xf bank_mask:0xf
	v_lshl_add_u64 v[160:161], v[154:155], 0, s[60:61]
	v_cndmask_b32_e64 v131, v135, v103, s[40:41]
	v_cndmask_b32_e64 v130, v134, v102, s[40:41]
	v_cndmask_b32_e64 v129, v133, v101, s[40:41]
	v_cndmask_b32_e64 v128, v132, v100, s[40:41]
	v_cndmask_b32_e64 v135, v99, v135, s[40:41]
	v_cndmask_b32_e64 v134, v98, v134, s[40:41]
	v_cndmask_b32_e64 v133, v97, v133, s[40:41]
	v_cndmask_b32_e64 v132, v96, v132, s[40:41]
	s_and_b64 vcc, exec, s[38:39]
	global_store_dwordx4 v[154:155], v[128:131], off offset:512 nt
	global_store_dwordx4 v[160:161], v[132:135], off offset:512 nt
	s_cbranch_vccnz .LBB0_325
	v_pk_mul_f32 v[128:129], v[46:47], v[102:103]
	v_pk_mul_f32 v[130:131], v[44:45], v[100:101]
	v_pk_mul_f32 v[132:133], v[42:43], v[98:99]
	v_pk_mul_f32 v[134:135], v[40:41], v[96:97]
	v_cvt_pk_bf16_f32 v130, v130, v131
	v_cvt_pk_bf16_f32 v128, v128, v129
	s_nop 0
	v_cvt_pk_bf16_f32 v134, v134, v135
	v_cvt_pk_bf16_f32 v131, v132, v133
	v_mov_b32_e32 v133, v193
	v_cndmask_b32_e64 v132, v130, v134, s[40:41]
	v_cndmask_b32_e64 v129, v128, v131, s[40:41]
	s_nop 0
	v_mov_b32_dpp v133, v132 row_ror:8 row_mask:0xf bank_mask:0xf
	v_mov_b32_e32 v132, v193
	s_nop 1
	v_mov_b32_dpp v132, v129 row_ror:8 row_mask:0xf bank_mask:0xf
	v_cndmask_b32_e64 v129, v132, v128, s[40:41]
	v_cndmask_b32_e64 v128, v133, v130, s[40:41]
	global_store_dwordx2 v[152:153], v[128:129], off offset:256
	v_add_co_u32_e32 v128, vcc, 0x4000, v152
	v_cndmask_b32_e64 v131, v131, v132, s[40:41]
	v_cndmask_b32_e64 v130, v134, v133, s[40:41]
	v_addc_co_u32_e32 v129, vcc, 0, v153, vcc
	global_store_dwordx2 v[128:129], v[130:131], off offset:256

; __device__ __forceinline__ unsigned cvt_pk_bf16(float lo, float hi) { unsigned r; asm volatile("v_cvt_pk_bf16_f32 %0, %1, %2" : "=v"(r) : "v"(lo), "v"(hi)); return r; }
;     __device__ __forceinline__ void operator()(const f32x4 (&acc)[2][2][4][2], const pg8::Unit& u, int wr, int wc, int fr_, int fq_) const {
;     ...
;         for (int r = 0; r < 8; ++r) {
;             const int ai = r >> 2, m = r & 3;
;             const int grow = grow0 + ai * 128 + m * 16;
;             const size_t mo0 = (size_t)(mrow0 + ai * 128 + m * 16) * D + mcol, mo1 = mo0 + (size_t)8 * D;
;             f32x4 xo[2][2];
; #pragma unroll
;             for (int bj = 0; bj < 2; ++bj) {
;                 const f32x4 L1 = xi[r % RES_DEPTH][bj * 2], L2 = xi[r % RES_DEPTH][bj * 2 + 1];
;                 const f32x4 T = dpp_ror8(hi ? L1 : L2);
;                 const f32x4 x0 = hi ? T : L1, x1 = hi ? L2 : T;
;                 xo[bj][0] = x0 + gv[bj][0] * acc[ai][bj][m][0]; xo[bj][1] = x1 + gv[bj][1] * acc[ai][bj][m][1];
;             }
;             if (r + RES_DEPTH < 8) {
;                 const int r2 = r + RES_DEPTH;
; #pragma unroll
;                 for (int q = 0; q < 4; ++q) xi[r % RES_DEPTH][q] = *(const f32x4*)(rp0 + (size_t)((r2 >> 2) * 128 + (r2 & 3) * 16 + (q & 1) * 8) * D + (q >> 1) * 128);
;             }
;             float ss = 0.f;
; #pragma unroll
;             for (int bj = 0; bj < 2; ++bj) {
;                 const f32x4 a0 = xo[bj][0], a1 = xo[bj][1];
;                 ss += ((a0[0] * a0[0] + a0[1] * a0[1]) + (a0[2] * a0[2] + a0[3] * a0[3])) + ((a1[0] * a1[0] + a1[1] * a1[1]) + (a1[2] * a1[2] + a1[3] * a1[3]));
;                 const f32x4 T2 = dpp_ror8(hi ? a0 : a1);
;                 const f32x4 d1 = hi ? T2 : a0, d2 = hi ? a1 : T2;
;                 *(f32x4*)(out + mo0 + bj * 128) = d1; *(f32x4*)(out + mo1 + bj * 128) = d2;
;                 if (gm) { const f32x4 o0 = a0 * mv[bj][0], o1 = a1 * mv[bj][1];
;                     u32x2 w0, w1; w0.x = cvt_pk_bf16(o0[0], o0[1]); w0.y = cvt_pk_bf16(o0[2], o0[3]); w1.x = cvt_pk_bf16(o1[0], o1[1]); w1.y = cvt_pk_bf16(o1[2], o1[3]);
;                     const u32x2 T3 = dpp_ror8(hi ? w0 : w1);
;                     const u32x2 e1 = hi ? T3 : w0, e2 = hi ? w1 : T3;
;                     *(u32x2*)(xg + mo0 + bj * 128) = e1; *(u32x2*)(xg + mo1 + bj * 128) = e2; }
;             }
.LBB0_327:
	s_or_b64 exec, exec, s[26:27]
	v_or_b32_e32 v96, 48, v216
	s_waitcnt lgkmcnt(0)
	v_ashrrev_i32_e32 v97, 31, v96
	v_lshlrev_b64 v[96:97], 10, v[96:97]
	s_waitcnt vmcnt(14)
	v_cndmask_b32_e64 v98, v137, v141, s[40:41]
	v_cndmask_b32_e64 v99, v136, v140, s[40:41]
	v_mov_b32_e32 v100, v193
	v_mov_b32_e32 v101, v193
	v_lshl_add_u64 v[144:145], v[96:97], 0, v[218:219]
	v_cndmask_b32_e64 v96, v139, v143, s[40:41]
	v_cndmask_b32_e64 v97, v138, v142, s[40:41]
	v_mov_b32_dpp v100, v99 row_ror:8 row_mask:0xf bank_mask:0xf
	v_mov_b32_dpp v101, v98 row_ror:8 row_mask:0xf bank_mask:0xf
	v_mov_b32_e32 v102, v193
	v_mov_b32_e32 v103, v193
	s_mov_b32 s2, 0x90000
	v_mov_b32_dpp v102, v97 row_ror:8 row_mask:0xf bank_mask:0xf
	v_mov_b32_dpp v103, v96 row_ror:8 row_mask:0xf bank_mask:0xf
	v_cndmask_b32_e64 v97, v101, v137, s[40:41]
	v_cndmask_b32_e64 v96, v100, v136, s[40:41]
	v_cndmask_b32_e64 v101, v141, v101, s[40:41]
	v_cndmask_b32_e64 v100, v140, v100, s[40:41]
	v_cndmask_b32_e64 v99, v103, v139, s[40:41]
	v_cndmask_b32_e64 v103, v143, v103, s[40:41]
	v_pk_fma_f32 v[130:131], v[88:89], v[188:189], v[100:101]
	s_waitcnt vmcnt(12)
	v_cndmask_b32_e64 v88, v123, v127, s[40:41]
	v_mov_b32_e32 v143, 0
	v_cndmask_b32_e64 v89, v122, v126, s[40:41]
	v_mov_b32_e32 v141, 0
	v_mov_b32_dpp v143, v88 row_ror:8 row_mask:0xf bank_mask:0xf
	v_add_co_u32_e32 v88, vcc, s2, v220
	v_mov_b32_dpp v141, v89 row_ror:8 row_mask:0xf bank_mask:0xf
	s_nop 0
	v_addc_co_u32_e32 v89, vcc, 0, v221, vcc
	s_mov_b32 s2, 0x98000
	v_cndmask_b32_e64 v98, v102, v138, s[40:41]
	v_cndmask_b32_e64 v102, v142, v102, s[40:41]
	v_pk_fma_f32 v[134:135], v[92:93], v[184:185], v[96:97]
	v_add_co_u32_e32 v92, vcc, s2, v220
	v_pk_fma_f32 v[128:129], v[90:91], v[190:191], v[102:103]
	v_cndmask_b32_e64 v90, v121, v125, s[40:41]
	v_cndmask_b32_e64 v91, v120, v124, s[40:41]
	v_mov_b32_e32 v140, 0
	v_mov_b32_e32 v142, 0
	v_addc_co_u32_e32 v93, vcc, 0, v221, vcc
	v_pk_fma_f32 v[132:133], v[94:95], v[186:187], v[98:99]
	v_mov_b32_dpp v140, v91 row_ror:8 row_mask:0xf bank_mask:0xf
	v_mov_b32_dpp v142, v90 row_ror:8 row_mask:0xf bank_mask:0xf
	global_load_dwordx4 v[96:99], v[88:89], off nt
	global_load_dwordx4 v[100:103], v[92:93], off nt
	s_nop 0
	global_load_dwordx4 v[88:91], v[88:89], off offset:512 nt
	s_nop 0
	global_load_dwordx4 v[92:95], v[92:93], off offset:512 nt
	v_cndmask_b32_e64 v139, v134, v130, s[40:41]
	v_mov_b32_e32 v150, v193
	v_cndmask_b32_e64 v138, v135, v131, s[40:41]
	v_cndmask_b32_e64 v137, v132, v128, s[40:41]
	v_mov_b32_dpp v150, v139 row_ror:8 row_mask:0xf bank_mask:0xf
	v_mov_b32_e32 v139, v193
	v_cndmask_b32_e64 v136, v133, v129, s[40:41]
	v_cndmask_b32_e64 v146, v150, v134, s[40:41]
	v_mov_b32_dpp v139, v138 row_ror:8 row_mask:0xf bank_mask:0xf
	v_mov_b32_e32 v138, v193
	v_cndmask_b32_e64 v147, v139, v135, s[40:41]
	v_cndmask_b32_e64 v151, v131, v139, s[40:41]
	v_mov_b32_dpp v138, v137 row_ror:8 row_mask:0xf bank_mask:0xf
	v_mov_b32_e32 v137, v193
	v_cndmask_b32_e64 v148, v138, v132, s[40:41]
	v_cndmask_b32_e64 v152, v128, v138, s[40:41]
	v_lshl_add_u64 v[138:139], v[144:145], 2, s[82:83]
	v_mov_b32_dpp v137, v136 row_ror:8 row_mask:0xf bank_mask:0xf
	v_add_co_u32_e32 v136, vcc, 0x8000, v138
	v_cndmask_b32_e64 v149, v137, v133, s[40:41]
	v_cndmask_b32_e64 v153, v129, v137, s[40:41]
	v_cndmask_b32_e64 v150, v130, v150, s[40:41]
	v_addc_co_u32_e32 v137, vcc, 0, v139, vcc
	global_store_dwordx4 v[136:137], v[150:153], off nt
	s_and_b64 vcc, exec, s[38:39]
	v_lshl_add_u64 v[136:137], v[144:145], 1, s[8:9]
	global_store_dwordx4 v[138:139], v[146:149], off nt
	s_cbranch_vccnz .LBB0_329
	v_pk_mul_f32 v[144:145], v[54:55], v[132:133]
	v_pk_mul_f32 v[146:147], v[52:53], v[134:135]
	v_pk_mul_f32 v[148:149], v[50:51], v[128:129]
	v_pk_mul_f32 v[150:151], v[48:49], v[130:131]
	v_cvt_pk_bf16_f32 v146, v146, v147
	v_cvt_pk_bf16_f32 v144, v144, v145
	s_nop 0
	v_cvt_pk_bf16_f32 v150, v150, v151
	v_cvt_pk_bf16_f32 v147, v148, v149
	v_mov_b32_e32 v149, v193
	v_cndmask_b32_e64 v148, v146, v150, s[40:41]
	v_cndmask_b32_e64 v145, v144, v147, s[40:41]
	s_nop 0
	v_mov_b32_dpp v149, v148 row_ror:8 row_mask:0xf bank_mask:0xf
	v_mov_b32_e32 v148, v193
	s_nop 1
	v_mov_b32_dpp v148, v145 row_ror:8 row_mask:0xf bank_mask:0xf
	v_cndmask_b32_e64 v145, v148, v144, s[40:41]
	v_cndmask_b32_e64 v144, v149, v146, s[40:41]
	global_store_dwordx2 v[136:137], v[144:145], off
	v_add_co_u32_e32 v144, vcc, 0x4000, v136
	v_cndmask_b32_e64 v147, v147, v148, s[40:41]
	v_cndmask_b32_e64 v146, v150, v149, s[40:41]
	v_addc_co_u32_e32 v145, vcc, 0, v137, vcc
	global_store_dwordx2 v[144:145], v[146:147], off
; __device__ __forceinline__ unsigned cvt_pk_bf16(float lo, float hi) { unsigned r; asm volatile("v_cvt_pk_bf16_f32 %0, %1, %2" : "=v"(r) : "v"(lo), "v"(hi)); return r; }
;     __device__ __forceinline__ void operator()(const f32x4 (&acc)[2][2][4][2], const pg8::Unit& u, int wr, int wc, int fr_, int fq_) const {
;     ...
;         for (int r = 0; r < 8; ++r) {
;             const int ai = r >> 2, m = r & 3;
;             const int grow = grow0 + ai * 128 + m * 16;
;             const size_t mo0 = (size_t)(mrow0 + ai * 128 + m * 16) * D + mcol, mo1 = mo0 + (size_t)8 * D;
;             f32x4 xo[2][2];
; #pragma unroll
;             for (int bj = 0; bj < 2; ++bj) {
;                 const f32x4 L1 = xi[r % RES_DEPTH][bj * 2], L2 = xi[r % RES_DEPTH][bj * 2 + 1];
;                 const f32x4 T = dpp_ror8(hi ? L1 : L2);
;                 const f32x4 x0 = hi ? T : L1, x1 = hi ? L2 : T;
;                 xo[bj][0] = x0 + gv[bj][0] * acc[ai][bj][m][0]; xo[bj][1] = x1 + gv[bj][1] * acc[ai][bj][m][1];
;             }
;             if (r + RES_DEPTH < 8) {
;                 const int r2 = r + RES_DEPTH;
; #pragma unroll
;                 for (int q = 0; q < 4; ++q) xi[r % RES_DEPTH][q] = *(const f32x4*)(rp0 + (size_t)((r2 >> 2) * 128 + (r2 & 3) * 16 + (q & 1) * 8) * D + (q >> 1) * 128);
;             }
;             float ss = 0.f;
; #pragma unroll
;             for (int bj = 0; bj < 2; ++bj) {
;                 const f32x4 a0 = xo[bj][0], a1 = xo[bj][1];
;                 ss += ((a0[0] * a0[0] + a0[1] * a0[1]) + (a0[2] * a0[2] + a0[3] * a0[3])) + ((a1[0] * a1[0] + a1[1] * a1[1]) + (a1[2] * a1[2] + a1[3] * a1[3]));
;                 const f32x4 T2 = dpp_ror8(hi ? a0 : a1);
;                 const f32x4 d1 = hi ? T2 : a0, d2 = hi ? a1 : T2;
;                 *(f32x4*)(out + mo0 + bj * 128) = d1; *(f32x4*)(out + mo1 + bj * 128) = d2;
;                 if (gm) { const f32x4 o0 = a0 * mv[bj][0], o1 = a1 * mv[bj][1];
;                     u32x2 w0, w1; w0.x = cvt_pk_bf16(o0[0], o0[1]); w0.y = cvt_pk_bf16(o0[2], o0[3]); w1.x = cvt_pk_bf16(o1[0], o1[1]); w1.y = cvt_pk_bf16(o1[2], o1[3]);
;                     const u32x2 T3 = dpp_ror8(hi ? w0 : w1);
;                     const u32x2 e1 = hi ? T3 : w0, e2 = hi ? w1 : T3;
;                     *(u32x2*)(xg + mo0 + bj * 128) = e1; *(u32x2*)(xg + mo1 + bj * 128) = e2; }
.LBB0_329:
	v_cndmask_b32_e64 v121, v142, v121, s[40:41]
	v_cndmask_b32_e64 v120, v140, v120, s[40:41]
	v_cndmask_b32_e64 v123, v143, v123, s[40:41]
	v_cndmask_b32_e64 v122, v141, v122, s[40:41]
	v_cndmask_b32_e64 v125, v125, v142, s[40:41]
	v_cndmask_b32_e64 v124, v124, v140, s[40:41]
	v_cndmask_b32_e64 v127, v127, v143, s[40:41]
	v_cndmask_b32_e64 v126, v126, v141, s[40:41]
	v_pk_fma_f32 v[86:87], v[86:87], v[178:179], v[122:123]
	v_pk_fma_f32 v[84:85], v[84:85], v[176:177], v[120:121]
	v_pk_fma_f32 v[82:83], v[82:83], v[182:183], v[126:127]
	v_pk_fma_f32 v[80:81], v[80:81], v[180:181], v[124:125]
	v_cndmask_b32_e64 v120, v87, v83, s[40:41]
	v_cndmask_b32_e64 v121, v86, v82, s[40:41]
	v_cndmask_b32_e64 v122, v85, v81, s[40:41]
	v_cndmask_b32_e64 v123, v84, v80, s[40:41]
	v_mov_b32_e32 v124, v193
	v_mov_b32_e32 v125, v193
	v_mov_b32_e32 v126, v193
	v_mov_b32_e32 v127, v193
	v_mov_b32_dpp v124, v123 row_ror:8 row_mask:0xf bank_mask:0xf
	v_mov_b32_dpp v125, v122 row_ror:8 row_mask:0xf bank_mask:0xf
	v_mov_b32_dpp v126, v121 row_ror:8 row_mask:0xf bank_mask:0xf
	v_mov_b32_dpp v127, v120 row_ror:8 row_mask:0xf bank_mask:0xf
	v_lshl_add_u64 v[144:145], v[138:139], 0, s[60:61]
	v_cndmask_b32_e64 v123, v127, v87, s[40:41]
	v_cndmask_b32_e64 v122, v126, v86, s[40:41]
	v_cndmask_b32_e64 v121, v125, v85, s[40:41]
	v_cndmask_b32_e64 v120, v124, v84, s[40:41]
	v_cndmask_b32_e64 v127, v83, v127, s[40:41]
	v_cndmask_b32_e64 v126, v82, v126, s[40:41]
	v_cndmask_b32_e64 v125, v81, v125, s[40:41]
	v_cndmask_b32_e64 v124, v80, v124, s[40:41]
	s_and_b64 vcc, exec, s[38:39]
	global_store_dwordx4 v[138:139], v[120:123], off offset:512 nt
	global_store_dwordx4 v[144:145], v[124:127], off offset:512 nt
	s_cbranch_vccnz .LBB0_331
	v_pk_mul_f32 v[120:121], v[46:47], v[86:87]
	v_pk_mul_f32 v[122:123], v[44:45], v[84:85]
	v_pk_mul_f32 v[124:125], v[42:43], v[82:83]
	v_pk_mul_f32 v[126:127], v[40:41], v[80:81]
	v_cvt_pk_bf16_f32 v122, v122, v123
	v_cvt_pk_bf16_f32 v120, v120, v121
	s_nop 0
	v_cvt_pk_bf16_f32 v126, v126, v127
	v_cvt_pk_bf16_f32 v123, v124, v125
	v_mov_b32_e32 v125, v193
	v_cndmask_b32_e64 v124, v122, v126, s[40:41]
	v_cndmask_b32_e64 v121, v120, v123, s[40:41]
	s_nop 0
	v_mov_b32_dpp v125, v124 row_ror:8 row_mask:0xf bank_mask:0xf
	v_mov_b32_e32 v124, v193
	s_nop 1
	v_mov_b32_dpp v124, v121 row_ror:8 row_mask:0xf bank_mask:0xf
	v_cndmask_b32_e64 v121, v124, v120, s[40:41]
	v_cndmask_b32_e64 v120, v125, v122, s[40:41]
	global_store_dwordx2 v[136:137], v[120:121], off offset:256
	v_add_co_u32_e32 v120, vcc, 0x4000, v136
	v_cndmask_b32_e64 v123, v123, v124, s[40:41]
	v_cndmask_b32_e64 v122, v126, v125, s[40:41]
	v_addc_co_u32_e32 v121, vcc, 0, v137, vcc
	global_store_dwordx2 v[120:121], v[122:123], off offset:256

; __device__ __forceinline__ unsigned cvt_pk_bf16(float lo, float hi) { unsigned r; asm volatile("v_cvt_pk_bf16_f32 %0, %1, %2" : "=v"(r) : "v"(lo), "v"(hi)); return r; }
;     __device__ __forceinline__ void operator()(const f32x4 (&acc)[2][2][4][2], const pg8::Unit& u, int wr, int wc, int fr_, int fq_) const {
;     ...
;         for (int r = 0; r < 8; ++r) {
;             const int ai = r >> 2, m = r & 3;
;             const int grow = grow0 + ai * 128 + m * 16;
;             const size_t mo0 = (size_t)(mrow0 + ai * 128 + m * 16) * D + mcol, mo1 = mo0 + (size_t)8 * D;
;             f32x4 xo[2][2];
; #pragma unroll
;             for (int bj = 0; bj < 2; ++bj) {
;                 const f32x4 L1 = xi[r % RES_DEPTH][bj * 2], L2 = xi[r % RES_DEPTH][bj * 2 + 1];
;                 const f32x4 T = dpp_ror8(hi ? L1 : L2);
;                 const f32x4 x0 = hi ? T : L1, x1 = hi ? L2 : T;
;                 xo[bj][0] = x0 + gv[bj][0] * acc[ai][bj][m][0]; xo[bj][1] = x1 + gv[bj][1] * acc[ai][bj][m][1];
;             }
;             if (r + RES_DEPTH < 8) {
;                 const int r2 = r + RES_DEPTH;
; #pragma unroll
;                 for (int q = 0; q < 4; ++q) xi[r % RES_DEPTH][q] = *(const f32x4*)(rp0 + (size_t)((r2 >> 2) * 128 + (r2 & 3) * 16 + (q & 1) * 8) * D + (q >> 1) * 128);
;             }
;             float ss = 0.f;
; #pragma unroll
;             for (int bj = 0; bj < 2; ++bj) {
;                 const f32x4 a0 = xo[bj][0], a1 = xo[bj][1];
;                 ss += ((a0[0] * a0[0] + a0[1] * a0[1]) + (a0[2] * a0[2] + a0[3] * a0[3])) + ((a1[0] * a1[0] + a1[1] * a1[1]) + (a1[2] * a1[2] + a1[3] * a1[3]));
;                 const f32x4 T2 = dpp_ror8(hi ? a0 : a1);
;                 const f32x4 d1 = hi ? T2 : a0, d2 = hi ? a1 : T2;
;                 *(f32x4*)(out + mo0 + bj * 128) = d1; *(f32x4*)(out + mo1 + bj * 128) = d2;
;                 if (gm) { const f32x4 o0 = a0 * mv[bj][0], o1 = a1 * mv[bj][1];
;                     u32x2 w0, w1; w0.x = cvt_pk_bf16(o0[0], o0[1]); w0.y = cvt_pk_bf16(o0[2], o0[3]); w1.x = cvt_pk_bf16(o1[0], o1[1]); w1.y = cvt_pk_bf16(o1[2], o1[3]);
;                     const u32x2 T3 = dpp_ror8(hi ? w0 : w1);
;                     const u32x2 e1 = hi ? T3 : w0, e2 = hi ? w1 : T3;
;                     *(u32x2*)(xg + mo0 + bj * 128) = e1; *(u32x2*)(xg + mo1 + bj * 128) = e2; }
;             }
.LBB0_333:
	s_or_b64 exec, exec, s[26:27]
	v_add_u32_e32 v80, 0x80, v216
	s_waitcnt lgkmcnt(0)
	v_ashrrev_i32_e32 v81, 31, v80
	v_lshlrev_b64 v[80:81], 10, v[80:81]
	s_waitcnt vmcnt(14)
	v_cndmask_b32_e64 v82, v113, v117, s[40:41]
	v_cndmask_b32_e64 v83, v112, v116, s[40:41]
	v_mov_b32_e32 v84, v193
	v_mov_b32_e32 v85, v193
	v_lshl_add_u64 v[120:121], v[80:81], 0, v[218:219]
	v_cndmask_b32_e64 v80, v115, v119, s[40:41]
	v_cndmask_b32_e64 v81, v114, v118, s[40:41]
	v_mov_b32_dpp v84, v83 row_ror:8 row_mask:0xf bank_mask:0xf
	v_mov_b32_dpp v85, v82 row_ror:8 row_mask:0xf bank_mask:0xf
	v_mov_b32_e32 v86, v193
	v_mov_b32_e32 v87, v193
	v_mov_b32_e32 v127, 0
	v_mov_b32_dpp v86, v81 row_ror:8 row_mask:0xf bank_mask:0xf
	v_mov_b32_dpp v87, v80 row_ror:8 row_mask:0xf bank_mask:0xf
	v_cndmask_b32_e64 v81, v85, v113, s[40:41]
	v_cndmask_b32_e64 v80, v84, v112, s[40:41]
	v_cndmask_b32_e64 v85, v117, v85, s[40:41]
	v_cndmask_b32_e64 v84, v116, v84, s[40:41]
	v_cndmask_b32_e64 v83, v87, v115, s[40:41]
	v_cndmask_b32_e64 v82, v86, v114, s[40:41]
	v_pk_fma_f32 v[114:115], v[72:73], v[188:189], v[84:85]
	s_waitcnt vmcnt(12)
	v_cndmask_b32_e64 v72, v107, v111, s[40:41]
	s_mov_b32 s2, 0xa0000
	v_cndmask_b32_e64 v73, v106, v110, s[40:41]
	v_mov_b32_e32 v125, 0
	v_mov_b32_dpp v127, v72 row_ror:8 row_mask:0xf bank_mask:0xf
	v_add_co_u32_e32 v72, vcc, s2, v220
	v_mov_b32_dpp v125, v73 row_ror:8 row_mask:0xf bank_mask:0xf
	s_nop 0
	v_addc_co_u32_e32 v73, vcc, 0, v221, vcc
	s_mov_b32 s2, 0xa8000
	v_cndmask_b32_e64 v87, v119, v87, s[40:41]
	v_cndmask_b32_e64 v86, v118, v86, s[40:41]
	v_pk_fma_f32 v[118:119], v[76:77], v[184:185], v[80:81]
	v_add_co_u32_e32 v76, vcc, s2, v220
	v_pk_fma_f32 v[112:113], v[74:75], v[190:191], v[86:87]
	v_cndmask_b32_e64 v74, v105, v109, s[40:41]
	v_cndmask_b32_e64 v75, v104, v108, s[40:41]
	v_mov_b32_e32 v124, 0
	v_mov_b32_e32 v126, 0
	v_addc_co_u32_e32 v77, vcc, 0, v221, vcc
	v_pk_fma_f32 v[116:117], v[78:79], v[186:187], v[82:83]
	v_mov_b32_dpp v124, v75 row_ror:8 row_mask:0xf bank_mask:0xf
	v_mov_b32_dpp v126, v74 row_ror:8 row_mask:0xf bank_mask:0xf
	global_load_dwordx4 v[80:83], v[72:73], off nt
	global_load_dwordx4 v[84:87], v[76:77], off nt
	s_nop 0
	global_load_dwordx4 v[72:75], v[72:73], off offset:512 nt
	s_nop 0
	global_load_dwordx4 v[76:79], v[76:77], off offset:512 nt
	v_cndmask_b32_e64 v123, v116, v112, s[40:41]
	v_mov_b32_e32 v134, v193
	v_cndmask_b32_e64 v122, v117, v113, s[40:41]
	v_cndmask_b32_e64 v128, v119, v115, s[40:41]
	v_cndmask_b32_e64 v129, v118, v114, s[40:41]
	v_mov_b32_e32 v132, v193
	v_mov_b32_e32 v133, v193
	v_mov_b32_dpp v134, v123 row_ror:8 row_mask:0xf bank_mask:0xf
	v_mov_b32_e32 v123, v193
	v_mov_b32_dpp v132, v129 row_ror:8 row_mask:0xf bank_mask:0xf
	v_mov_b32_dpp v133, v128 row_ror:8 row_mask:0xf bank_mask:0xf
	v_mov_b32_dpp v123, v122 row_ror:8 row_mask:0xf bank_mask:0xf
	v_cndmask_b32_e64 v131, v123, v117, s[40:41]
	v_cndmask_b32_e64 v130, v134, v116, s[40:41]
	v_cndmask_b32_e64 v129, v133, v119, s[40:41]
	v_cndmask_b32_e64 v128, v132, v118, s[40:41]
	v_cndmask_b32_e64 v135, v113, v123, s[40:41]
	v_lshl_add_u64 v[122:123], v[120:121], 2, s[82:83]
	global_store_dwordx4 v[122:123], v[128:131], off nt
	v_cndmask_b32_e64 v134, v112, v134, s[40:41]
	v_cndmask_b32_e64 v133, v115, v133, s[40:41]
	v_add_co_u32_e32 v128, vcc, 0x8000, v122
	v_cndmask_b32_e64 v132, v114, v132, s[40:41]
	s_nop 0
	v_addc_co_u32_e32 v129, vcc, 0, v123, vcc
	s_and_b64 vcc, exec, s[38:39]
	v_lshl_add_u64 v[120:121], v[120:121], 1, s[8:9]
	global_store_dwordx4 v[128:129], v[132:135], off nt
	s_cbranch_vccnz .LBB0_335
	v_pk_mul_f32 v[128:129], v[54:55], v[116:117]
	v_pk_mul_f32 v[130:131], v[52:53], v[118:119]
	v_pk_mul_f32 v[132:133], v[50:51], v[112:113]
	v_pk_mul_f32 v[134:135], v[48:49], v[114:115]
	v_cvt_pk_bf16_f32 v130, v130, v131
	v_cvt_pk_bf16_f32 v128, v128, v129
	s_nop 0
	v_cvt_pk_bf16_f32 v134, v134, v135
	v_cvt_pk_bf16_f32 v131, v132, v133
	v_mov_b32_e32 v133, v193
	v_cndmask_b32_e64 v132, v130, v134, s[40:41]
	v_cndmask_b32_e64 v129, v128, v131, s[40:41]
	s_nop 0
	v_mov_b32_dpp v133, v132 row_ror:8 row_mask:0xf bank_mask:0xf
	v_mov_b32_e32 v132, v193
	s_nop 1
	v_mov_b32_dpp v132, v129 row_ror:8 row_mask:0xf bank_mask:0xf
	v_cndmask_b32_e64 v129, v132, v128, s[40:41]
	v_cndmask_b32_e64 v128, v133, v130, s[40:41]
	global_store_dwordx2 v[120:121], v[128:129], off
	v_add_co_u32_e32 v128, vcc, 0x4000, v120
	v_cndmask_b32_e64 v131, v131, v132, s[40:41]
	v_cndmask_b32_e64 v130, v134, v133, s[40:41]
	v_addc_co_u32_e32 v129, vcc, 0, v121, vcc
	global_store_dwordx2 v[128:129], v[130:131], off
; __device__ __forceinline__ unsigned cvt_pk_bf16(float lo, float hi) { unsigned r; asm volatile("v_cvt_pk_bf16_f32 %0, %1, %2" : "=v"(r) : "v"(lo), "v"(hi)); return r; }
;     __device__ __forceinline__ void operator()(const f32x4 (&acc)[2][2][4][2], const pg8::Unit& u, int wr, int wc, int fr_, int fq_) const {
;     ...
;         for (int r = 0; r < 8; ++r) {
;             const int ai = r >> 2, m = r & 3;
;             const int grow = grow0 + ai * 128 + m * 16;
;             const size_t mo0 = (size_t)(mrow0 + ai * 128 + m * 16) * D + mcol, mo1 = mo0 + (size_t)8 * D;
;             f32x4 xo[2][2];
; #pragma unroll
;             for (int bj = 0; bj < 2; ++bj) {
;                 const f32x4 L1 = xi[r % RES_DEPTH][bj * 2], L2 = xi[r % RES_DEPTH][bj * 2 + 1];
;                 const f32x4 T = dpp_ror8(hi ? L1 : L2);
;                 const f32x4 x0 = hi ? T : L1, x1 = hi ? L2 : T;
;                 xo[bj][0] = x0 + gv[bj][0] * acc[ai][bj][m][0]; xo[bj][1] = x1 + gv[bj][1] * acc[ai][bj][m][1];
;             }
;             if (r + RES_DEPTH < 8) {
;                 const int r2 = r + RES_DEPTH;
; #pragma unroll
;                 for (int q = 0; q < 4; ++q) xi[r % RES_DEPTH][q] = *(const f32x4*)(rp0 + (size_t)((r2 >> 2) * 128 + (r2 & 3) * 16 + (q & 1) * 8) * D + (q >> 1) * 128);
;             }
;             float ss = 0.f;
; #pragma unroll
;             for (int bj = 0; bj < 2; ++bj) {
;                 const f32x4 a0 = xo[bj][0], a1 = xo[bj][1];
;                 ss += ((a0[0] * a0[0] + a0[1] * a0[1]) + (a0[2] * a0[2] + a0[3] * a0[3])) + ((a1[0] * a1[0] + a1[1] * a1[1]) + (a1[2] * a1[2] + a1[3] * a1[3]));
;                 const f32x4 T2 = dpp_ror8(hi ? a0 : a1);
;                 const f32x4 d1 = hi ? T2 : a0, d2 = hi ? a1 : T2;
;                 *(f32x4*)(out + mo0 + bj * 128) = d1; *(f32x4*)(out + mo1 + bj * 128) = d2;
;                 if (gm) { const f32x4 o0 = a0 * mv[bj][0], o1 = a1 * mv[bj][1];
;                     u32x2 w0, w1; w0.x = cvt_pk_bf16(o0[0], o0[1]); w0.y = cvt_pk_bf16(o0[2], o0[3]); w1.x = cvt_pk_bf16(o1[0], o1[1]); w1.y = cvt_pk_bf16(o1[2], o1[3]);
;                     const u32x2 T3 = dpp_ror8(hi ? w0 : w1);
;                     const u32x2 e1 = hi ? T3 : w0, e2 = hi ? w1 : T3;
;                     *(u32x2*)(xg + mo0 + bj * 128) = e1; *(u32x2*)(xg + mo1 + bj * 128) = e2; }
.LBB0_335:
	v_cndmask_b32_e64 v105, v126, v105, s[40:41]
	v_cndmask_b32_e64 v104, v124, v104, s[40:41]
	v_cndmask_b32_e64 v107, v127, v107, s[40:41]
	v_cndmask_b32_e64 v106, v125, v106, s[40:41]
	v_cndmask_b32_e64 v109, v109, v126, s[40:41]
	v_cndmask_b32_e64 v108, v108, v124, s[40:41]
	v_cndmask_b32_e64 v111, v111, v127, s[40:41]
	v_cndmask_b32_e64 v110, v110, v125, s[40:41]
	v_pk_fma_f32 v[70:71], v[70:71], v[178:179], v[106:107]
	v_pk_fma_f32 v[68:69], v[68:69], v[176:177], v[104:105]
	v_pk_fma_f32 v[66:67], v[66:67], v[182:183], v[110:111]
	v_pk_fma_f32 v[64:65], v[64:65], v[180:181], v[108:109]
	v_cndmask_b32_e64 v104, v71, v67, s[40:41]
	v_cndmask_b32_e64 v105, v70, v66, s[40:41]
	v_cndmask_b32_e64 v106, v69, v65, s[40:41]
	v_cndmask_b32_e64 v107, v68, v64, s[40:41]
	v_mov_b32_e32 v108, v193
	v_mov_b32_e32 v109, v193
	v_mov_b32_e32 v110, v193
	v_mov_b32_e32 v111, v193
	v_mov_b32_dpp v108, v107 row_ror:8 row_mask:0xf bank_mask:0xf
	v_mov_b32_dpp v109, v106 row_ror:8 row_mask:0xf bank_mask:0xf
	v_mov_b32_dpp v110, v105 row_ror:8 row_mask:0xf bank_mask:0xf
	v_mov_b32_dpp v111, v104 row_ror:8 row_mask:0xf bank_mask:0xf
	v_lshl_add_u64 v[128:129], v[122:123], 0, s[60:61]
	v_cndmask_b32_e64 v107, v111, v71, s[40:41]
	v_cndmask_b32_e64 v106, v110, v70, s[40:41]
	v_cndmask_b32_e64 v105, v109, v69, s[40:41]
	v_cndmask_b32_e64 v104, v108, v68, s[40:41]
	v_cndmask_b32_e64 v111, v67, v111, s[40:41]
	v_cndmask_b32_e64 v110, v66, v110, s[40:41]
	v_cndmask_b32_e64 v109, v65, v109, s[40:41]
	v_cndmask_b32_e64 v108, v64, v108, s[40:41]
	s_and_b64 vcc, exec, s[38:39]
	global_store_dwordx4 v[122:123], v[104:107], off offset:512 nt
	global_store_dwordx4 v[128:129], v[108:111], off offset:512 nt
	s_cbranch_vccnz .LBB0_337
	v_pk_mul_f32 v[104:105], v[46:47], v[70:71]
	v_pk_mul_f32 v[106:107], v[44:45], v[68:69]
	v_pk_mul_f32 v[108:109], v[42:43], v[66:67]
	v_pk_mul_f32 v[110:111], v[40:41], v[64:65]
	v_cvt_pk_bf16_f32 v106, v106, v107
	v_cvt_pk_bf16_f32 v104, v104, v105
	s_nop 0
	v_cvt_pk_bf16_f32 v110, v110, v111
	v_cvt_pk_bf16_f32 v107, v108, v109
	v_mov_b32_e32 v109, v193
	v_cndmask_b32_e64 v108, v106, v110, s[40:41]
	v_cndmask_b32_e64 v105, v104, v107, s[40:41]
	s_nop 0
	v_mov_b32_dpp v109, v108 row_ror:8 row_mask:0xf bank_mask:0xf
	v_mov_b32_e32 v108, v193
	s_nop 1
	v_mov_b32_dpp v108, v105 row_ror:8 row_mask:0xf bank_mask:0xf
	v_cndmask_b32_e64 v105, v108, v104, s[40:41]
	v_cndmask_b32_e64 v104, v109, v106, s[40:41]
	global_store_dwordx2 v[120:121], v[104:105], off offset:256
	v_add_co_u32_e32 v104, vcc, 0x4000, v120
	v_cndmask_b32_e64 v107, v107, v108, s[40:41]
	v_cndmask_b32_e64 v106, v110, v109, s[40:41]
	v_addc_co_u32_e32 v105, vcc, 0, v121, vcc
	global_store_dwordx2 v[104:105], v[106:107], off offset:256

; __device__ __forceinline__ unsigned cvt_pk_bf16(float lo, float hi) { unsigned r; asm volatile("v_cvt_pk_bf16_f32 %0, %1, %2" : "=v"(r) : "v"(lo), "v"(hi)); return r; }
;     __device__ __forceinline__ void operator()(const f32x4 (&acc)[2][2][4][2], const pg8::Unit& u, int wr, int wc, int fr_, int fq_) const {
;     ...
;         for (int r = 0; r < 8; ++r) {
;             const int ai = r >> 2, m = r & 3;
;             const int grow = grow0 + ai * 128 + m * 16;
;             const size_t mo0 = (size_t)(mrow0 + ai * 128 + m * 16) * D + mcol, mo1 = mo0 + (size_t)8 * D;
;             f32x4 xo[2][2];
; #pragma unroll
;             for (int bj = 0; bj < 2; ++bj) {
;                 const f32x4 L1 = xi[r % RES_DEPTH][bj * 2], L2 = xi[r % RES_DEPTH][bj * 2 + 1];
;                 const f32x4 T = dpp_ror8(hi ? L1 : L2);
;                 const f32x4 x0 = hi ? T : L1, x1 = hi ? L2 : T;
;                 xo[bj][0] = x0 + gv[bj][0] * acc[ai][bj][m][0]; xo[bj][1] = x1 + gv[bj][1] * acc[ai][bj][m][1];
;             }
;             if (r + RES_DEPTH < 8) {
;                 const int r2 = r + RES_DEPTH;
; #pragma unroll
;                 for (int q = 0; q < 4; ++q) xi[r % RES_DEPTH][q] = *(const f32x4*)(rp0 + (size_t)((r2 >> 2) * 128 + (r2 & 3) * 16 + (q & 1) * 8) * D + (q >> 1) * 128);
;             }
;             float ss = 0.f;
; #pragma unroll
;             for (int bj = 0; bj < 2; ++bj) {
;                 const f32x4 a0 = xo[bj][0], a1 = xo[bj][1];
;                 ss += ((a0[0] * a0[0] + a0[1] * a0[1]) + (a0[2] * a0[2] + a0[3] * a0[3])) + ((a1[0] * a1[0] + a1[1] * a1[1]) + (a1[2] * a1[2] + a1[3] * a1[3]));
;                 const f32x4 T2 = dpp_ror8(hi ? a0 : a1);
;                 const f32x4 d1 = hi ? T2 : a0, d2 = hi ? a1 : T2;
;                 *(f32x4*)(out + mo0 + bj * 128) = d1; *(f32x4*)(out + mo1 + bj * 128) = d2;
;                 if (gm) { const f32x4 o0 = a0 * mv[bj][0], o1 = a1 * mv[bj][1];
;                     u32x2 w0, w1; w0.x = cvt_pk_bf16(o0[0], o0[1]); w0.y = cvt_pk_bf16(o0[2], o0[3]); w1.x = cvt_pk_bf16(o1[0], o1[1]); w1.y = cvt_pk_bf16(o1[2], o1[3]);
;                     const u32x2 T3 = dpp_ror8(hi ? w0 : w1);
;                     const u32x2 e1 = hi ? T3 : w0, e2 = hi ? w1 : T3;
;                     *(u32x2*)(xg + mo0 + bj * 128) = e1; *(u32x2*)(xg + mo1 + bj * 128) = e2; }
;             }
.LBB0_339:
	s_or_b64 exec, exec, s[26:27]
	v_add_u32_e32 v64, 0x90, v216
	s_waitcnt lgkmcnt(0)
	v_ashrrev_i32_e32 v65, 31, v64
	v_lshlrev_b64 v[64:65], 10, v[64:65]
	s_waitcnt vmcnt(14)
	v_cndmask_b32_e64 v66, v97, v101, s[40:41]
	v_cndmask_b32_e64 v67, v96, v100, s[40:41]
	v_mov_b32_e32 v68, v193
	v_mov_b32_e32 v69, v193
	v_lshl_add_u64 v[104:105], v[64:65], 0, v[218:219]
	v_cndmask_b32_e64 v64, v99, v103, s[40:41]
	v_cndmask_b32_e64 v65, v98, v102, s[40:41]
	v_mov_b32_dpp v68, v67 row_ror:8 row_mask:0xf bank_mask:0xf
	v_mov_b32_dpp v69, v66 row_ror:8 row_mask:0xf bank_mask:0xf
	v_mov_b32_e32 v70, v193
	v_mov_b32_e32 v71, v193
	v_mov_b32_e32 v111, 0
	v_mov_b32_dpp v70, v65 row_ror:8 row_mask:0xf bank_mask:0xf
	v_mov_b32_dpp v71, v64 row_ror:8 row_mask:0xf bank_mask:0xf
	v_cndmask_b32_e64 v65, v69, v97, s[40:41]
	v_cndmask_b32_e64 v64, v68, v96, s[40:41]
	v_cndmask_b32_e64 v69, v101, v69, s[40:41]
	v_cndmask_b32_e64 v68, v100, v68, s[40:41]
	v_cndmask_b32_e64 v67, v71, v99, s[40:41]
	v_cndmask_b32_e64 v66, v70, v98, s[40:41]
	v_pk_fma_f32 v[98:99], v[56:57], v[188:189], v[68:69]
	s_waitcnt vmcnt(12)
	v_cndmask_b32_e64 v56, v91, v95, s[40:41]
	s_mov_b32 s2, 0xb0000
	v_cndmask_b32_e64 v57, v90, v94, s[40:41]
	v_mov_b32_e32 v109, 0
	v_mov_b32_dpp v111, v56 row_ror:8 row_mask:0xf bank_mask:0xf
	v_add_co_u32_e32 v56, vcc, s2, v220
	v_mov_b32_dpp v109, v57 row_ror:8 row_mask:0xf bank_mask:0xf
	s_nop 0
	v_addc_co_u32_e32 v57, vcc, 0, v221, vcc
	s_mov_b32 s2, 0xb8000
	v_cndmask_b32_e64 v71, v103, v71, s[40:41]
	v_cndmask_b32_e64 v70, v102, v70, s[40:41]
	v_pk_fma_f32 v[102:103], v[60:61], v[184:185], v[64:65]
	v_add_co_u32_e32 v60, vcc, s2, v220
	v_pk_fma_f32 v[96:97], v[58:59], v[190:191], v[70:71]
	v_cndmask_b32_e64 v58, v89, v93, s[40:41]
	v_cndmask_b32_e64 v59, v88, v92, s[40:41]
	v_mov_b32_e32 v108, 0
	v_mov_b32_e32 v110, 0
	v_addc_co_u32_e32 v61, vcc, 0, v221, vcc
	v_pk_fma_f32 v[100:101], v[62:63], v[186:187], v[66:67]
	v_mov_b32_dpp v108, v59 row_ror:8 row_mask:0xf bank_mask:0xf
	v_mov_b32_dpp v110, v58 row_ror:8 row_mask:0xf bank_mask:0xf
	global_load_dwordx4 v[64:67], v[56:57], off nt
	global_load_dwordx4 v[68:71], v[60:61], off nt
	s_nop 0
	global_load_dwordx4 v[56:59], v[56:57], off offset:512 nt
	s_nop 0
	global_load_dwordx4 v[60:63], v[60:61], off offset:512 nt
	v_cndmask_b32_e64 v107, v100, v96, s[40:41]
	v_mov_b32_e32 v118, v193
	v_cndmask_b32_e64 v106, v101, v97, s[40:41]
	v_cndmask_b32_e64 v112, v103, v99, s[40:41]
	v_cndmask_b32_e64 v113, v102, v98, s[40:41]
	v_mov_b32_e32 v116, v193
	v_mov_b32_e32 v117, v193
	v_mov_b32_dpp v118, v107 row_ror:8 row_mask:0xf bank_mask:0xf
	v_mov_b32_e32 v107, v193
	v_mov_b32_dpp v116, v113 row_ror:8 row_mask:0xf bank_mask:0xf
	v_mov_b32_dpp v117, v112 row_ror:8 row_mask:0xf bank_mask:0xf
	v_mov_b32_dpp v107, v106 row_ror:8 row_mask:0xf bank_mask:0xf
	v_cndmask_b32_e64 v115, v107, v101, s[40:41]
	v_cndmask_b32_e64 v114, v118, v100, s[40:41]
	v_cndmask_b32_e64 v113, v117, v103, s[40:41]
	v_cndmask_b32_e64 v112, v116, v102, s[40:41]
	v_cndmask_b32_e64 v119, v97, v107, s[40:41]
	v_lshl_add_u64 v[106:107], v[104:105], 2, s[82:83]
	global_store_dwordx4 v[106:107], v[112:115], off nt
	v_cndmask_b32_e64 v118, v96, v118, s[40:41]
	v_cndmask_b32_e64 v117, v99, v117, s[40:41]
	v_add_co_u32_e32 v112, vcc, 0x8000, v106
	v_cndmask_b32_e64 v116, v98, v116, s[40:41]
	s_nop 0
	v_addc_co_u32_e32 v113, vcc, 0, v107, vcc
	s_and_b64 vcc, exec, s[38:39]
	v_lshl_add_u64 v[104:105], v[104:105], 1, s[8:9]
	global_store_dwordx4 v[112:113], v[116:119], off nt
	s_cbranch_vccnz .LBB0_341
	v_pk_mul_f32 v[112:113], v[54:55], v[100:101]
	v_pk_mul_f32 v[114:115], v[52:53], v[102:103]
	v_pk_mul_f32 v[116:117], v[50:51], v[96:97]
	v_pk_mul_f32 v[118:119], v[48:49], v[98:99]
	v_cvt_pk_bf16_f32 v114, v114, v115
	v_cvt_pk_bf16_f32 v112, v112, v113
	s_nop 0
	v_cvt_pk_bf16_f32 v118, v118, v119
	v_cvt_pk_bf16_f32 v115, v116, v117
	v_mov_b32_e32 v117, v193
	v_cndmask_b32_e64 v116, v114, v118, s[40:41]
	v_cndmask_b32_e64 v113, v112, v115, s[40:41]
	s_nop 0
	v_mov_b32_dpp v117, v116 row_ror:8 row_mask:0xf bank_mask:0xf
	v_mov_b32_e32 v116, v193
	s_nop 1
	v_mov_b32_dpp v116, v113 row_ror:8 row_mask:0xf bank_mask:0xf
	v_cndmask_b32_e64 v113, v116, v112, s[40:41]
	v_cndmask_b32_e64 v112, v117, v114, s[40:41]
	global_store_dwordx2 v[104:105], v[112:113], off
	v_add_co_u32_e32 v112, vcc, 0x4000, v104
	v_cndmask_b32_e64 v115, v115, v116, s[40:41]
	v_cndmask_b32_e64 v114, v118, v117, s[40:41]
	v_addc_co_u32_e32 v113, vcc, 0, v105, vcc
	global_store_dwordx2 v[112:113], v[114:115], off
; __device__ __forceinline__ unsigned cvt_pk_bf16(float lo, float hi) { unsigned r; asm volatile("v_cvt_pk_bf16_f32 %0, %1, %2" : "=v"(r) : "v"(lo), "v"(hi)); return r; }
;     __device__ __forceinline__ void operator()(const f32x4 (&acc)[2][2][4][2], const pg8::Unit& u, int wr, int wc, int fr_, int fq_) const {
;     ...
;         for (int r = 0; r < 8; ++r) {
;             const int ai = r >> 2, m = r & 3;
;             const int grow = grow0 + ai * 128 + m * 16;
;             const size_t mo0 = (size_t)(mrow0 + ai * 128 + m * 16) * D + mcol, mo1 = mo0 + (size_t)8 * D;
;             f32x4 xo[2][2];
; #pragma unroll
;             for (int bj = 0; bj < 2; ++bj) {
;                 const f32x4 L1 = xi[r % RES_DEPTH][bj * 2], L2 = xi[r % RES_DEPTH][bj * 2 + 1];
;                 const f32x4 T = dpp_ror8(hi ? L1 : L2);
;                 const f32x4 x0 = hi ? T : L1, x1 = hi ? L2 : T;
;                 xo[bj][0] = x0 + gv[bj][0] * acc[ai][bj][m][0]; xo[bj][1] = x1 + gv[bj][1] * acc[ai][bj][m][1];
;             }
;             if (r + RES_DEPTH < 8) {
;                 const int r2 = r + RES_DEPTH;
; #pragma unroll
;                 for (int q = 0; q < 4; ++q) xi[r % RES_DEPTH][q] = *(const f32x4*)(rp0 + (size_t)((r2 >> 2) * 128 + (r2 & 3) * 16 + (q & 1) * 8) * D + (q >> 1) * 128);
;             }
;             float ss = 0.f;
; #pragma unroll
;             for (int bj = 0; bj < 2; ++bj) {
;                 const f32x4 a0 = xo[bj][0], a1 = xo[bj][1];
;                 ss += ((a0[0] * a0[0] + a0[1] * a0[1]) + (a0[2] * a0[2] + a0[3] * a0[3])) + ((a1[0] * a1[0] + a1[1] * a1[1]) + (a1[2] * a1[2] + a1[3] * a1[3]));
;                 const f32x4 T2 = dpp_ror8(hi ? a0 : a1);
;                 const f32x4 d1 = hi ? T2 : a0, d2 = hi ? a1 : T2;
;                 *(f32x4*)(out + mo0 + bj * 128) = d1; *(f32x4*)(out + mo1 + bj * 128) = d2;
;                 if (gm) { const f32x4 o0 = a0 * mv[bj][0], o1 = a1 * mv[bj][1];
;                     u32x2 w0, w1; w0.x = cvt_pk_bf16(o0[0], o0[1]); w0.y = cvt_pk_bf16(o0[2], o0[3]); w1.x = cvt_pk_bf16(o1[0], o1[1]); w1.y = cvt_pk_bf16(o1[2], o1[3]);
;                     const u32x2 T3 = dpp_ror8(hi ? w0 : w1);
;                     const u32x2 e1 = hi ? T3 : w0, e2 = hi ? w1 : T3;
;                     *(u32x2*)(xg + mo0 + bj * 128) = e1; *(u32x2*)(xg + mo1 + bj * 128) = e2; }
.LBB0_341:
	v_cndmask_b32_e64 v89, v110, v89, s[40:41]
	v_cndmask_b32_e64 v88, v108, v88, s[40:41]
	v_cndmask_b32_e64 v91, v111, v91, s[40:41]
	v_cndmask_b32_e64 v90, v109, v90, s[40:41]
	v_cndmask_b32_e64 v93, v93, v110, s[40:41]
	v_cndmask_b32_e64 v92, v92, v108, s[40:41]
	v_cndmask_b32_e64 v95, v95, v111, s[40:41]
	v_cndmask_b32_e64 v94, v94, v109, s[40:41]
	v_pk_fma_f32 v[38:39], v[38:39], v[178:179], v[90:91]
	v_pk_fma_f32 v[36:37], v[36:37], v[176:177], v[88:89]
	v_pk_fma_f32 v[34:35], v[34:35], v[182:183], v[94:95]
	v_pk_fma_f32 v[32:33], v[32:33], v[180:181], v[92:93]
	v_cndmask_b32_e64 v88, v39, v35, s[40:41]
	v_cndmask_b32_e64 v89, v38, v34, s[40:41]
	v_cndmask_b32_e64 v90, v37, v33, s[40:41]
	v_cndmask_b32_e64 v91, v36, v32, s[40:41]
	v_mov_b32_e32 v92, v193
	v_mov_b32_e32 v93, v193
	v_mov_b32_e32 v94, v193
	v_mov_b32_e32 v95, v193
	v_mov_b32_dpp v92, v91 row_ror:8 row_mask:0xf bank_mask:0xf
	v_mov_b32_dpp v93, v90 row_ror:8 row_mask:0xf bank_mask:0xf
	v_mov_b32_dpp v94, v89 row_ror:8 row_mask:0xf bank_mask:0xf
	v_mov_b32_dpp v95, v88 row_ror:8 row_mask:0xf bank_mask:0xf
	v_lshl_add_u64 v[112:113], v[106:107], 0, s[60:61]
	v_cndmask_b32_e64 v91, v95, v39, s[40:41]
	v_cndmask_b32_e64 v90, v94, v38, s[40:41]
	v_cndmask_b32_e64 v89, v93, v37, s[40:41]
	v_cndmask_b32_e64 v88, v92, v36, s[40:41]
	v_cndmask_b32_e64 v95, v35, v95, s[40:41]
	v_cndmask_b32_e64 v94, v34, v94, s[40:41]
	v_cndmask_b32_e64 v93, v33, v93, s[40:41]
	v_cndmask_b32_e64 v92, v32, v92, s[40:41]
	s_and_b64 vcc, exec, s[38:39]
	global_store_dwordx4 v[106:107], v[88:91], off offset:512 nt
	global_store_dwordx4 v[112:113], v[92:95], off offset:512 nt
	s_cbranch_vccnz .LBB0_343
	v_pk_mul_f32 v[88:89], v[46:47], v[38:39]
	v_pk_mul_f32 v[90:91], v[44:45], v[36:37]
	v_pk_mul_f32 v[92:93], v[42:43], v[34:35]
	v_pk_mul_f32 v[94:95], v[40:41], v[32:33]
	v_cvt_pk_bf16_f32 v90, v90, v91
	v_cvt_pk_bf16_f32 v88, v88, v89
	s_nop 0
	v_cvt_pk_bf16_f32 v94, v94, v95
	v_cvt_pk_bf16_f32 v91, v92, v93
	v_mov_b32_e32 v93, v193
	v_cndmask_b32_e64 v92, v90, v94, s[40:41]
	v_cndmask_b32_e64 v89, v88, v91, s[40:41]
	s_nop 0
	v_mov_b32_dpp v93, v92 row_ror:8 row_mask:0xf bank_mask:0xf
	v_mov_b32_e32 v92, v193
	s_nop 1
	v_mov_b32_dpp v92, v89 row_ror:8 row_mask:0xf bank_mask:0xf
	v_cndmask_b32_e64 v89, v92, v88, s[40:41]
	v_cndmask_b32_e64 v88, v93, v90, s[40:41]
	global_store_dwordx2 v[104:105], v[88:89], off offset:256
	v_add_co_u32_e32 v88, vcc, 0x4000, v104
	v_cndmask_b32_e64 v91, v91, v92, s[40:41]
	v_cndmask_b32_e64 v90, v94, v93, s[40:41]
	v_addc_co_u32_e32 v89, vcc, 0, v105, vcc
	global_store_dwordx2 v[88:89], v[90:91], off offset:256

; __device__ __forceinline__ unsigned cvt_pk_bf16(float lo, float hi) { unsigned r; asm volatile("v_cvt_pk_bf16_f32 %0, %1, %2" : "=v"(r) : "v"(lo), "v"(hi)); return r; }
;     __device__ __forceinline__ void operator()(const f32x4 (&acc)[2][2][4][2], const pg8::Unit& u, int wr, int wc, int fr_, int fq_) const {
;     ...
;         for (int r = 0; r < 8; ++r) {
;             const int ai = r >> 2, m = r & 3;
;             const int grow = grow0 + ai * 128 + m * 16;
;             const size_t mo0 = (size_t)(mrow0 + ai * 128 + m * 16) * D + mcol, mo1 = mo0 + (size_t)8 * D;
;             f32x4 xo[2][2];
; #pragma unroll
;             for (int bj = 0; bj < 2; ++bj) {
;                 const f32x4 L1 = xi[r % RES_DEPTH][bj * 2], L2 = xi[r % RES_DEPTH][bj * 2 + 1];
;                 const f32x4 T = dpp_ror8(hi ? L1 : L2);
;                 const f32x4 x0 = hi ? T : L1, x1 = hi ? L2 : T;
;                 xo[bj][0] = x0 + gv[bj][0] * acc[ai][bj][m][0]; xo[bj][1] = x1 + gv[bj][1] * acc[ai][bj][m][1];
;             }
;             if (r + RES_DEPTH < 8) {
;                 const int r2 = r + RES_DEPTH;
; #pragma unroll
;                 for (int q = 0; q < 4; ++q) xi[r % RES_DEPTH][q] = *(const f32x4*)(rp0 + (size_t)((r2 >> 2) * 128 + (r2 & 3) * 16 + (q & 1) * 8) * D + (q >> 1) * 128);
;             }
;             float ss = 0.f;
; #pragma unroll
;             for (int bj = 0; bj < 2; ++bj) {
;                 const f32x4 a0 = xo[bj][0], a1 = xo[bj][1];
;                 ss += ((a0[0] * a0[0] + a0[1] * a0[1]) + (a0[2] * a0[2] + a0[3] * a0[3])) + ((a1[0] * a1[0] + a1[1] * a1[1]) + (a1[2] * a1[2] + a1[3] * a1[3]));
;                 const f32x4 T2 = dpp_ror8(hi ? a0 : a1);
;                 const f32x4 d1 = hi ? T2 : a0, d2 = hi ? a1 : T2;
;                 *(f32x4*)(out + mo0 + bj * 128) = d1; *(f32x4*)(out + mo1 + bj * 128) = d2;
;                 if (gm) { const f32x4 o0 = a0 * mv[bj][0], o1 = a1 * mv[bj][1];
;                     u32x2 w0, w1; w0.x = cvt_pk_bf16(o0[0], o0[1]); w0.y = cvt_pk_bf16(o0[2], o0[3]); w1.x = cvt_pk_bf16(o1[0], o1[1]); w1.y = cvt_pk_bf16(o1[2], o1[3]);
;                     const u32x2 T3 = dpp_ror8(hi ? w0 : w1);
;                     const u32x2 e1 = hi ? T3 : w0, e2 = hi ? w1 : T3;
;                     *(u32x2*)(xg + mo0 + bj * 128) = e1; *(u32x2*)(xg + mo1 + bj * 128) = e2; }
.LBB0_345:
	s_or_b64 exec, exec, s[26:27]
	s_waitcnt vmcnt(14)
	v_cndmask_b32_e64 v36, v81, v85, s[40:41]
	v_mov_b32_e32 v89, v193
	v_cndmask_b32_e64 v37, v80, v84, s[40:41]
	v_mov_b32_e32 v88, v193
	v_mov_b32_dpp v89, v36 row_ror:8 row_mask:0xf bank_mask:0xf
	s_waitcnt vmcnt(12)
	v_cndmask_b32_e64 v38, v72, v76, s[40:41]
	v_mov_b32_e32 v36, 0
	v_cndmask_b32_e64 v34, v83, v87, s[40:41]
	v_cndmask_b32_e64 v35, v82, v86, s[40:41]
	v_mov_b32_dpp v88, v37 row_ror:8 row_mask:0xf bank_mask:0xf
	v_mov_b32_e32 v90, v193
	v_mov_b32_e32 v91, v193
	v_cndmask_b32_e64 v37, v73, v77, s[40:41]
	v_mov_b32_dpp v36, v38 row_ror:8 row_mask:0xf bank_mask:0xf
	v_mov_b32_e32 v38, 0
	v_mov_b32_dpp v90, v35 row_ror:8 row_mask:0xf bank_mask:0xf
	v_mov_b32_dpp v91, v34 row_ror:8 row_mask:0xf bank_mask:0xf
	v_cndmask_b32_e64 v34, v75, v79, s[40:41]
	v_cndmask_b32_e64 v35, v74, v78, s[40:41]
	v_mov_b32_dpp v38, v37 row_ror:8 row_mask:0xf bank_mask:0xf
	v_mov_b32_e32 v37, 0
	v_mov_b32_e32 v39, 0
	v_add_u32_e32 v32, 0xa0, v216
	v_mov_b32_dpp v37, v35 row_ror:8 row_mask:0xf bank_mask:0xf
	v_mov_b32_dpp v39, v34 row_ror:8 row_mask:0xf bank_mask:0xf
	v_cndmask_b32_e64 v35, v85, v89, s[40:41]
	v_cndmask_b32_e64 v34, v84, v88, s[40:41]
	v_cndmask_b32_e64 v85, v87, v91, s[40:41]
	v_cndmask_b32_e64 v84, v86, v90, s[40:41]
	v_pk_fma_f32 v[28:29], v[28:29], v[188:189], v[34:35]
	v_cndmask_b32_e64 v35, v89, v81, s[40:41]
	v_cndmask_b32_e64 v34, v88, v80, s[40:41]
	v_cndmask_b32_e64 v81, v91, v83, s[40:41]
	v_cndmask_b32_e64 v80, v90, v82, s[40:41]
	v_pk_fma_f32 v[30:31], v[30:31], v[190:191], v[84:85]
	v_pk_fma_f32 v[26:27], v[26:27], v[186:187], v[80:81]
	s_waitcnt lgkmcnt(0)
	v_ashrrev_i32_e32 v33, 31, v32
	v_pk_fma_f32 v[24:25], v[24:25], v[184:185], v[34:35]
	v_cndmask_b32_e64 v35, v26, v30, s[40:41]
	v_mov_b32_e32 v86, v193
	v_lshlrev_b64 v[32:33], 10, v[32:33]
	v_cndmask_b32_e64 v34, v27, v31, s[40:41]
	v_cndmask_b32_e64 v80, v25, v29, s[40:41]
	v_cndmask_b32_e64 v81, v24, v28, s[40:41]
	v_mov_b32_e32 v84, v193
	v_mov_b32_e32 v85, v193
	v_mov_b32_dpp v86, v35 row_ror:8 row_mask:0xf bank_mask:0xf
	v_mov_b32_e32 v35, v193
	v_lshl_add_u64 v[32:33], v[32:33], 0, v[218:219]
	v_mov_b32_dpp v84, v81 row_ror:8 row_mask:0xf bank_mask:0xf
	v_mov_b32_dpp v85, v80 row_ror:8 row_mask:0xf bank_mask:0xf
	v_mov_b32_dpp v35, v34 row_ror:8 row_mask:0xf bank_mask:0xf
	v_cndmask_b32_e64 v83, v35, v27, s[40:41]
	v_cndmask_b32_e64 v82, v86, v26, s[40:41]
	v_cndmask_b32_e64 v81, v85, v25, s[40:41]
	v_cndmask_b32_e64 v80, v84, v24, s[40:41]
	v_cndmask_b32_e64 v87, v31, v35, s[40:41]
	v_lshl_add_u64 v[34:35], v[32:33], 2, s[82:83]
	global_store_dwordx4 v[34:35], v[80:83], off nt
	v_cndmask_b32_e64 v86, v30, v86, s[40:41]
	v_cndmask_b32_e64 v85, v29, v85, s[40:41]
	v_add_co_u32_e32 v80, vcc, 0x8000, v34
	v_cndmask_b32_e64 v84, v28, v84, s[40:41]
	s_nop 0
	v_addc_co_u32_e32 v81, vcc, 0, v35, vcc
	s_and_b64 vcc, exec, s[38:39]
	v_lshl_add_u64 v[32:33], v[32:33], 1, s[8:9]
	global_store_dwordx4 v[80:81], v[84:87], off nt
	s_cbranch_vccnz .LBB0_347
	v_pk_mul_f32 v[80:81], v[54:55], v[26:27]
	v_pk_mul_f32 v[82:83], v[52:53], v[24:25]
	v_pk_mul_f32 v[84:85], v[50:51], v[30:31]
	v_pk_mul_f32 v[86:87], v[48:49], v[28:29]
	v_cvt_pk_bf16_f32 v82, v82, v83
	v_cvt_pk_bf16_f32 v80, v80, v81
	s_nop 0
	v_cvt_pk_bf16_f32 v86, v86, v87
	v_cvt_pk_bf16_f32 v83, v84, v85
	v_mov_b32_e32 v85, v193
	v_cndmask_b32_e64 v84, v82, v86, s[40:41]
	v_cndmask_b32_e64 v81, v80, v83, s[40:41]
	s_nop 0
	v_mov_b32_dpp v85, v84 row_ror:8 row_mask:0xf bank_mask:0xf
	v_mov_b32_e32 v84, v193
	s_nop 1
	v_mov_b32_dpp v84, v81 row_ror:8 row_mask:0xf bank_mask:0xf
	v_cndmask_b32_e64 v81, v84, v80, s[40:41]
	v_cndmask_b32_e64 v80, v85, v82, s[40:41]
	global_store_dwordx2 v[32:33], v[80:81], off
	v_add_co_u32_e32 v80, vcc, 0x4000, v32
	v_cndmask_b32_e64 v83, v83, v84, s[40:41]
	v_cndmask_b32_e64 v82, v86, v85, s[40:41]
	v_addc_co_u32_e32 v81, vcc, 0, v33, vcc
	global_store_dwordx2 v[80:81], v[82:83], off
.LBB0_347:
	v_cndmask_b32_e64 v73, v38, v73, s[40:41]
	v_cndmask_b32_e64 v72, v36, v72, s[40:41]
	v_cndmask_b32_e64 v75, v39, v75, s[40:41]
	v_cndmask_b32_e64 v74, v37, v74, s[40:41]
	v_cndmask_b32_e64 v77, v77, v38, s[40:41]
	v_cndmask_b32_e64 v76, v76, v36, s[40:41]
	v_cndmask_b32_e64 v39, v79, v39, s[40:41]
	v_cndmask_b32_e64 v38, v78, v37, s[40:41]
	v_pk_fma_f32 v[22:23], v[22:23], v[178:179], v[74:75]
	v_pk_fma_f32 v[20:21], v[20:21], v[176:177], v[72:73]
	v_pk_fma_f32 v[18:19], v[18:19], v[182:183], v[38:39]
	v_pk_fma_f32 v[16:17], v[16:17], v[180:181], v[76:77]
	v_cndmask_b32_e64 v36, v23, v19, s[40:41]
	v_cndmask_b32_e64 v37, v22, v18, s[40:41]
	v_cndmask_b32_e64 v38, v21, v17, s[40:41]
	v_cndmask_b32_e64 v39, v20, v16, s[40:41]
	v_mov_b32_e32 v72, v193
	v_mov_b32_e32 v73, v193
	v_mov_b32_e32 v74, v193
	v_mov_b32_e32 v75, v193
	v_mov_b32_dpp v72, v39 row_ror:8 row_mask:0xf bank_mask:0xf
	v_mov_b32_dpp v73, v38 row_ror:8 row_mask:0xf bank_mask:0xf
	v_mov_b32_dpp v74, v37 row_ror:8 row_mask:0xf bank_mask:0xf
	v_mov_b32_dpp v75, v36 row_ror:8 row_mask:0xf bank_mask:0xf
	v_lshl_add_u64 v[80:81], v[34:35], 0, s[60:61]
	v_cndmask_b32_e64 v39, v75, v23, s[40:41]
	v_cndmask_b32_e64 v38, v74, v22, s[40:41]
	v_cndmask_b32_e64 v37, v73, v21, s[40:41]
	v_cndmask_b32_e64 v36, v72, v20, s[40:41]
	v_cndmask_b32_e64 v75, v19, v75, s[40:41]
	v_cndmask_b32_e64 v74, v18, v74, s[40:41]
	v_cndmask_b32_e64 v73, v17, v73, s[40:41]
	v_cndmask_b32_e64 v72, v16, v72, s[40:41]
	s_and_b64 vcc, exec, s[38:39]
	global_store_dwordx4 v[34:35], v[36:39], off offset:512 nt
	global_store_dwordx4 v[80:81], v[72:75], off offset:512 nt
	s_cbranch_vccnz .LBB0_349
	v_pk_mul_f32 v[34:35], v[46:47], v[22:23]
	v_pk_mul_f32 v[36:37], v[44:45], v[20:21]
	v_pk_mul_f32 v[38:39], v[42:43], v[18:19]
	v_pk_mul_f32 v[72:73], v[40:41], v[16:17]
	v_cvt_pk_bf16_f32 v36, v36, v37
	v_cvt_pk_bf16_f32 v34, v34, v35
	s_nop 0
	v_cvt_pk_bf16_f32 v72, v72, v73
	v_cvt_pk_bf16_f32 v37, v38, v39
	v_mov_b32_e32 v39, v193
	v_cndmask_b32_e64 v38, v36, v72, s[40:41]
	v_cndmask_b32_e64 v35, v34, v37, s[40:41]
	s_nop 0
	v_mov_b32_dpp v39, v38 row_ror:8 row_mask:0xf bank_mask:0xf
	v_mov_b32_e32 v38, v193
	s_nop 1
	v_mov_b32_dpp v38, v35 row_ror:8 row_mask:0xf bank_mask:0xf
	v_cndmask_b32_e64 v35, v38, v34, s[40:41]
	v_cndmask_b32_e64 v34, v39, v36, s[40:41]
	global_store_dwordx2 v[32:33], v[34:35], off offset:256
	v_add_co_u32_e32 v32, vcc, 0x4000, v32
	v_cndmask_b32_e64 v37, v37, v38, s[40:41]
	v_cndmask_b32_e64 v36, v72, v39, s[40:41]
	v_addc_co_u32_e32 v33, vcc, 0, v33, vcc
	global_store_dwordx2 v[32:33], v[36:37], off offset:256

; __device__ __forceinline__ unsigned cvt_pk_bf16(float lo, float hi) { unsigned r; asm volatile("v_cvt_pk_bf16_f32 %0, %1, %2" : "=v"(r) : "v"(lo), "v"(hi)); return r; }
;     __device__ __forceinline__ void operator()(const f32x4 (&acc)[2][2][4][2], const pg8::Unit& u, int wr, int wc, int fr_, int fq_) const {
;     ...
;         for (int r = 0; r < 8; ++r) {
;             const int ai = r >> 2, m = r & 3;
;             const int grow = grow0 + ai * 128 + m * 16;
;             const size_t mo0 = (size_t)(mrow0 + ai * 128 + m * 16) * D + mcol, mo1 = mo0 + (size_t)8 * D;
;             f32x4 xo[2][2];
; #pragma unroll
;             for (int bj = 0; bj < 2; ++bj) {
;                 const f32x4 L1 = xi[r % RES_DEPTH][bj * 2], L2 = xi[r % RES_DEPTH][bj * 2 + 1];
;                 const f32x4 T = dpp_ror8(hi ? L1 : L2);
;                 const f32x4 x0 = hi ? T : L1, x1 = hi ? L2 : T;
;                 xo[bj][0] = x0 + gv[bj][0] * acc[ai][bj][m][0]; xo[bj][1] = x1 + gv[bj][1] * acc[ai][bj][m][1];
;             }
;             if (r + RES_DEPTH < 8) {
;                 const int r2 = r + RES_DEPTH;
; #pragma unroll
;                 for (int q = 0; q < 4; ++q) xi[r % RES_DEPTH][q] = *(const f32x4*)(rp0 + (size_t)((r2 >> 2) * 128 + (r2 & 3) * 16 + (q & 1) * 8) * D + (q >> 1) * 128);
;             }
;             float ss = 0.f;
; #pragma unroll
;             for (int bj = 0; bj < 2; ++bj) {
;                 const f32x4 a0 = xo[bj][0], a1 = xo[bj][1];
;                 ss += ((a0[0] * a0[0] + a0[1] * a0[1]) + (a0[2] * a0[2] + a0[3] * a0[3])) + ((a1[0] * a1[0] + a1[1] * a1[1]) + (a1[2] * a1[2] + a1[3] * a1[3]));
;                 const f32x4 T2 = dpp_ror8(hi ? a0 : a1);
;                 const f32x4 d1 = hi ? T2 : a0, d2 = hi ? a1 : T2;
;                 *(f32x4*)(out + mo0 + bj * 128) = d1; *(f32x4*)(out + mo1 + bj * 128) = d2;
;                 if (gm) { const f32x4 o0 = a0 * mv[bj][0], o1 = a1 * mv[bj][1];
;                     u32x2 w0, w1; w0.x = cvt_pk_bf16(o0[0], o0[1]); w0.y = cvt_pk_bf16(o0[2], o0[3]); w1.x = cvt_pk_bf16(o1[0], o1[1]); w1.y = cvt_pk_bf16(o1[2], o1[3]);
;                     const u32x2 T3 = dpp_ror8(hi ? w0 : w1);
;                     const u32x2 e1 = hi ? T3 : w0, e2 = hi ? w1 : T3;
;                     *(u32x2*)(xg + mo0 + bj * 128) = e1; *(u32x2*)(xg + mo1 + bj * 128) = e2; }
.LBB0_351:
	s_or_b64 exec, exec, s[26:27]
	s_waitcnt vmcnt(10)
	v_cndmask_b32_e64 v20, v65, v69, s[40:41]
	v_mov_b32_e32 v27, v193
	v_cndmask_b32_e64 v18, v67, v71, s[40:41]
	v_cndmask_b32_e64 v19, v66, v70, s[40:41]
	v_cndmask_b32_e64 v21, v64, v68, s[40:41]
	v_mov_b32_e32 v26, v193
	v_mov_b32_dpp v27, v20 row_ror:8 row_mask:0xf bank_mask:0xf
	v_mov_b32_e32 v28, v193
	v_mov_b32_e32 v29, v193
	s_waitcnt vmcnt(8)
	v_cndmask_b32_e64 v22, v56, v60, s[40:41]
	v_mov_b32_e32 v20, 0
	v_mov_b32_dpp v26, v21 row_ror:8 row_mask:0xf bank_mask:0xf
	v_mov_b32_dpp v28, v19 row_ror:8 row_mask:0xf bank_mask:0xf
	v_mov_b32_dpp v29, v18 row_ror:8 row_mask:0xf bank_mask:0xf
	v_cndmask_b32_e64 v21, v57, v61, s[40:41]
	v_mov_b32_dpp v20, v22 row_ror:8 row_mask:0xf bank_mask:0xf
	v_mov_b32_e32 v22, 0
	v_cndmask_b32_e64 v18, v59, v63, s[40:41]
	v_cndmask_b32_e64 v19, v58, v62, s[40:41]
	v_mov_b32_dpp v22, v21 row_ror:8 row_mask:0xf bank_mask:0xf
	v_mov_b32_e32 v21, 0
	v_mov_b32_e32 v23, 0
	v_cndmask_b32_e64 v25, v71, v29, s[40:41]
	v_cndmask_b32_e64 v24, v70, v28, s[40:41]
	v_mov_b32_dpp v21, v19 row_ror:8 row_mask:0xf bank_mask:0xf
	v_mov_b32_dpp v23, v18 row_ror:8 row_mask:0xf bank_mask:0xf
	v_cndmask_b32_e64 v19, v69, v27, s[40:41]
	v_cndmask_b32_e64 v18, v68, v26, s[40:41]
	v_pk_fma_f32 v[14:15], v[14:15], v[190:191], v[24:25]
	v_cndmask_b32_e64 v25, v29, v67, s[40:41]
	v_cndmask_b32_e64 v24, v28, v66, s[40:41]
	v_add_u32_e32 v16, 0xb0, v216
	v_pk_fma_f32 v[12:13], v[12:13], v[188:189], v[18:19]
	v_cndmask_b32_e64 v19, v27, v65, s[40:41]
	v_cndmask_b32_e64 v18, v26, v64, s[40:41]
	v_pk_fma_f32 v[10:11], v[10:11], v[186:187], v[24:25]
	s_waitcnt lgkmcnt(0)
	v_ashrrev_i32_e32 v17, 31, v16
	v_pk_fma_f32 v[8:9], v[8:9], v[184:185], v[18:19]
	v_cndmask_b32_e64 v19, v10, v14, s[40:41]
	v_mov_b32_e32 v30, v193
	v_lshlrev_b64 v[16:17], 10, v[16:17]
	v_cndmask_b32_e64 v18, v11, v15, s[40:41]
	v_cndmask_b32_e64 v24, v9, v13, s[40:41]
	v_cndmask_b32_e64 v25, v8, v12, s[40:41]
	v_mov_b32_e32 v28, v193
	v_mov_b32_e32 v29, v193
	v_mov_b32_dpp v30, v19 row_ror:8 row_mask:0xf bank_mask:0xf
	v_mov_b32_e32 v19, v193
	v_lshl_add_u64 v[16:17], v[16:17], 0, v[218:219]
	v_mov_b32_dpp v28, v25 row_ror:8 row_mask:0xf bank_mask:0xf
	v_mov_b32_dpp v29, v24 row_ror:8 row_mask:0xf bank_mask:0xf
	v_mov_b32_dpp v19, v18 row_ror:8 row_mask:0xf bank_mask:0xf
	v_cndmask_b32_e64 v27, v19, v11, s[40:41]
	v_cndmask_b32_e64 v26, v30, v10, s[40:41]
	v_cndmask_b32_e64 v25, v29, v9, s[40:41]
	v_cndmask_b32_e64 v24, v28, v8, s[40:41]
	v_cndmask_b32_e64 v31, v15, v19, s[40:41]
	v_lshl_add_u64 v[18:19], v[16:17], 2, s[82:83]
	global_store_dwordx4 v[18:19], v[24:27], off nt
	v_cndmask_b32_e64 v30, v14, v30, s[40:41]
	v_cndmask_b32_e64 v29, v13, v29, s[40:41]
	v_add_co_u32_e32 v24, vcc, 0x8000, v18
	v_cndmask_b32_e64 v28, v12, v28, s[40:41]
	s_nop 0
	v_addc_co_u32_e32 v25, vcc, 0, v19, vcc
	s_and_b64 vcc, exec, s[38:39]
	v_lshl_add_u64 v[16:17], v[16:17], 1, s[8:9]
	global_store_dwordx4 v[24:25], v[28:31], off nt
	s_cbranch_vccnz .LBB0_353
	v_pk_mul_f32 v[24:25], v[54:55], v[10:11]
	v_pk_mul_f32 v[26:27], v[52:53], v[8:9]
	v_pk_mul_f32 v[28:29], v[50:51], v[14:15]
	v_pk_mul_f32 v[30:31], v[48:49], v[12:13]
	v_cvt_pk_bf16_f32 v26, v26, v27
	v_cvt_pk_bf16_f32 v24, v24, v25
	s_nop 0
	v_cvt_pk_bf16_f32 v30, v30, v31
	v_cvt_pk_bf16_f32 v27, v28, v29
	v_mov_b32_e32 v29, v193
	v_cndmask_b32_e64 v28, v26, v30, s[40:41]
	v_cndmask_b32_e64 v25, v24, v27, s[40:41]
	s_nop 0
	v_mov_b32_dpp v29, v28 row_ror:8 row_mask:0xf bank_mask:0xf
	v_mov_b32_e32 v28, v193
	s_nop 1
	v_mov_b32_dpp v28, v25 row_ror:8 row_mask:0xf bank_mask:0xf
	v_cndmask_b32_e64 v25, v28, v24, s[40:41]
	v_cndmask_b32_e64 v24, v29, v26, s[40:41]
	global_store_dwordx2 v[16:17], v[24:25], off
	v_add_co_u32_e32 v24, vcc, 0x4000, v16
	v_cndmask_b32_e64 v27, v27, v28, s[40:41]
	v_cndmask_b32_e64 v26, v30, v29, s[40:41]
	v_addc_co_u32_e32 v25, vcc, 0, v17, vcc
	global_store_dwordx2 v[24:25], v[26:27], off
.LBB0_353:
	v_cndmask_b32_e64 v25, v22, v57, s[40:41]
	v_cndmask_b32_e64 v24, v20, v56, s[40:41]
	v_cndmask_b32_e64 v27, v23, v59, s[40:41]
	v_cndmask_b32_e64 v26, v21, v58, s[40:41]
	v_cndmask_b32_e64 v31, v61, v22, s[40:41]
	v_cndmask_b32_e64 v30, v60, v20, s[40:41]
	v_cndmask_b32_e64 v23, v63, v23, s[40:41]
	v_cndmask_b32_e64 v22, v62, v21, s[40:41]
	v_pk_fma_f32 v[6:7], v[6:7], v[178:179], v[26:27]
	v_pk_fma_f32 v[4:5], v[4:5], v[176:177], v[24:25]
	v_pk_fma_f32 v[2:3], v[2:3], v[182:183], v[22:23]
	v_pk_fma_f32 v[0:1], v[0:1], v[180:181], v[30:31]
	v_cndmask_b32_e64 v20, v7, v3, s[40:41]
	v_cndmask_b32_e64 v21, v6, v2, s[40:41]
	v_cndmask_b32_e64 v22, v5, v1, s[40:41]
	v_cndmask_b32_e64 v23, v4, v0, s[40:41]
	v_mov_b32_e32 v24, v193
	v_mov_b32_e32 v25, v193
	v_mov_b32_e32 v26, v193
	v_mov_b32_e32 v27, v193
	v_mov_b32_dpp v24, v23 row_ror:8 row_mask:0xf bank_mask:0xf
	v_mov_b32_dpp v25, v22 row_ror:8 row_mask:0xf bank_mask:0xf
	v_mov_b32_dpp v26, v21 row_ror:8 row_mask:0xf bank_mask:0xf
	v_mov_b32_dpp v27, v20 row_ror:8 row_mask:0xf bank_mask:0xf
	v_lshl_add_u64 v[28:29], v[18:19], 0, s[60:61]
	v_cndmask_b32_e64 v23, v27, v7, s[40:41]
	v_cndmask_b32_e64 v22, v26, v6, s[40:41]
	v_cndmask_b32_e64 v21, v25, v5, s[40:41]
	v_cndmask_b32_e64 v20, v24, v4, s[40:41]
	v_cndmask_b32_e64 v27, v3, v27, s[40:41]
	v_cndmask_b32_e64 v26, v2, v26, s[40:41]
	v_cndmask_b32_e64 v25, v1, v25, s[40:41]
	v_cndmask_b32_e64 v24, v0, v24, s[40:41]
	s_and_b64 vcc, exec, s[38:39]
	global_store_dwordx4 v[18:19], v[20:23], off offset:512 nt
	global_store_dwordx4 v[28:29], v[24:27], off offset:512 nt
	s_cbranch_vccnz .LBB0_355
	v_pk_mul_f32 v[18:19], v[46:47], v[6:7]
	v_pk_mul_f32 v[20:21], v[44:45], v[4:5]
	v_pk_mul_f32 v[22:23], v[42:43], v[2:3]
	v_pk_mul_f32 v[24:25], v[40:41], v[0:1]
	v_cvt_pk_bf16_f32 v20, v20, v21
	v_cvt_pk_bf16_f32 v18, v18, v19
	s_nop 0
	v_cvt_pk_bf16_f32 v24, v24, v25
	v_cvt_pk_bf16_f32 v21, v22, v23
	v_mov_b32_e32 v23, v193
	v_cndmask_b32_e64 v22, v20, v24, s[40:41]
	v_cndmask_b32_e64 v19, v18, v21, s[40:41]
	s_nop 0
	v_mov_b32_dpp v23, v22 row_ror:8 row_mask:0xf bank_mask:0xf
	v_mov_b32_e32 v22, v193
	s_nop 1
	v_mov_b32_dpp v22, v19 row_ror:8 row_mask:0xf bank_mask:0xf
	v_cndmask_b32_e64 v19, v22, v18, s[40:41]
	v_cndmask_b32_e64 v18, v23, v20, s[40:41]
	global_store_dwordx2 v[16:17], v[18:19], off offset:256
	v_add_co_u32_e32 v16, vcc, 0x4000, v16
	v_cndmask_b32_e64 v21, v21, v22, s[40:41]
	v_cndmask_b32_e64 v20, v24, v23, s[40:41]
	v_addc_co_u32_e32 v17, vcc, 0, v17, vcc
	global_store_dwordx2 v[16:17], v[20:21], off offset:256
